# K=2 late barrier + cache policy swap: residual stream X cacheable, FFN hidden (HID) stores and FFN2 A-operand LDS-DMA loads nontemporal
# baseline (speedup 1.0000x reference)
.LBB0_1091:
	s_lshl_b32 s30, s36, 8
	s_add_i32 s34, s30, s62
	s_lshl_b32 s30, s37, 8
	s_or_b32 s35, s30, s63
	s_lshr_b32 s30, s36, 4
	s_add_i32 s30, s30, -1
	v_or_b32_e32 v2, s35, v186
	s_cmp_gt_i32 s36, 31
	s_cselect_b32 s30, s30, 0
	v_ashrrev_i32_e32 v3, 31, v2
	v_or_b32_e32 v168, s34, v187
	v_lshlrev_b64 v[10:11], 2, v[2:3]
	v_ashrrev_i32_e32 v169, 31, v168
	s_ashr_i32 s31, s30, 31
	v_lshl_add_u64 v[12:13], s[20:21], 0, v[10:11]
	v_lshl_add_u64 v[100:101], v[168:169], 2, s[16:17]
	s_lshl_b64 s[30:31], s[30:31], 15
	global_load_dwordx4 v[2:5], v[12:13], off offset:16
	global_load_dwordx4 v[6:9], v[12:13], off
	global_load_dword v190, v[100:101], off
	s_add_u32 s30, s57, s30
	global_load_dwordx4 v[14:17], v[12:13], off offset:528
	global_load_dwordx4 v[30:33], v[12:13], off offset:512
	s_addc_u32 s31, s58, s31
	v_lshl_add_u64 v[10:11], s[30:31], 0, v[10:11]
	global_load_dwordx4 v[26:29], v[10:11], off
	global_load_dwordx4 v[22:25], v[10:11], off offset:16
	global_load_dwordx4 v[18:21], v[10:11], off offset:512
	s_nop 0
	global_load_dwordx4 v[10:13], v[10:11], off offset:528
	s_ashr_i32 s34, s34, 8
	v_bitop3_b32 v90, s35, 56, v186 bitop3:0xc8
	s_ashr_i32 s30, s35, 6
	s_ashr_i32 s35, s34, 31
	s_ashr_i32 s31, s30, 31
	s_lshl_b64 s[38:39], s[34:35], 7
	s_add_u32 s34, s38, s30
	s_addc_u32 s35, s39, s31
	s_lshl_b64 s[34:35], s[34:35], 15
	s_add_u32 s36, s12, s34
	s_addc_u32 s37, s13, s35
	s_or_b32 s34, s30, 2
	s_ashr_i32 s35, s34, 31
	s_add_u32 s38, s38, s34
	v_lshlrev_b32_e32 v169, 7, v168
	s_addc_u32 s39, s39, s35
	v_and_b32_e32 v138, 0x6780, v169
	s_lshl_b64 s[38:39], s[38:39], 15
	v_mov_b32_e32 v91, v139
	v_lshlrev_b32_e32 v90, 1, v90
	v_lshl_add_u64 v[192:193], s[36:37], 0, v[138:139]
	s_add_u32 s38, s12, s38
	v_lshl_add_u64 v[192:193], v[192:193], 0, v[90:91]
	s_addc_u32 s39, s13, s39
	s_and_b64 vcc, exec, s[0:1]
	s_mov_b64 s[0:1], -1
	s_waitcnt vmcnt(0)
	v_pk_mul_f32 v[194:195], v[6:7], v[190:191] op_sel_hi:[1,0]
	v_pk_mul_f32 v[196:197], v[8:9], v[190:191] op_sel_hi:[1,0]
	v_pk_mul_f32 v[198:199], v[2:3], v[190:191] op_sel_hi:[1,0]
	v_pk_mul_f32 v[204:205], v[32:33], v[190:191] op_sel_hi:[1,0]
	v_pk_fma_f32 v[170:171], v[196:197], v[170:171], v[28:29]
	v_pk_fma_f32 v[172:173], v[194:195], v[172:173], v[26:27]
	v_pk_mul_f32 v[200:201], v[4:5], v[190:191] op_sel_hi:[1,0]
	v_pk_mul_f32 v[202:203], v[30:31], v[190:191] op_sel_hi:[1,0]
	v_pk_mul_f32 v[206:207], v[14:15], v[190:191] op_sel_hi:[1,0]
	v_pk_mul_f32 v[190:191], v[16:17], v[190:191] op_sel_hi:[1,0]
	v_pk_fma_f32 v[174:175], v[198:199], v[174:175], v[22:23]
	v_pk_fma_f32 v[182:183], v[204:205], v[182:183], v[20:21]
	v_max_f32_e32 v173, 0, v173
	v_max_f32_e32 v172, 0, v172
	v_max_f32_e32 v171, 0, v171
	v_max_f32_e32 v170, 0, v170
	v_pk_fma_f32 v[176:177], v[200:201], v[176:177], v[24:25]
	v_pk_fma_f32 v[180:181], v[202:203], v[180:181], v[18:19]
	v_pk_fma_f32 v[184:185], v[190:191], v[184:185], v[12:13]
	v_max_f32_e32 v175, 0, v175
	v_max_f32_e32 v174, 0, v174
	v_max_f32_e32 v183, 0, v183
	v_max_f32_e32 v182, 0, v182
	v_pk_mul_f32 v[190:191], v[170:171], v[170:171]
	v_pk_mul_f32 v[170:171], v[172:173], v[172:173]
	v_max_f32_e32 v177, 0, v177
	v_max_f32_e32 v176, 0, v176
	v_max_f32_e32 v181, 0, v181
	v_max_f32_e32 v180, 0, v180
	v_pk_mul_f32 v[172:173], v[174:175], v[174:175]
	v_pk_mul_f32 v[174:175], v[182:183], v[182:183]
	v_cvt_pk_bf16_f32 v170, v170, v171
	v_cvt_pk_bf16_f32 v171, v190, v191
	v_pk_fma_f32 v[178:179], v[206:207], v[178:179], v[10:11]
	v_pk_mul_f32 v[176:177], v[176:177], v[176:177]
	v_pk_mul_f32 v[180:181], v[180:181], v[180:181]
	v_cvt_pk_bf16_f32 v172, v172, v173
	v_cvt_pk_bf16_f32 v173, v176, v177
	global_store_dwordx4 v[192:193], v[170:173], off nt
	v_max_f32_e32 v179, 0, v179
	v_max_f32_e32 v178, 0, v178
	v_cvt_pk_bf16_f32 v170, v180, v181
	v_cvt_pk_bf16_f32 v171, v174, v175
	v_lshl_add_u64 v[174:175], s[38:39], 0, v[138:139]
	v_max_f32_e32 v185, 0, v185
	v_max_f32_e32 v184, 0, v184
	v_lshl_add_u64 v[174:175], v[174:175], 0, v[90:91]
	v_pk_mul_f32 v[182:183], v[184:185], v[184:185]
	v_pk_mul_f32 v[178:179], v[178:179], v[178:179]
	s_nop 0
	v_cvt_pk_bf16_f32 v172, v178, v179
	v_cvt_pk_bf16_f32 v173, v182, v183
	global_store_dwordx4 v[174:175], v[170:173], off nt
	v_or_b32_e32 v174, 32, v168
	v_ashrrev_i32_e32 v175, 31, v174
	v_or_b32_e32 v170, 16, v168
	v_ashrrev_i32_e32 v171, 31, v170
	v_lshl_add_u64 v[172:173], v[170:171], 2, s[16:17]
	global_load_dword v172, v[172:173], off
	v_lshlrev_b32_e32 v138, 7, v170
	v_and_b32_e32 v138, 0x6f80, v138
	v_lshl_add_u64 v[176:177], s[36:37], 0, v[138:139]
	v_lshl_add_u64 v[178:179], s[38:39], 0, v[138:139]
	v_lshl_add_u64 v[176:177], v[176:177], 0, v[90:91]
	v_lshl_add_u64 v[178:179], v[178:179], 0, v[90:91]
	v_lshl_add_u64 v[170:171], v[174:175], 2, s[16:17]
	v_lshlrev_b32_e32 v138, 7, v174
	v_and_b32_e32 v138, 0x7780, v138
	s_waitcnt vmcnt(0)
	v_pk_mul_f32 v[180:181], v[6:7], v[172:173] op_sel_hi:[1,0]
	v_pk_mul_f32 v[182:183], v[8:9], v[172:173] op_sel_hi:[1,0]
	v_pk_mul_f32 v[184:185], v[2:3], v[172:173] op_sel_hi:[1,0]
	v_pk_mul_f32 v[190:191], v[4:5], v[172:173] op_sel_hi:[1,0]
	v_pk_fma_f32 v[154:155], v[182:183], v[154:155], v[28:29]
	v_pk_fma_f32 v[152:153], v[180:181], v[152:153], v[26:27]
	v_pk_mul_f32 v[192:193], v[30:31], v[172:173] op_sel_hi:[1,0]
	v_pk_mul_f32 v[194:195], v[32:33], v[172:173] op_sel_hi:[1,0]
	v_pk_mul_f32 v[196:197], v[14:15], v[172:173] op_sel_hi:[1,0]
	v_pk_mul_f32 v[172:173], v[16:17], v[172:173] op_sel_hi:[1,0]
	v_pk_fma_f32 v[158:159], v[190:191], v[158:159], v[24:25]
	v_pk_fma_f32 v[156:157], v[184:185], v[156:157], v[22:23]
	v_max_f32_e32 v153, 0, v153
	v_max_f32_e32 v152, 0, v152
	v_max_f32_e32 v155, 0, v155
	v_max_f32_e32 v154, 0, v154
	v_pk_fma_f32 v[162:163], v[194:195], v[162:163], v[20:21]
	v_pk_fma_f32 v[160:161], v[192:193], v[160:161], v[18:19]
	v_pk_fma_f32 v[166:167], v[172:173], v[166:167], v[12:13]
	v_pk_fma_f32 v[164:165], v[196:197], v[164:165], v[10:11]
	v_max_f32_e32 v157, 0, v157
	v_max_f32_e32 v156, 0, v156
	v_max_f32_e32 v159, 0, v159
	v_max_f32_e32 v158, 0, v158
	v_pk_mul_f32 v[154:155], v[154:155], v[154:155]
	v_pk_mul_f32 v[152:153], v[152:153], v[152:153]
	v_max_f32_e32 v161, 0, v161
	v_max_f32_e32 v160, 0, v160
	v_max_f32_e32 v163, 0, v163
	v_max_f32_e32 v162, 0, v162
	v_max_f32_e32 v165, 0, v165
	v_max_f32_e32 v164, 0, v164
	v_max_f32_e32 v167, 0, v167
	v_max_f32_e32 v166, 0, v166
	v_pk_mul_f32 v[158:159], v[158:159], v[158:159]
	v_pk_mul_f32 v[156:157], v[156:157], v[156:157]
	v_cvt_pk_bf16_f32 v152, v152, v153
	v_cvt_pk_bf16_f32 v153, v154, v155
	v_pk_mul_f32 v[162:163], v[162:163], v[162:163]
	v_cvt_pk_bf16_f32 v154, v156, v157
	v_cvt_pk_bf16_f32 v155, v158, v159
	v_pk_mul_f32 v[160:161], v[160:161], v[160:161]
	v_pk_mul_f32 v[166:167], v[166:167], v[166:167]
	v_pk_mul_f32 v[164:165], v[164:165], v[164:165]
	global_store_dwordx4 v[176:177], v[152:155], off nt
	v_lshl_add_u64 v[158:159], s[36:37], 0, v[138:139]
	v_lshl_add_u64 v[158:159], v[158:159], 0, v[90:91]
	v_cvt_pk_bf16_f32 v152, v160, v161
	v_cvt_pk_bf16_f32 v153, v162, v163
	v_cvt_pk_bf16_f32 v154, v164, v165
	v_cvt_pk_bf16_f32 v155, v166, v167
	global_store_dwordx4 v[178:179], v[152:155], off nt
	global_load_dword v152, v[170:171], off
	v_lshl_add_u64 v[160:161], s[38:39], 0, v[138:139]
	v_or_b32_e32 v154, 48, v168
	v_ashrrev_i32_e32 v155, 31, v154
	v_lshl_add_u64 v[160:161], v[160:161], 0, v[90:91]
	v_lshl_add_u64 v[156:157], v[154:155], 2, s[16:17]
	s_waitcnt vmcnt(0)
	v_pk_mul_f32 v[162:163], v[6:7], v[152:153] op_sel_hi:[1,0]
	v_pk_mul_f32 v[164:165], v[8:9], v[152:153] op_sel_hi:[1,0]
	v_pk_mul_f32 v[166:167], v[2:3], v[152:153] op_sel_hi:[1,0]
	v_pk_mul_f32 v[170:171], v[4:5], v[152:153] op_sel_hi:[1,0]
	v_pk_fma_f32 v[120:121], v[164:165], v[120:121], v[28:29]
	v_pk_fma_f32 v[118:119], v[162:163], v[118:119], v[26:27]
	v_pk_mul_f32 v[172:173], v[30:31], v[152:153] op_sel_hi:[1,0]
	v_pk_mul_f32 v[174:175], v[32:33], v[152:153] op_sel_hi:[1,0]
	v_pk_mul_f32 v[176:177], v[14:15], v[152:153] op_sel_hi:[1,0]
	v_pk_mul_f32 v[152:153], v[16:17], v[152:153] op_sel_hi:[1,0]
	v_pk_fma_f32 v[124:125], v[170:171], v[124:125], v[24:25]
	v_pk_fma_f32 v[122:123], v[166:167], v[122:123], v[22:23]
	v_max_f32_e32 v119, 0, v119
	v_max_f32_e32 v118, 0, v118
	v_max_f32_e32 v121, 0, v121
	v_max_f32_e32 v120, 0, v120
	v_pk_fma_f32 v[128:129], v[174:175], v[128:129], v[20:21]
	v_pk_fma_f32 v[126:127], v[172:173], v[126:127], v[18:19]
	v_pk_fma_f32 v[150:151], v[152:153], v[150:151], v[12:13]
	v_pk_fma_f32 v[148:149], v[176:177], v[148:149], v[10:11]
	v_max_f32_e32 v123, 0, v123
	v_max_f32_e32 v122, 0, v122
	v_max_f32_e32 v125, 0, v125
	v_max_f32_e32 v124, 0, v124
	v_pk_mul_f32 v[120:121], v[120:121], v[120:121]
	v_pk_mul_f32 v[118:119], v[118:119], v[118:119]
	v_max_f32_e32 v127, 0, v127
	v_max_f32_e32 v126, 0, v126
	v_max_f32_e32 v129, 0, v129
	v_max_f32_e32 v128, 0, v128
	v_max_f32_e32 v149, 0, v149
	v_max_f32_e32 v148, 0, v148
	v_max_f32_e32 v151, 0, v151
	v_max_f32_e32 v150, 0, v150
	v_pk_mul_f32 v[124:125], v[124:125], v[124:125]
	v_pk_mul_f32 v[122:123], v[122:123], v[122:123]
	v_cvt_pk_bf16_f32 v118, v118, v119
	v_cvt_pk_bf16_f32 v119, v120, v121
	v_pk_mul_f32 v[128:129], v[128:129], v[128:129]
	v_cvt_pk_bf16_f32 v120, v122, v123
	v_cvt_pk_bf16_f32 v121, v124, v125
	v_pk_mul_f32 v[126:127], v[126:127], v[126:127]
	v_pk_mul_f32 v[150:151], v[150:151], v[150:151]
	v_pk_mul_f32 v[148:149], v[148:149], v[148:149]
	global_store_dwordx4 v[158:159], v[118:121], off nt
	s_nop 1
	v_cvt_pk_bf16_f32 v118, v126, v127
	v_cvt_pk_bf16_f32 v119, v128, v129
	v_cvt_pk_bf16_f32 v120, v148, v149
	v_cvt_pk_bf16_f32 v121, v150, v151
	global_store_dwordx4 v[160:161], v[118:121], off nt
	global_load_dword v118, v[156:157], off
	s_nop 0
	v_lshlrev_b32_e32 v119, 7, v154
	v_and_b32_e32 v138, 0x7f80, v119
	v_lshl_add_u64 v[120:121], s[36:37], 0, v[138:139]
	v_lshl_add_u64 v[122:123], s[38:39], 0, v[138:139]
	v_lshl_add_u64 v[120:121], v[120:121], 0, v[90:91]
	v_lshl_add_u64 v[122:123], v[122:123], 0, v[90:91]
	s_waitcnt vmcnt(0)
	v_pk_mul_f32 v[124:125], v[6:7], v[118:119] op_sel_hi:[1,0]
	v_pk_mul_f32 v[126:127], v[8:9], v[118:119] op_sel_hi:[1,0]
	v_pk_mul_f32 v[128:129], v[2:3], v[118:119] op_sel_hi:[1,0]
	v_pk_mul_f32 v[148:149], v[4:5], v[118:119] op_sel_hi:[1,0]
	v_pk_fma_f32 v[104:105], v[126:127], v[104:105], v[28:29]
	v_pk_fma_f32 v[102:103], v[124:125], v[102:103], v[26:27]
	v_pk_mul_f32 v[150:151], v[30:31], v[118:119] op_sel_hi:[1,0]
	v_pk_mul_f32 v[152:153], v[32:33], v[118:119] op_sel_hi:[1,0]
	v_pk_mul_f32 v[154:155], v[14:15], v[118:119] op_sel_hi:[1,0]
	v_pk_mul_f32 v[118:119], v[16:17], v[118:119] op_sel_hi:[1,0]
	v_pk_fma_f32 v[108:109], v[148:149], v[108:109], v[24:25]
	v_pk_fma_f32 v[106:107], v[128:129], v[106:107], v[22:23]
	v_max_f32_e32 v103, 0, v103
	v_max_f32_e32 v102, 0, v102
	v_max_f32_e32 v105, 0, v105
	v_max_f32_e32 v104, 0, v104
	v_pk_fma_f32 v[112:113], v[152:153], v[112:113], v[20:21]
	v_pk_fma_f32 v[110:111], v[150:151], v[110:111], v[18:19]
	v_pk_fma_f32 v[116:117], v[118:119], v[116:117], v[12:13]
	v_pk_fma_f32 v[114:115], v[154:155], v[114:115], v[10:11]
	v_max_f32_e32 v107, 0, v107
	v_max_f32_e32 v106, 0, v106
	v_max_f32_e32 v109, 0, v109
	v_max_f32_e32 v108, 0, v108
	v_pk_mul_f32 v[104:105], v[104:105], v[104:105]
	v_pk_mul_f32 v[102:103], v[102:103], v[102:103]
	v_max_f32_e32 v111, 0, v111
	v_max_f32_e32 v110, 0, v110
	v_max_f32_e32 v113, 0, v113
	v_max_f32_e32 v112, 0, v112
	v_max_f32_e32 v115, 0, v115
	v_max_f32_e32 v114, 0, v114
	v_max_f32_e32 v117, 0, v117
	v_max_f32_e32 v116, 0, v116
	v_pk_mul_f32 v[108:109], v[108:109], v[108:109]
	v_pk_mul_f32 v[106:107], v[106:107], v[106:107]
	v_cvt_pk_bf16_f32 v102, v102, v103
	v_cvt_pk_bf16_f32 v103, v104, v105
	v_pk_mul_f32 v[112:113], v[112:113], v[112:113]
	v_cvt_pk_bf16_f32 v104, v106, v107
	v_cvt_pk_bf16_f32 v105, v108, v109
	v_pk_mul_f32 v[110:111], v[110:111], v[110:111]
	v_pk_mul_f32 v[116:117], v[116:117], v[116:117]
	v_pk_mul_f32 v[114:115], v[114:115], v[114:115]
	global_store_dwordx4 v[120:121], v[102:105], off nt
	s_nop 1
	v_cvt_pk_bf16_f32 v102, v110, v111
	v_cvt_pk_bf16_f32 v103, v112, v113
	v_cvt_pk_bf16_f32 v104, v114, v115
	v_cvt_pk_bf16_f32 v105, v116, v117
	global_store_dwordx4 v[122:123], v[102:105], off nt
	global_load_dword v106, v[100:101], off offset:512
	s_nop 0
	v_add_u32_e32 v103, 0x80, v168
	v_ashrrev_i32_e32 v102, 8, v103
	v_lshlrev_b32_e32 v107, 7, v103
	v_ashrrev_i32_e32 v103, 31, v102
	v_lshlrev_b64 v[104:105], 7, v[102:103]
	v_lshl_add_u64 v[102:103], v[104:105], 0, s[30:31]
	v_lshl_add_u64 v[104:105], v[104:105], 0, s[34:35]
	v_lshlrev_b64 v[102:103], 15, v[102:103]
	v_lshlrev_b64 v[104:105], 15, v[104:105]
	v_lshl_add_u64 v[102:103], s[12:13], 0, v[102:103]
	v_lshl_add_u64 v[104:105], s[12:13], 0, v[104:105]
	v_and_b32_e32 v138, 0x6780, v107
	v_lshl_add_u64 v[108:109], v[102:103], 0, v[138:139]
	v_lshl_add_u64 v[110:111], v[104:105], 0, v[138:139]
	v_lshl_add_u64 v[108:109], v[108:109], 0, v[90:91]
	v_lshl_add_u64 v[110:111], v[110:111], 0, v[90:91]
	s_waitcnt vmcnt(0)
	v_pk_mul_f32 v[112:113], v[6:7], v[106:107] op_sel_hi:[1,0]
	v_pk_mul_f32 v[114:115], v[8:9], v[106:107] op_sel_hi:[1,0]
	v_pk_mul_f32 v[116:117], v[2:3], v[106:107] op_sel_hi:[1,0]
	v_pk_mul_f32 v[118:119], v[4:5], v[106:107] op_sel_hi:[1,0]
	v_pk_fma_f32 v[84:85], v[114:115], v[84:85], v[28:29]
	v_pk_fma_f32 v[82:83], v[112:113], v[82:83], v[26:27]
	v_pk_mul_f32 v[120:121], v[30:31], v[106:107] op_sel_hi:[1,0]
	v_pk_mul_f32 v[122:123], v[32:33], v[106:107] op_sel_hi:[1,0]
	v_pk_mul_f32 v[124:125], v[14:15], v[106:107] op_sel_hi:[1,0]
	v_pk_mul_f32 v[106:107], v[16:17], v[106:107] op_sel_hi:[1,0]
	v_pk_fma_f32 v[88:89], v[118:119], v[88:89], v[24:25]
	v_pk_fma_f32 v[86:87], v[116:117], v[86:87], v[22:23]
	v_max_f32_e32 v83, 0, v83
	v_max_f32_e32 v82, 0, v82
	v_max_f32_e32 v85, 0, v85
	v_max_f32_e32 v84, 0, v84
	v_pk_fma_f32 v[94:95], v[122:123], v[94:95], v[20:21]
	v_pk_fma_f32 v[92:93], v[120:121], v[92:93], v[18:19]
	v_pk_fma_f32 v[98:99], v[106:107], v[98:99], v[12:13]
	v_pk_fma_f32 v[96:97], v[124:125], v[96:97], v[10:11]
	v_max_f32_e32 v87, 0, v87
	v_max_f32_e32 v86, 0, v86
	v_max_f32_e32 v89, 0, v89
	v_max_f32_e32 v88, 0, v88
	v_pk_mul_f32 v[84:85], v[84:85], v[84:85]
	v_pk_mul_f32 v[82:83], v[82:83], v[82:83]
	v_max_f32_e32 v93, 0, v93
	v_max_f32_e32 v92, 0, v92
	v_max_f32_e32 v95, 0, v95
	v_max_f32_e32 v94, 0, v94
	v_max_f32_e32 v97, 0, v97
	v_max_f32_e32 v96, 0, v96
	v_max_f32_e32 v99, 0, v99
	v_max_f32_e32 v98, 0, v98
	v_pk_mul_f32 v[88:89], v[88:89], v[88:89]
	v_pk_mul_f32 v[86:87], v[86:87], v[86:87]
	v_cvt_pk_bf16_f32 v82, v82, v83
	v_cvt_pk_bf16_f32 v83, v84, v85
	v_pk_mul_f32 v[94:95], v[94:95], v[94:95]
	v_cvt_pk_bf16_f32 v84, v86, v87
	v_cvt_pk_bf16_f32 v85, v88, v89
	v_pk_mul_f32 v[92:93], v[92:93], v[92:93]
	v_pk_mul_f32 v[98:99], v[98:99], v[98:99]
	v_pk_mul_f32 v[96:97], v[96:97], v[96:97]
	global_store_dwordx4 v[108:109], v[82:85], off nt
	s_nop 1
	v_cvt_pk_bf16_f32 v82, v92, v93
	v_cvt_pk_bf16_f32 v83, v94, v95
	v_cvt_pk_bf16_f32 v84, v96, v97
	v_cvt_pk_bf16_f32 v85, v98, v99
	global_store_dwordx4 v[110:111], v[82:85], off nt
	global_load_dword v82, v[100:101], off offset:576
	s_nop 0
	v_add_u32_e32 v83, 0x4800, v169
	v_and_b32_e32 v138, 0x6f80, v83
	v_lshl_add_u64 v[84:85], v[102:103], 0, v[138:139]
	v_lshl_add_u64 v[86:87], v[104:105], 0, v[138:139]
	v_lshl_add_u64 v[84:85], v[84:85], 0, v[90:91]
	v_lshl_add_u64 v[86:87], v[86:87], 0, v[90:91]
	s_waitcnt vmcnt(0)
	v_pk_mul_f32 v[88:89], v[6:7], v[82:83] op_sel_hi:[1,0]
	v_pk_mul_f32 v[92:93], v[8:9], v[82:83] op_sel_hi:[1,0]
	v_pk_mul_f32 v[94:95], v[2:3], v[82:83] op_sel_hi:[1,0]
	v_pk_mul_f32 v[96:97], v[4:5], v[82:83] op_sel_hi:[1,0]
	v_pk_fma_f32 v[68:69], v[92:93], v[68:69], v[28:29]
	v_pk_fma_f32 v[66:67], v[88:89], v[66:67], v[26:27]
	v_pk_mul_f32 v[98:99], v[30:31], v[82:83] op_sel_hi:[1,0]
	v_pk_mul_f32 v[106:107], v[32:33], v[82:83] op_sel_hi:[1,0]
	v_pk_mul_f32 v[108:109], v[14:15], v[82:83] op_sel_hi:[1,0]
	v_pk_mul_f32 v[82:83], v[16:17], v[82:83] op_sel_hi:[1,0]
	v_pk_fma_f32 v[72:73], v[96:97], v[72:73], v[24:25]
	v_pk_fma_f32 v[70:71], v[94:95], v[70:71], v[22:23]
	v_max_f32_e32 v67, 0, v67
	v_max_f32_e32 v66, 0, v66
	v_max_f32_e32 v69, 0, v69
	v_max_f32_e32 v68, 0, v68
	v_pk_fma_f32 v[76:77], v[106:107], v[76:77], v[20:21]
	v_pk_fma_f32 v[74:75], v[98:99], v[74:75], v[18:19]
	v_pk_fma_f32 v[80:81], v[82:83], v[80:81], v[12:13]
	v_pk_fma_f32 v[78:79], v[108:109], v[78:79], v[10:11]
	v_max_f32_e32 v71, 0, v71
	v_max_f32_e32 v70, 0, v70
	v_max_f32_e32 v73, 0, v73
	v_max_f32_e32 v72, 0, v72
	v_pk_mul_f32 v[68:69], v[68:69], v[68:69]
	v_pk_mul_f32 v[66:67], v[66:67], v[66:67]
	v_max_f32_e32 v75, 0, v75
	v_max_f32_e32 v74, 0, v74
	v_max_f32_e32 v77, 0, v77
	v_max_f32_e32 v76, 0, v76
	v_max_f32_e32 v79, 0, v79
	v_max_f32_e32 v78, 0, v78
	v_max_f32_e32 v81, 0, v81
	v_max_f32_e32 v80, 0, v80
	v_pk_mul_f32 v[72:73], v[72:73], v[72:73]
	v_pk_mul_f32 v[70:71], v[70:71], v[70:71]
	v_cvt_pk_bf16_f32 v66, v66, v67
	v_cvt_pk_bf16_f32 v67, v68, v69
	v_pk_mul_f32 v[76:77], v[76:77], v[76:77]
	v_cvt_pk_bf16_f32 v68, v70, v71
	v_cvt_pk_bf16_f32 v69, v72, v73
	v_pk_mul_f32 v[74:75], v[74:75], v[74:75]
	v_pk_mul_f32 v[80:81], v[80:81], v[80:81]
	v_pk_mul_f32 v[78:79], v[78:79], v[78:79]
	global_store_dwordx4 v[84:85], v[66:69], off nt
	s_nop 1
	v_cvt_pk_bf16_f32 v66, v74, v75
	v_cvt_pk_bf16_f32 v67, v76, v77
	v_cvt_pk_bf16_f32 v68, v78, v79
	v_cvt_pk_bf16_f32 v69, v80, v81
	global_store_dwordx4 v[86:87], v[66:69], off nt
	global_load_dword v66, v[100:101], off offset:640
	s_nop 0
	v_add_u32_e32 v67, 0x5000, v169
	v_and_b32_e32 v138, 0x7780, v67
	v_lshl_add_u64 v[68:69], v[102:103], 0, v[138:139]
	v_lshl_add_u64 v[70:71], v[104:105], 0, v[138:139]
	v_lshl_add_u64 v[68:69], v[68:69], 0, v[90:91]
	v_lshl_add_u64 v[70:71], v[70:71], 0, v[90:91]
	s_waitcnt vmcnt(0)
	v_pk_mul_f32 v[72:73], v[6:7], v[66:67] op_sel_hi:[1,0]
	v_pk_mul_f32 v[74:75], v[8:9], v[66:67] op_sel_hi:[1,0]
	v_pk_mul_f32 v[76:77], v[2:3], v[66:67] op_sel_hi:[1,0]
	v_pk_mul_f32 v[78:79], v[4:5], v[66:67] op_sel_hi:[1,0]
	v_pk_fma_f32 v[52:53], v[74:75], v[52:53], v[28:29]
	v_pk_fma_f32 v[50:51], v[72:73], v[50:51], v[26:27]
	v_pk_mul_f32 v[80:81], v[30:31], v[66:67] op_sel_hi:[1,0]
	v_pk_mul_f32 v[82:83], v[32:33], v[66:67] op_sel_hi:[1,0]
	v_pk_mul_f32 v[84:85], v[14:15], v[66:67] op_sel_hi:[1,0]
	v_pk_mul_f32 v[66:67], v[16:17], v[66:67] op_sel_hi:[1,0]
	v_pk_fma_f32 v[56:57], v[78:79], v[56:57], v[24:25]
	v_pk_fma_f32 v[54:55], v[76:77], v[54:55], v[22:23]
	v_max_f32_e32 v51, 0, v51
	v_max_f32_e32 v50, 0, v50
	v_max_f32_e32 v53, 0, v53
	v_max_f32_e32 v52, 0, v52
	v_pk_fma_f32 v[60:61], v[82:83], v[60:61], v[20:21]
	v_pk_fma_f32 v[58:59], v[80:81], v[58:59], v[18:19]
	v_pk_fma_f32 v[64:65], v[66:67], v[64:65], v[12:13]
	v_pk_fma_f32 v[62:63], v[84:85], v[62:63], v[10:11]
	v_max_f32_e32 v55, 0, v55
	v_max_f32_e32 v54, 0, v54
	v_max_f32_e32 v57, 0, v57
	v_max_f32_e32 v56, 0, v56
	v_pk_mul_f32 v[52:53], v[52:53], v[52:53]
	v_pk_mul_f32 v[50:51], v[50:51], v[50:51]
	v_max_f32_e32 v59, 0, v59
	v_max_f32_e32 v58, 0, v58
	v_max_f32_e32 v61, 0, v61
	v_max_f32_e32 v60, 0, v60
	v_max_f32_e32 v63, 0, v63
	v_max_f32_e32 v62, 0, v62
	v_max_f32_e32 v65, 0, v65
	v_max_f32_e32 v64, 0, v64
	v_pk_mul_f32 v[56:57], v[56:57], v[56:57]
	v_pk_mul_f32 v[54:55], v[54:55], v[54:55]
	v_cvt_pk_bf16_f32 v50, v50, v51
	v_cvt_pk_bf16_f32 v51, v52, v53
	v_pk_mul_f32 v[60:61], v[60:61], v[60:61]
	v_cvt_pk_bf16_f32 v52, v54, v55
	v_cvt_pk_bf16_f32 v53, v56, v57
	v_pk_mul_f32 v[58:59], v[58:59], v[58:59]
	v_pk_mul_f32 v[64:65], v[64:65], v[64:65]
	v_pk_mul_f32 v[62:63], v[62:63], v[62:63]
	global_store_dwordx4 v[68:69], v[50:53], off nt
	s_nop 1
	v_cvt_pk_bf16_f32 v50, v58, v59
	v_cvt_pk_bf16_f32 v51, v60, v61
	v_cvt_pk_bf16_f32 v52, v62, v63
	v_cvt_pk_bf16_f32 v53, v64, v65
	global_store_dwordx4 v[70:71], v[50:53], off nt
	global_load_dword v50, v[100:101], off offset:704
	s_nop 0
	v_add_u32_e32 v51, 0x5800, v169
	v_and_b32_e32 v138, 0x7f80, v51
	v_lshl_add_u64 v[52:53], v[102:103], 0, v[138:139]
	v_lshl_add_u64 v[54:55], v[104:105], 0, v[138:139]
	v_lshl_add_u64 v[52:53], v[52:53], 0, v[90:91]
	v_lshl_add_u64 v[54:55], v[54:55], 0, v[90:91]
	s_waitcnt vmcnt(0)
	v_pk_mul_f32 v[2:3], v[2:3], v[50:51] op_sel_hi:[1,0]
	v_pk_mul_f32 v[4:5], v[4:5], v[50:51] op_sel_hi:[1,0]
	v_pk_mul_f32 v[6:7], v[6:7], v[50:51] op_sel_hi:[1,0]
	v_pk_mul_f32 v[8:9], v[8:9], v[50:51] op_sel_hi:[1,0]
	v_pk_mul_f32 v[30:31], v[30:31], v[50:51] op_sel_hi:[1,0]
	v_pk_fma_f32 v[4:5], v[4:5], v[40:41], v[24:25]
	v_pk_fma_f32 v[2:3], v[2:3], v[38:39], v[22:23]
	v_pk_mul_f32 v[32:33], v[32:33], v[50:51] op_sel_hi:[1,0]
	v_pk_mul_f32 v[14:15], v[14:15], v[50:51] op_sel_hi:[1,0]
	v_pk_mul_f32 v[16:17], v[16:17], v[50:51] op_sel_hi:[1,0]
	v_pk_fma_f32 v[8:9], v[8:9], v[36:37], v[28:29]
	v_pk_fma_f32 v[6:7], v[6:7], v[34:35], v[26:27]
	v_pk_fma_f32 v[18:19], v[30:31], v[42:43], v[18:19]
	v_max_f32_e32 v3, 0, v3
	v_max_f32_e32 v2, 0, v2
	v_max_f32_e32 v5, 0, v5
	v_max_f32_e32 v4, 0, v4
	v_pk_fma_f32 v[20:21], v[32:33], v[44:45], v[20:21]
	v_pk_fma_f32 v[12:13], v[16:17], v[48:49], v[12:13]
	v_pk_fma_f32 v[10:11], v[14:15], v[46:47], v[10:11]
	v_max_f32_e32 v7, 0, v7
	v_max_f32_e32 v6, 0, v6
	v_max_f32_e32 v9, 0, v9
	v_max_f32_e32 v8, 0, v8
	v_max_f32_e32 v15, 0, v19
	v_max_f32_e32 v14, 0, v18
	v_pk_mul_f32 v[18:19], v[4:5], v[4:5]
	v_pk_mul_f32 v[4:5], v[2:3], v[2:3]
	v_max_f32_e32 v17, 0, v21
	v_max_f32_e32 v16, 0, v20
	v_max_f32_e32 v11, 0, v11
	v_max_f32_e32 v10, 0, v10
	v_max_f32_e32 v13, 0, v13
	v_max_f32_e32 v12, 0, v12
	v_pk_mul_f32 v[8:9], v[8:9], v[8:9]
	v_pk_mul_f32 v[6:7], v[6:7], v[6:7]
	v_pk_mul_f32 v[16:17], v[16:17], v[16:17]
	v_cvt_pk_bf16_f32 v2, v6, v7
	v_cvt_pk_bf16_f32 v3, v8, v9
	v_cvt_pk_bf16_f32 v4, v4, v5
	v_cvt_pk_bf16_f32 v5, v18, v19
	v_pk_mul_f32 v[14:15], v[14:15], v[14:15]
	v_pk_mul_f32 v[12:13], v[12:13], v[12:13]
	v_pk_mul_f32 v[10:11], v[10:11], v[10:11]
	global_store_dwordx4 v[52:53], v[2:5], off nt
	s_nop 1
	v_cvt_pk_bf16_f32 v2, v14, v15
	v_cvt_pk_bf16_f32 v3, v16, v17
	v_cvt_pk_bf16_f32 v4, v10, v11
	v_cvt_pk_bf16_f32 v5, v12, v13
	global_store_dwordx4 v[54:55], v[2:5], off nt
	s_cbranch_vccnz .LBB0_1074
	s_andn2_b64 vcc, exec, s[10:11]
	s_cbranch_vccnz .LBB0_1073
	s_barrier
	s_branch .LBB0_1073

.LBB0_1170:
	s_waitcnt lgkmcnt(0)
	ds_read_b128 v[114:117], v209
	ds_read_b128 v[118:121], v209 offset:1024
	ds_read_b128 v[122:125], v209 offset:2048
	ds_read_b128 v[126:129], v209 offset:3072
	ds_read_b128 v[146:149], v210
	ds_read_b128 v[150:153], v210 offset:1024
	ds_read_b128 v[154:157], v210 offset:2048
	ds_read_b128 v[158:161], v210 offset:3072
	s_add_i32 s92, s42, 2
	s_add_u32 s43, s38, 0x4000
	s_addc_u32 s44, s39, 0
	s_cmp_eq_u32 s81, s42
	s_cselect_b32 s45, s5, s44
	s_cselect_b32 s44, s4, s43
	s_cselect_b32 s94, s36, s90
	s_cselect_b32 s95, s37, s91
	s_add_u32 s42, s44, 0x8000
	s_addc_u32 s43, s45, 0
	v_lshl_add_u64 v[218:219], s[38:39], 0, v[170:171]
	s_add_i32 m0, s55, 0xc000
	ds_read_b128 v[178:181], v211
	ds_read_b128 v[182:185], v211 offset:1024
	ds_read_b128 v[186:189], v211 offset:2048
	ds_read_b128 v[190:193], v211 offset:3072
	ds_read_b128 v[194:197], v211 offset:4096
	ds_read_b128 v[198:201], v211 offset:5120
	ds_read_b128 v[202:205], v211 offset:6144
	ds_read_b128 v[214:217], v211 offset:7168
	global_load_lds_dwordx4 v[218:219], off nt
	v_lshl_add_u64 v[218:219], s[38:39], 0, v[172:173]
	s_add_i32 m0, s55, 0xe000
	s_nop 0
	global_load_lds_dwordx4 v[218:219], off nt
	s_waitcnt vmcnt(8)
	s_waitcnt lgkmcnt(0)
	s_setprio 1
	s_waitcnt lgkmcnt(0)
	v_mfma_f32_16x16x32_bf16 v[142:145], v[114:117], v[178:181], v[142:145]
	v_mfma_f32_16x16x32_bf16 v[138:141], v[122:125], v[178:181], v[138:141]
	s_barrier
	v_mfma_f32_16x16x32_bf16 v[110:113], v[114:117], v[186:189], v[110:113]
	v_mfma_f32_16x16x32_bf16 v[106:109], v[122:125], v[186:189], v[106:109]
	v_mfma_f32_16x16x32_bf16 v[94:97], v[114:117], v[194:197], v[94:97]
	v_mfma_f32_16x16x32_bf16 v[90:93], v[122:125], v[194:197], v[90:93]
	v_mfma_f32_16x16x32_bf16 v[78:81], v[114:117], v[202:205], v[78:81]
	v_mfma_f32_16x16x32_bf16 v[74:77], v[122:125], v[202:205], v[74:77]
	v_mfma_f32_16x16x32_bf16 v[142:145], v[118:121], v[182:185], v[142:145]
	v_mfma_f32_16x16x32_bf16 v[138:141], v[126:129], v[182:185], v[138:141]
	v_mfma_f32_16x16x32_bf16 v[110:113], v[118:121], v[190:193], v[110:113]
	v_mfma_f32_16x16x32_bf16 v[106:109], v[126:129], v[190:193], v[106:109]
	v_mfma_f32_16x16x32_bf16 v[94:97], v[118:121], v[198:201], v[94:97]
	v_mfma_f32_16x16x32_bf16 v[90:93], v[126:129], v[198:201], v[90:93]
	v_mfma_f32_16x16x32_bf16 v[78:81], v[118:121], v[214:217], v[78:81]
	v_mfma_f32_16x16x32_bf16 v[74:77], v[126:129], v[214:217], v[74:77]
	s_setprio 0
	s_setprio 1
	v_mfma_f32_16x16x32_bf16 v[134:137], v[146:149], v[178:181], v[134:137]
	v_mfma_f32_16x16x32_bf16 v[130:133], v[154:157], v[178:181], v[130:133]
	v_mfma_f32_16x16x32_bf16 v[102:105], v[146:149], v[186:189], v[102:105]
	v_mfma_f32_16x16x32_bf16 v[98:101], v[154:157], v[186:189], v[98:101]
	v_mfma_f32_16x16x32_bf16 v[86:89], v[146:149], v[194:197], v[86:89]
	v_mfma_f32_16x16x32_bf16 v[82:85], v[154:157], v[194:197], v[82:85]
	v_mfma_f32_16x16x32_bf16 v[70:73], v[146:149], v[202:205], v[70:73]
	v_mfma_f32_16x16x32_bf16 v[66:69], v[154:157], v[202:205], v[66:69]
	v_mfma_f32_16x16x32_bf16 v[134:137], v[150:153], v[182:185], v[134:137]
	v_mfma_f32_16x16x32_bf16 v[130:133], v[158:161], v[182:185], v[130:133]
	v_mfma_f32_16x16x32_bf16 v[102:105], v[150:153], v[190:193], v[102:105]
	v_mfma_f32_16x16x32_bf16 v[98:101], v[158:161], v[190:193], v[98:101]
	v_mfma_f32_16x16x32_bf16 v[86:89], v[150:153], v[198:201], v[86:89]
	v_mfma_f32_16x16x32_bf16 v[82:85], v[158:161], v[198:201], v[82:85]
	v_mfma_f32_16x16x32_bf16 v[70:73], v[150:153], v[214:217], v[70:73]
	v_mfma_f32_16x16x32_bf16 v[66:69], v[158:161], v[214:217], v[66:69]
	s_setprio 0
	s_barrier
	s_add_i32 s93, s84, s54
	v_lshl_add_u64 v[218:219], s[94:95], 0, v[164:165]
	s_mov_b32 m0, s93
	ds_read_b128 v[178:181], v211 offset:16384
	ds_read_b128 v[182:185], v211 offset:17408
	ds_read_b128 v[186:189], v211 offset:18432
	ds_read_b128 v[190:193], v211 offset:19456
	ds_read_b128 v[194:197], v211 offset:20480
	ds_read_b128 v[198:201], v211 offset:21504
	ds_read_b128 v[202:205], v211 offset:22528
	ds_read_b128 v[214:217], v211 offset:23552
	global_load_lds_dwordx4 v[218:219], off
	s_add_i32 m0, s93, 0x2000
	v_lshl_add_u64 v[220:221], s[94:95], 0, v[168:169]
	s_add_u32 s94, s94, s8
	s_addc_u32 s95, s95, s9
	s_add_i32 s93, s85, s54
	global_load_lds_dwordx4 v[220:221], off
	v_lshl_add_u64 v[222:223], s[94:95], 0, v[164:165]
	s_mov_b32 m0, s93
	v_lshl_add_u64 v[224:225], s[94:95], 0, v[168:169]
	global_load_lds_dwordx4 v[222:223], off
	s_add_i32 m0, s93, 0x2000
	v_lshl_add_u64 v[226:227], s[44:45], 0, v[162:163]
	global_load_lds_dwordx4 v[224:225], off
	s_mov_b32 m0, s55
	s_nop 0
	global_load_lds_dwordx4 v[226:227], off nt
	v_lshl_add_u64 v[226:227], s[44:45], 0, v[166:167]
	s_mov_b32 m0, s56
	s_nop 0
	global_load_lds_dwordx4 v[226:227], off nt
	s_waitcnt vmcnt(8)
	s_waitcnt lgkmcnt(0)
	s_setprio 1
	s_waitcnt lgkmcnt(0)
	v_mfma_f32_16x16x32_bf16 v[62:65], v[114:117], v[178:181], v[62:65]
	v_mfma_f32_16x16x32_bf16 v[58:61], v[122:125], v[178:181], v[58:61]
	s_barrier
	v_mfma_f32_16x16x32_bf16 v[46:49], v[114:117], v[186:189], v[46:49]
	v_mfma_f32_16x16x32_bf16 v[42:45], v[122:125], v[186:189], v[42:45]
	v_mfma_f32_16x16x32_bf16 v[30:33], v[114:117], v[194:197], v[30:33]
	v_mfma_f32_16x16x32_bf16 v[26:29], v[122:125], v[194:197], v[26:29]
	v_mfma_f32_16x16x32_bf16 v[14:17], v[114:117], v[202:205], v[14:17]
	v_mfma_f32_16x16x32_bf16 v[10:13], v[122:125], v[202:205], v[10:13]
	v_mfma_f32_16x16x32_bf16 v[62:65], v[118:121], v[182:185], v[62:65]
	v_mfma_f32_16x16x32_bf16 v[58:61], v[126:129], v[182:185], v[58:61]
	v_mfma_f32_16x16x32_bf16 v[46:49], v[118:121], v[190:193], v[46:49]
	v_mfma_f32_16x16x32_bf16 v[42:45], v[126:129], v[190:193], v[42:45]
	v_mfma_f32_16x16x32_bf16 v[30:33], v[118:121], v[198:201], v[30:33]
	v_mfma_f32_16x16x32_bf16 v[26:29], v[126:129], v[198:201], v[26:29]
	v_mfma_f32_16x16x32_bf16 v[14:17], v[118:121], v[214:217], v[14:17]
	v_mfma_f32_16x16x32_bf16 v[10:13], v[126:129], v[214:217], v[10:13]
	s_setprio 0
	s_setprio 1
	v_mfma_f32_16x16x32_bf16 v[54:57], v[146:149], v[178:181], v[54:57]
	v_mfma_f32_16x16x32_bf16 v[50:53], v[154:157], v[178:181], v[50:53]
	v_mfma_f32_16x16x32_bf16 v[38:41], v[146:149], v[186:189], v[38:41]
	v_mfma_f32_16x16x32_bf16 v[34:37], v[154:157], v[186:189], v[34:37]
	v_mfma_f32_16x16x32_bf16 v[22:25], v[146:149], v[194:197], v[22:25]
	v_mfma_f32_16x16x32_bf16 v[18:21], v[154:157], v[194:197], v[18:21]
	v_mfma_f32_16x16x32_bf16 v[6:9], v[146:149], v[202:205], v[6:9]
	v_mfma_f32_16x16x32_bf16 v[2:5], v[154:157], v[202:205], v[2:5]
	v_mfma_f32_16x16x32_bf16 v[54:57], v[150:153], v[182:185], v[54:57]
	v_mfma_f32_16x16x32_bf16 v[50:53], v[158:161], v[182:185], v[50:53]
	v_mfma_f32_16x16x32_bf16 v[38:41], v[150:153], v[190:193], v[38:41]
	v_mfma_f32_16x16x32_bf16 v[34:37], v[158:161], v[190:193], v[34:37]
	v_mfma_f32_16x16x32_bf16 v[22:25], v[150:153], v[198:201], v[22:25]
	v_mfma_f32_16x16x32_bf16 v[18:21], v[158:161], v[198:201], v[18:21]
	v_mfma_f32_16x16x32_bf16 v[6:9], v[150:153], v[214:217], v[6:9]
	v_mfma_f32_16x16x32_bf16 v[2:5], v[158:161], v[214:217], v[2:5]
	s_setprio 0
	s_barrier
	s_add_i32 s93, 0, 0x18000
	s_add_i32 s94, 0, 0x1c000
	v_add_u32_e32 v126, s93, v207
	v_add_u32_e32 v158, s94, v207
	ds_read_b128 v[114:117], v126
	ds_read_b128 v[118:121], v126 offset:1024
	ds_read_b128 v[122:125], v126 offset:2048
	ds_read_b128 v[126:129], v126 offset:3072
	ds_read_b128 v[146:149], v158
	ds_read_b128 v[150:153], v158 offset:1024
	ds_read_b128 v[154:157], v158 offset:2048
	ds_read_b128 v[158:161], v158 offset:3072
	s_add_u32 s44, s44, 0x4000
	s_addc_u32 s45, s45, 0
	s_mov_b32 m0, s57
	v_lshl_add_u64 v[226:227], s[44:45], 0, v[162:163]
	ds_read_b128 v[178:181], v211 offset:32768
	ds_read_b128 v[182:185], v211 offset:33792
	ds_read_b128 v[186:189], v211 offset:34816
	ds_read_b128 v[190:193], v211 offset:35840
	ds_read_b128 v[194:197], v211 offset:36864
	ds_read_b128 v[198:201], v211 offset:37888
	ds_read_b128 v[202:205], v211 offset:38912
	ds_read_b128 v[214:217], v211 offset:39936
	global_load_lds_dwordx4 v[226:227], off nt
	v_lshl_add_u64 v[226:227], s[44:45], 0, v[166:167]
	s_mov_b32 m0, s58
	s_nop 0
	global_load_lds_dwordx4 v[226:227], off nt
	s_waitcnt vmcnt(8)
	s_waitcnt lgkmcnt(0)
	s_setprio 1
	s_waitcnt lgkmcnt(0)
	v_mfma_f32_16x16x32_bf16 v[142:145], v[114:117], v[178:181], v[142:145]
	v_mfma_f32_16x16x32_bf16 v[138:141], v[122:125], v[178:181], v[138:141]
	s_barrier
	v_mfma_f32_16x16x32_bf16 v[110:113], v[114:117], v[186:189], v[110:113]
	v_mfma_f32_16x16x32_bf16 v[106:109], v[122:125], v[186:189], v[106:109]
	v_mfma_f32_16x16x32_bf16 v[94:97], v[114:117], v[194:197], v[94:97]
	v_mfma_f32_16x16x32_bf16 v[90:93], v[122:125], v[194:197], v[90:93]
	v_mfma_f32_16x16x32_bf16 v[78:81], v[114:117], v[202:205], v[78:81]
	v_mfma_f32_16x16x32_bf16 v[74:77], v[122:125], v[202:205], v[74:77]
	v_mfma_f32_16x16x32_bf16 v[142:145], v[118:121], v[182:185], v[142:145]
	v_mfma_f32_16x16x32_bf16 v[138:141], v[126:129], v[182:185], v[138:141]
	v_mfma_f32_16x16x32_bf16 v[110:113], v[118:121], v[190:193], v[110:113]
	v_mfma_f32_16x16x32_bf16 v[106:109], v[126:129], v[190:193], v[106:109]
	v_mfma_f32_16x16x32_bf16 v[94:97], v[118:121], v[198:201], v[94:97]
	v_mfma_f32_16x16x32_bf16 v[90:93], v[126:129], v[198:201], v[90:93]
	v_mfma_f32_16x16x32_bf16 v[78:81], v[118:121], v[214:217], v[78:81]
	v_mfma_f32_16x16x32_bf16 v[74:77], v[126:129], v[214:217], v[74:77]
	s_setprio 0
	s_setprio 1
	v_mfma_f32_16x16x32_bf16 v[134:137], v[146:149], v[178:181], v[134:137]
	v_mfma_f32_16x16x32_bf16 v[130:133], v[154:157], v[178:181], v[130:133]
	v_mfma_f32_16x16x32_bf16 v[102:105], v[146:149], v[186:189], v[102:105]
	v_mfma_f32_16x16x32_bf16 v[98:101], v[154:157], v[186:189], v[98:101]
	v_mfma_f32_16x16x32_bf16 v[86:89], v[146:149], v[194:197], v[86:89]
	v_mfma_f32_16x16x32_bf16 v[82:85], v[154:157], v[194:197], v[82:85]
	v_mfma_f32_16x16x32_bf16 v[70:73], v[146:149], v[202:205], v[70:73]
	v_mfma_f32_16x16x32_bf16 v[66:69], v[154:157], v[202:205], v[66:69]
	v_mfma_f32_16x16x32_bf16 v[134:137], v[150:153], v[182:185], v[134:137]
	v_mfma_f32_16x16x32_bf16 v[130:133], v[158:161], v[182:185], v[130:133]
	v_mfma_f32_16x16x32_bf16 v[102:105], v[150:153], v[190:193], v[102:105]
	v_mfma_f32_16x16x32_bf16 v[98:101], v[158:161], v[190:193], v[98:101]
	v_mfma_f32_16x16x32_bf16 v[86:89], v[150:153], v[198:201], v[86:89]
	v_mfma_f32_16x16x32_bf16 v[82:85], v[158:161], v[198:201], v[82:85]
	v_mfma_f32_16x16x32_bf16 v[70:73], v[150:153], v[214:217], v[70:73]
	v_mfma_f32_16x16x32_bf16 v[66:69], v[158:161], v[214:217], v[66:69]
	s_setprio 0
	s_barrier
	s_add_i32 s44, s93, s54
	v_lshl_add_u64 v[218:219], v[218:219], 0, s[28:29]
	s_mov_b32 m0, s44
	ds_read_b128 v[178:181], v211 offset:49152
	ds_read_b128 v[182:185], v211 offset:50176
	ds_read_b128 v[186:189], v211 offset:51200
	ds_read_b128 v[190:193], v211 offset:52224
	ds_read_b128 v[194:197], v211 offset:53248
	ds_read_b128 v[198:201], v211 offset:54272
	ds_read_b128 v[202:205], v211 offset:55296
	ds_read_b128 v[214:217], v211 offset:56320
	global_load_lds_dwordx4 v[218:219], off
	v_lshl_add_u64 v[218:219], v[220:221], 0, s[28:29]
	s_add_i32 m0, s44, 0x2000
	s_add_i32 s44, s94, s54
	global_load_lds_dwordx4 v[218:219], off
	v_lshl_add_u64 v[218:219], v[222:223], 0, s[28:29]
	s_mov_b32 m0, s44
	s_nop 0
	global_load_lds_dwordx4 v[218:219], off
	v_lshl_add_u64 v[218:219], v[224:225], 0, s[28:29]
	s_add_i32 m0, s44, 0x2000
	s_nop 0
	global_load_lds_dwordx4 v[218:219], off
	v_lshl_add_u64 v[218:219], s[42:43], 0, v[162:163]
	s_mov_b32 m0, s65
	s_nop 0
	global_load_lds_dwordx4 v[218:219], off nt
	v_lshl_add_u64 v[218:219], s[42:43], 0, v[166:167]
	s_mov_b32 m0, s80
	s_nop 0
	global_load_lds_dwordx4 v[218:219], off nt
	s_waitcnt vmcnt(8)
	s_waitcnt lgkmcnt(0)
	s_setprio 1
	s_waitcnt lgkmcnt(0)
	v_mfma_f32_16x16x32_bf16 v[62:65], v[114:117], v[178:181], v[62:65]
	v_mfma_f32_16x16x32_bf16 v[58:61], v[122:125], v[178:181], v[58:61]
	s_barrier
	v_mfma_f32_16x16x32_bf16 v[46:49], v[114:117], v[186:189], v[46:49]
	v_mfma_f32_16x16x32_bf16 v[42:45], v[122:125], v[186:189], v[42:45]
	v_mfma_f32_16x16x32_bf16 v[30:33], v[114:117], v[194:197], v[30:33]
	v_mfma_f32_16x16x32_bf16 v[26:29], v[122:125], v[194:197], v[26:29]
	v_mfma_f32_16x16x32_bf16 v[14:17], v[114:117], v[202:205], v[14:17]
	v_mfma_f32_16x16x32_bf16 v[10:13], v[122:125], v[202:205], v[10:13]
	v_mfma_f32_16x16x32_bf16 v[62:65], v[118:121], v[182:185], v[62:65]
	v_mfma_f32_16x16x32_bf16 v[58:61], v[126:129], v[182:185], v[58:61]
	v_mfma_f32_16x16x32_bf16 v[46:49], v[118:121], v[190:193], v[46:49]
	v_mfma_f32_16x16x32_bf16 v[42:45], v[126:129], v[190:193], v[42:45]
	v_mfma_f32_16x16x32_bf16 v[30:33], v[118:121], v[198:201], v[30:33]
	v_mfma_f32_16x16x32_bf16 v[26:29], v[126:129], v[198:201], v[26:29]
	v_mfma_f32_16x16x32_bf16 v[14:17], v[118:121], v[214:217], v[14:17]
	v_mfma_f32_16x16x32_bf16 v[10:13], v[126:129], v[214:217], v[10:13]
	s_setprio 0
	s_setprio 1
	v_mfma_f32_16x16x32_bf16 v[54:57], v[146:149], v[178:181], v[54:57]
	v_mfma_f32_16x16x32_bf16 v[50:53], v[154:157], v[178:181], v[50:53]
	v_mfma_f32_16x16x32_bf16 v[38:41], v[146:149], v[186:189], v[38:41]
	v_mfma_f32_16x16x32_bf16 v[34:37], v[154:157], v[186:189], v[34:37]
	v_mfma_f32_16x16x32_bf16 v[22:25], v[146:149], v[194:197], v[22:25]
	v_mfma_f32_16x16x32_bf16 v[18:21], v[154:157], v[194:197], v[18:21]
	v_mfma_f32_16x16x32_bf16 v[6:9], v[146:149], v[202:205], v[6:9]
	v_mfma_f32_16x16x32_bf16 v[2:5], v[154:157], v[202:205], v[2:5]
	v_mfma_f32_16x16x32_bf16 v[54:57], v[150:153], v[182:185], v[54:57]
	v_mfma_f32_16x16x32_bf16 v[50:53], v[158:161], v[182:185], v[50:53]
	v_mfma_f32_16x16x32_bf16 v[38:41], v[150:153], v[190:193], v[38:41]
	v_mfma_f32_16x16x32_bf16 v[34:37], v[158:161], v[190:193], v[34:37]
	v_mfma_f32_16x16x32_bf16 v[22:25], v[150:153], v[198:201], v[22:25]
	v_mfma_f32_16x16x32_bf16 v[18:21], v[158:161], v[198:201], v[18:21]
	v_mfma_f32_16x16x32_bf16 v[6:9], v[150:153], v[214:217], v[6:9]
	v_mfma_f32_16x16x32_bf16 v[2:5], v[158:161], v[214:217], v[2:5]
	s_setprio 0
	s_barrier
	s_add_u32 s90, s90, 0x100
	s_addc_u32 s91, s91, 0
	s_add_u32 s38, s38, 0x10000
	s_addc_u32 s39, s39, 0
	s_cmp_ge_i32 s92, s64
	s_mov_b32 s42, s92
	s_cbranch_scc0 .LBB0_1170

.LBB0_1943:
	s_lshl_b32 s26, s30, 8
	s_add_i32 s28, s26, s58
	s_lshl_b32 s26, s31, 8
	s_or_b32 s29, s26, s59
	s_lshr_b32 s26, s30, 4
	s_add_i32 s26, s26, -1
	v_or_b32_e32 v2, s29, v186
	s_cmp_gt_i32 s30, 31
	s_cselect_b32 s26, s26, 0
	v_ashrrev_i32_e32 v3, 31, v2
	v_or_b32_e32 v168, s28, v187
	v_lshlrev_b64 v[10:11], 2, v[2:3]
	v_ashrrev_i32_e32 v169, 31, v168
	s_ashr_i32 s27, s26, 31
	v_lshl_add_u64 v[12:13], s[16:17], 0, v[10:11]
	v_lshl_add_u64 v[100:101], v[168:169], 2, s[14:15]
	s_lshl_b64 s[26:27], s[26:27], 15
	global_load_dwordx4 v[2:5], v[12:13], off offset:16
	global_load_dwordx4 v[6:9], v[12:13], off
	global_load_dword v190, v[100:101], off
	s_add_u32 s26, s51, s26
	global_load_dwordx4 v[14:17], v[12:13], off offset:528
	global_load_dwordx4 v[30:33], v[12:13], off offset:512
	s_addc_u32 s27, s54, s27
	v_lshl_add_u64 v[10:11], s[26:27], 0, v[10:11]
	global_load_dwordx4 v[26:29], v[10:11], off
	global_load_dwordx4 v[22:25], v[10:11], off offset:16
	global_load_dwordx4 v[18:21], v[10:11], off offset:512
	s_nop 0
	global_load_dwordx4 v[10:13], v[10:11], off offset:528
	s_ashr_i32 s28, s28, 8
	v_bitop3_b32 v90, s29, 56, v186 bitop3:0xc8
	s_ashr_i32 s26, s29, 6
	s_ashr_i32 s29, s28, 31
	s_ashr_i32 s27, s26, 31
	s_lshl_b64 s[34:35], s[28:29], 7
	s_add_u32 s28, s34, s26
	s_addc_u32 s29, s35, s27
	s_lshl_b64 s[28:29], s[28:29], 15
	s_add_u32 s30, s12, s28
	s_addc_u32 s31, s13, s29
	s_or_b32 s28, s26, 2
	s_ashr_i32 s29, s28, 31
	s_add_u32 s34, s34, s28
	v_lshlrev_b32_e32 v169, 7, v168
	s_addc_u32 s35, s35, s29
	v_and_b32_e32 v138, 0x6780, v169
	s_lshl_b64 s[34:35], s[34:35], 15
	v_mov_b32_e32 v91, v139
	v_lshlrev_b32_e32 v90, 1, v90
	v_lshl_add_u64 v[192:193], s[30:31], 0, v[138:139]
	s_add_u32 s34, s12, s34
	v_lshl_add_u64 v[192:193], v[192:193], 0, v[90:91]
	s_addc_u32 s35, s13, s35
	s_and_b64 vcc, exec, s[0:1]
	s_mov_b64 s[0:1], -1
	s_waitcnt vmcnt(0)
	v_pk_mul_f32 v[194:195], v[6:7], v[190:191] op_sel_hi:[1,0]
	v_pk_mul_f32 v[196:197], v[8:9], v[190:191] op_sel_hi:[1,0]
	v_pk_mul_f32 v[198:199], v[2:3], v[190:191] op_sel_hi:[1,0]
	v_pk_mul_f32 v[204:205], v[32:33], v[190:191] op_sel_hi:[1,0]
	v_pk_fma_f32 v[170:171], v[196:197], v[170:171], v[28:29]
	v_pk_fma_f32 v[172:173], v[194:195], v[172:173], v[26:27]
	v_pk_mul_f32 v[200:201], v[4:5], v[190:191] op_sel_hi:[1,0]
	v_pk_mul_f32 v[202:203], v[30:31], v[190:191] op_sel_hi:[1,0]
	v_pk_mul_f32 v[206:207], v[14:15], v[190:191] op_sel_hi:[1,0]
	v_pk_mul_f32 v[190:191], v[16:17], v[190:191] op_sel_hi:[1,0]
	v_pk_fma_f32 v[174:175], v[198:199], v[174:175], v[22:23]
	v_pk_fma_f32 v[182:183], v[204:205], v[182:183], v[20:21]
	v_max_f32_e32 v173, 0, v173
	v_max_f32_e32 v172, 0, v172
	v_max_f32_e32 v171, 0, v171
	v_max_f32_e32 v170, 0, v170
	v_pk_fma_f32 v[176:177], v[200:201], v[176:177], v[24:25]
	v_pk_fma_f32 v[180:181], v[202:203], v[180:181], v[18:19]
	v_pk_fma_f32 v[184:185], v[190:191], v[184:185], v[12:13]
	v_max_f32_e32 v175, 0, v175
	v_max_f32_e32 v174, 0, v174
	v_max_f32_e32 v183, 0, v183
	v_max_f32_e32 v182, 0, v182
	v_pk_mul_f32 v[190:191], v[170:171], v[170:171]
	v_pk_mul_f32 v[170:171], v[172:173], v[172:173]
	v_max_f32_e32 v177, 0, v177
	v_max_f32_e32 v176, 0, v176
	v_max_f32_e32 v181, 0, v181
	v_max_f32_e32 v180, 0, v180
	v_pk_mul_f32 v[172:173], v[174:175], v[174:175]
	v_pk_mul_f32 v[174:175], v[182:183], v[182:183]
	v_cvt_pk_bf16_f32 v170, v170, v171
	v_cvt_pk_bf16_f32 v171, v190, v191
	v_pk_fma_f32 v[178:179], v[206:207], v[178:179], v[10:11]
	v_pk_mul_f32 v[176:177], v[176:177], v[176:177]
	v_pk_mul_f32 v[180:181], v[180:181], v[180:181]
	v_cvt_pk_bf16_f32 v172, v172, v173
	v_cvt_pk_bf16_f32 v173, v176, v177
	global_store_dwordx4 v[192:193], v[170:173], off nt
	v_max_f32_e32 v179, 0, v179
	v_max_f32_e32 v178, 0, v178
	v_cvt_pk_bf16_f32 v170, v180, v181
	v_cvt_pk_bf16_f32 v171, v174, v175
	v_lshl_add_u64 v[174:175], s[34:35], 0, v[138:139]
	v_max_f32_e32 v185, 0, v185
	v_max_f32_e32 v184, 0, v184
	v_lshl_add_u64 v[174:175], v[174:175], 0, v[90:91]
	v_pk_mul_f32 v[182:183], v[184:185], v[184:185]
	v_pk_mul_f32 v[178:179], v[178:179], v[178:179]
	s_nop 0
	v_cvt_pk_bf16_f32 v172, v178, v179
	v_cvt_pk_bf16_f32 v173, v182, v183
	global_store_dwordx4 v[174:175], v[170:173], off nt
	v_or_b32_e32 v174, 32, v168
	v_ashrrev_i32_e32 v175, 31, v174
	v_or_b32_e32 v170, 16, v168
	v_ashrrev_i32_e32 v171, 31, v170
	v_lshl_add_u64 v[172:173], v[170:171], 2, s[14:15]
	global_load_dword v172, v[172:173], off
	v_lshlrev_b32_e32 v138, 7, v170
	v_and_b32_e32 v138, 0x6f80, v138
	v_lshl_add_u64 v[176:177], s[30:31], 0, v[138:139]
	v_lshl_add_u64 v[178:179], s[34:35], 0, v[138:139]
	v_lshl_add_u64 v[176:177], v[176:177], 0, v[90:91]
	v_lshl_add_u64 v[178:179], v[178:179], 0, v[90:91]
	v_lshl_add_u64 v[170:171], v[174:175], 2, s[14:15]
	v_lshlrev_b32_e32 v138, 7, v174
	v_and_b32_e32 v138, 0x7780, v138
	s_waitcnt vmcnt(0)
	v_pk_mul_f32 v[180:181], v[6:7], v[172:173] op_sel_hi:[1,0]
	v_pk_mul_f32 v[182:183], v[8:9], v[172:173] op_sel_hi:[1,0]
	v_pk_mul_f32 v[184:185], v[2:3], v[172:173] op_sel_hi:[1,0]
	v_pk_mul_f32 v[190:191], v[4:5], v[172:173] op_sel_hi:[1,0]
	v_pk_fma_f32 v[154:155], v[182:183], v[154:155], v[28:29]
	v_pk_fma_f32 v[152:153], v[180:181], v[152:153], v[26:27]
	v_pk_mul_f32 v[192:193], v[30:31], v[172:173] op_sel_hi:[1,0]
	v_pk_mul_f32 v[194:195], v[32:33], v[172:173] op_sel_hi:[1,0]
	v_pk_mul_f32 v[196:197], v[14:15], v[172:173] op_sel_hi:[1,0]
	v_pk_mul_f32 v[172:173], v[16:17], v[172:173] op_sel_hi:[1,0]
	v_pk_fma_f32 v[158:159], v[190:191], v[158:159], v[24:25]
	v_pk_fma_f32 v[156:157], v[184:185], v[156:157], v[22:23]
	v_max_f32_e32 v153, 0, v153
	v_max_f32_e32 v152, 0, v152
	v_max_f32_e32 v155, 0, v155
	v_max_f32_e32 v154, 0, v154
	v_pk_fma_f32 v[162:163], v[194:195], v[162:163], v[20:21]
	v_pk_fma_f32 v[160:161], v[192:193], v[160:161], v[18:19]
	v_pk_fma_f32 v[166:167], v[172:173], v[166:167], v[12:13]
	v_pk_fma_f32 v[164:165], v[196:197], v[164:165], v[10:11]
	v_max_f32_e32 v157, 0, v157
	v_max_f32_e32 v156, 0, v156
	v_max_f32_e32 v159, 0, v159
	v_max_f32_e32 v158, 0, v158
	v_pk_mul_f32 v[154:155], v[154:155], v[154:155]
	v_pk_mul_f32 v[152:153], v[152:153], v[152:153]
	v_max_f32_e32 v161, 0, v161
	v_max_f32_e32 v160, 0, v160
	v_max_f32_e32 v163, 0, v163
	v_max_f32_e32 v162, 0, v162
	v_max_f32_e32 v165, 0, v165
	v_max_f32_e32 v164, 0, v164
	v_max_f32_e32 v167, 0, v167
	v_max_f32_e32 v166, 0, v166
	v_pk_mul_f32 v[158:159], v[158:159], v[158:159]
	v_pk_mul_f32 v[156:157], v[156:157], v[156:157]
	v_cvt_pk_bf16_f32 v152, v152, v153
	v_cvt_pk_bf16_f32 v153, v154, v155
	v_pk_mul_f32 v[162:163], v[162:163], v[162:163]
	v_cvt_pk_bf16_f32 v154, v156, v157
	v_cvt_pk_bf16_f32 v155, v158, v159
	v_pk_mul_f32 v[160:161], v[160:161], v[160:161]
	v_pk_mul_f32 v[166:167], v[166:167], v[166:167]
	v_pk_mul_f32 v[164:165], v[164:165], v[164:165]
	global_store_dwordx4 v[176:177], v[152:155], off nt
	v_lshl_add_u64 v[158:159], s[30:31], 0, v[138:139]
	v_lshl_add_u64 v[158:159], v[158:159], 0, v[90:91]
	v_cvt_pk_bf16_f32 v152, v160, v161
	v_cvt_pk_bf16_f32 v153, v162, v163
	v_cvt_pk_bf16_f32 v154, v164, v165
	v_cvt_pk_bf16_f32 v155, v166, v167
	global_store_dwordx4 v[178:179], v[152:155], off nt
	global_load_dword v152, v[170:171], off
	v_lshl_add_u64 v[160:161], s[34:35], 0, v[138:139]
	v_or_b32_e32 v154, 48, v168
	v_ashrrev_i32_e32 v155, 31, v154
	v_lshl_add_u64 v[160:161], v[160:161], 0, v[90:91]
	v_lshl_add_u64 v[156:157], v[154:155], 2, s[14:15]
	s_waitcnt vmcnt(0)
	v_pk_mul_f32 v[162:163], v[6:7], v[152:153] op_sel_hi:[1,0]
	v_pk_mul_f32 v[164:165], v[8:9], v[152:153] op_sel_hi:[1,0]
	v_pk_mul_f32 v[166:167], v[2:3], v[152:153] op_sel_hi:[1,0]
	v_pk_mul_f32 v[170:171], v[4:5], v[152:153] op_sel_hi:[1,0]
	v_pk_fma_f32 v[120:121], v[164:165], v[120:121], v[28:29]
	v_pk_fma_f32 v[118:119], v[162:163], v[118:119], v[26:27]
	v_pk_mul_f32 v[172:173], v[30:31], v[152:153] op_sel_hi:[1,0]
	v_pk_mul_f32 v[174:175], v[32:33], v[152:153] op_sel_hi:[1,0]
	v_pk_mul_f32 v[176:177], v[14:15], v[152:153] op_sel_hi:[1,0]
	v_pk_mul_f32 v[152:153], v[16:17], v[152:153] op_sel_hi:[1,0]
	v_pk_fma_f32 v[124:125], v[170:171], v[124:125], v[24:25]
	v_pk_fma_f32 v[122:123], v[166:167], v[122:123], v[22:23]
	v_max_f32_e32 v119, 0, v119
	v_max_f32_e32 v118, 0, v118
	v_max_f32_e32 v121, 0, v121
	v_max_f32_e32 v120, 0, v120
	v_pk_fma_f32 v[128:129], v[174:175], v[128:129], v[20:21]
	v_pk_fma_f32 v[126:127], v[172:173], v[126:127], v[18:19]
	v_pk_fma_f32 v[150:151], v[152:153], v[150:151], v[12:13]
	v_pk_fma_f32 v[148:149], v[176:177], v[148:149], v[10:11]
	v_max_f32_e32 v123, 0, v123
	v_max_f32_e32 v122, 0, v122
	v_max_f32_e32 v125, 0, v125
	v_max_f32_e32 v124, 0, v124
	v_pk_mul_f32 v[120:121], v[120:121], v[120:121]
	v_pk_mul_f32 v[118:119], v[118:119], v[118:119]
	v_max_f32_e32 v127, 0, v127
	v_max_f32_e32 v126, 0, v126
	v_max_f32_e32 v129, 0, v129
	v_max_f32_e32 v128, 0, v128
	v_max_f32_e32 v149, 0, v149
	v_max_f32_e32 v148, 0, v148
	v_max_f32_e32 v151, 0, v151
	v_max_f32_e32 v150, 0, v150
	v_pk_mul_f32 v[124:125], v[124:125], v[124:125]
	v_pk_mul_f32 v[122:123], v[122:123], v[122:123]
	v_cvt_pk_bf16_f32 v118, v118, v119
	v_cvt_pk_bf16_f32 v119, v120, v121
	v_pk_mul_f32 v[128:129], v[128:129], v[128:129]
	v_cvt_pk_bf16_f32 v120, v122, v123
	v_cvt_pk_bf16_f32 v121, v124, v125
	v_pk_mul_f32 v[126:127], v[126:127], v[126:127]
	v_pk_mul_f32 v[150:151], v[150:151], v[150:151]
	v_pk_mul_f32 v[148:149], v[148:149], v[148:149]
	global_store_dwordx4 v[158:159], v[118:121], off nt
	s_nop 1
	v_cvt_pk_bf16_f32 v118, v126, v127
	v_cvt_pk_bf16_f32 v119, v128, v129
	v_cvt_pk_bf16_f32 v120, v148, v149
	v_cvt_pk_bf16_f32 v121, v150, v151
	global_store_dwordx4 v[160:161], v[118:121], off nt
	global_load_dword v118, v[156:157], off
	s_nop 0
	v_lshlrev_b32_e32 v119, 7, v154
	v_and_b32_e32 v138, 0x7f80, v119
	v_lshl_add_u64 v[120:121], s[30:31], 0, v[138:139]
	v_lshl_add_u64 v[122:123], s[34:35], 0, v[138:139]
	v_lshl_add_u64 v[120:121], v[120:121], 0, v[90:91]
	v_lshl_add_u64 v[122:123], v[122:123], 0, v[90:91]
	s_waitcnt vmcnt(0)
	v_pk_mul_f32 v[124:125], v[6:7], v[118:119] op_sel_hi:[1,0]
	v_pk_mul_f32 v[126:127], v[8:9], v[118:119] op_sel_hi:[1,0]
	v_pk_mul_f32 v[128:129], v[2:3], v[118:119] op_sel_hi:[1,0]
	v_pk_mul_f32 v[148:149], v[4:5], v[118:119] op_sel_hi:[1,0]
	v_pk_fma_f32 v[104:105], v[126:127], v[104:105], v[28:29]
	v_pk_fma_f32 v[102:103], v[124:125], v[102:103], v[26:27]
	v_pk_mul_f32 v[150:151], v[30:31], v[118:119] op_sel_hi:[1,0]
	v_pk_mul_f32 v[152:153], v[32:33], v[118:119] op_sel_hi:[1,0]
	v_pk_mul_f32 v[154:155], v[14:15], v[118:119] op_sel_hi:[1,0]
	v_pk_mul_f32 v[118:119], v[16:17], v[118:119] op_sel_hi:[1,0]
	v_pk_fma_f32 v[108:109], v[148:149], v[108:109], v[24:25]
	v_pk_fma_f32 v[106:107], v[128:129], v[106:107], v[22:23]
	v_max_f32_e32 v103, 0, v103
	v_max_f32_e32 v102, 0, v102
	v_max_f32_e32 v105, 0, v105
	v_max_f32_e32 v104, 0, v104
	v_pk_fma_f32 v[112:113], v[152:153], v[112:113], v[20:21]
	v_pk_fma_f32 v[110:111], v[150:151], v[110:111], v[18:19]
	v_pk_fma_f32 v[116:117], v[118:119], v[116:117], v[12:13]
	v_pk_fma_f32 v[114:115], v[154:155], v[114:115], v[10:11]
	v_max_f32_e32 v107, 0, v107
	v_max_f32_e32 v106, 0, v106
	v_max_f32_e32 v109, 0, v109
	v_max_f32_e32 v108, 0, v108
	v_pk_mul_f32 v[104:105], v[104:105], v[104:105]
	v_pk_mul_f32 v[102:103], v[102:103], v[102:103]
	v_max_f32_e32 v111, 0, v111
	v_max_f32_e32 v110, 0, v110
	v_max_f32_e32 v113, 0, v113
	v_max_f32_e32 v112, 0, v112
	v_max_f32_e32 v115, 0, v115
	v_max_f32_e32 v114, 0, v114
	v_max_f32_e32 v117, 0, v117
	v_max_f32_e32 v116, 0, v116
	v_pk_mul_f32 v[108:109], v[108:109], v[108:109]
	v_pk_mul_f32 v[106:107], v[106:107], v[106:107]
	v_cvt_pk_bf16_f32 v102, v102, v103
	v_cvt_pk_bf16_f32 v103, v104, v105
	v_pk_mul_f32 v[112:113], v[112:113], v[112:113]
	v_cvt_pk_bf16_f32 v104, v106, v107
	v_cvt_pk_bf16_f32 v105, v108, v109
	v_pk_mul_f32 v[110:111], v[110:111], v[110:111]
	v_pk_mul_f32 v[116:117], v[116:117], v[116:117]
	v_pk_mul_f32 v[114:115], v[114:115], v[114:115]
	global_store_dwordx4 v[120:121], v[102:105], off nt
	s_nop 1
	v_cvt_pk_bf16_f32 v102, v110, v111
	v_cvt_pk_bf16_f32 v103, v112, v113
	v_cvt_pk_bf16_f32 v104, v114, v115
	v_cvt_pk_bf16_f32 v105, v116, v117
	global_store_dwordx4 v[122:123], v[102:105], off nt
	global_load_dword v106, v[100:101], off offset:512
	s_nop 0
	v_add_u32_e32 v103, 0x80, v168
	v_ashrrev_i32_e32 v102, 8, v103
	v_lshlrev_b32_e32 v107, 7, v103
	v_ashrrev_i32_e32 v103, 31, v102
	v_lshlrev_b64 v[104:105], 7, v[102:103]
	v_lshl_add_u64 v[102:103], v[104:105], 0, s[26:27]
	v_lshl_add_u64 v[104:105], v[104:105], 0, s[28:29]
	v_lshlrev_b64 v[102:103], 15, v[102:103]
	v_lshlrev_b64 v[104:105], 15, v[104:105]
	v_lshl_add_u64 v[102:103], s[12:13], 0, v[102:103]
	v_lshl_add_u64 v[104:105], s[12:13], 0, v[104:105]
	v_and_b32_e32 v138, 0x6780, v107
	v_lshl_add_u64 v[108:109], v[102:103], 0, v[138:139]
	v_lshl_add_u64 v[110:111], v[104:105], 0, v[138:139]
	v_lshl_add_u64 v[108:109], v[108:109], 0, v[90:91]
	v_lshl_add_u64 v[110:111], v[110:111], 0, v[90:91]
	s_waitcnt vmcnt(0)
	v_pk_mul_f32 v[112:113], v[6:7], v[106:107] op_sel_hi:[1,0]
	v_pk_mul_f32 v[114:115], v[8:9], v[106:107] op_sel_hi:[1,0]
	v_pk_mul_f32 v[116:117], v[2:3], v[106:107] op_sel_hi:[1,0]
	v_pk_mul_f32 v[118:119], v[4:5], v[106:107] op_sel_hi:[1,0]
	v_pk_fma_f32 v[84:85], v[114:115], v[84:85], v[28:29]
	v_pk_fma_f32 v[82:83], v[112:113], v[82:83], v[26:27]
	v_pk_mul_f32 v[120:121], v[30:31], v[106:107] op_sel_hi:[1,0]
	v_pk_mul_f32 v[122:123], v[32:33], v[106:107] op_sel_hi:[1,0]
	v_pk_mul_f32 v[124:125], v[14:15], v[106:107] op_sel_hi:[1,0]
	v_pk_mul_f32 v[106:107], v[16:17], v[106:107] op_sel_hi:[1,0]
	v_pk_fma_f32 v[88:89], v[118:119], v[88:89], v[24:25]
	v_pk_fma_f32 v[86:87], v[116:117], v[86:87], v[22:23]
	v_max_f32_e32 v83, 0, v83
	v_max_f32_e32 v82, 0, v82
	v_max_f32_e32 v85, 0, v85
	v_max_f32_e32 v84, 0, v84
	v_pk_fma_f32 v[94:95], v[122:123], v[94:95], v[20:21]
	v_pk_fma_f32 v[92:93], v[120:121], v[92:93], v[18:19]
	v_pk_fma_f32 v[98:99], v[106:107], v[98:99], v[12:13]
	v_pk_fma_f32 v[96:97], v[124:125], v[96:97], v[10:11]
	v_max_f32_e32 v87, 0, v87
	v_max_f32_e32 v86, 0, v86
	v_max_f32_e32 v89, 0, v89
	v_max_f32_e32 v88, 0, v88
	v_pk_mul_f32 v[84:85], v[84:85], v[84:85]
	v_pk_mul_f32 v[82:83], v[82:83], v[82:83]
	v_max_f32_e32 v93, 0, v93
	v_max_f32_e32 v92, 0, v92
	v_max_f32_e32 v95, 0, v95
	v_max_f32_e32 v94, 0, v94
	v_max_f32_e32 v97, 0, v97
	v_max_f32_e32 v96, 0, v96
	v_max_f32_e32 v99, 0, v99
	v_max_f32_e32 v98, 0, v98
	v_pk_mul_f32 v[88:89], v[88:89], v[88:89]
	v_pk_mul_f32 v[86:87], v[86:87], v[86:87]
	v_cvt_pk_bf16_f32 v82, v82, v83
	v_cvt_pk_bf16_f32 v83, v84, v85
	v_pk_mul_f32 v[94:95], v[94:95], v[94:95]
	v_cvt_pk_bf16_f32 v84, v86, v87
	v_cvt_pk_bf16_f32 v85, v88, v89
	v_pk_mul_f32 v[92:93], v[92:93], v[92:93]
	v_pk_mul_f32 v[98:99], v[98:99], v[98:99]
	v_pk_mul_f32 v[96:97], v[96:97], v[96:97]
	global_store_dwordx4 v[108:109], v[82:85], off nt
	s_nop 1
	v_cvt_pk_bf16_f32 v82, v92, v93
	v_cvt_pk_bf16_f32 v83, v94, v95
	v_cvt_pk_bf16_f32 v84, v96, v97
	v_cvt_pk_bf16_f32 v85, v98, v99
	global_store_dwordx4 v[110:111], v[82:85], off nt
	global_load_dword v82, v[100:101], off offset:576
	s_nop 0
	v_add_u32_e32 v83, 0x4800, v169
	v_and_b32_e32 v138, 0x6f80, v83
	v_lshl_add_u64 v[84:85], v[102:103], 0, v[138:139]
	v_lshl_add_u64 v[86:87], v[104:105], 0, v[138:139]
	v_lshl_add_u64 v[84:85], v[84:85], 0, v[90:91]
	v_lshl_add_u64 v[86:87], v[86:87], 0, v[90:91]
	s_waitcnt vmcnt(0)
	v_pk_mul_f32 v[88:89], v[6:7], v[82:83] op_sel_hi:[1,0]
	v_pk_mul_f32 v[92:93], v[8:9], v[82:83] op_sel_hi:[1,0]
	v_pk_mul_f32 v[94:95], v[2:3], v[82:83] op_sel_hi:[1,0]
	v_pk_mul_f32 v[96:97], v[4:5], v[82:83] op_sel_hi:[1,0]
	v_pk_fma_f32 v[68:69], v[92:93], v[68:69], v[28:29]
	v_pk_fma_f32 v[66:67], v[88:89], v[66:67], v[26:27]
	v_pk_mul_f32 v[98:99], v[30:31], v[82:83] op_sel_hi:[1,0]
	v_pk_mul_f32 v[106:107], v[32:33], v[82:83] op_sel_hi:[1,0]
	v_pk_mul_f32 v[108:109], v[14:15], v[82:83] op_sel_hi:[1,0]
	v_pk_mul_f32 v[82:83], v[16:17], v[82:83] op_sel_hi:[1,0]
	v_pk_fma_f32 v[72:73], v[96:97], v[72:73], v[24:25]
	v_pk_fma_f32 v[70:71], v[94:95], v[70:71], v[22:23]
	v_max_f32_e32 v67, 0, v67
	v_max_f32_e32 v66, 0, v66
	v_max_f32_e32 v69, 0, v69
	v_max_f32_e32 v68, 0, v68
	v_pk_fma_f32 v[76:77], v[106:107], v[76:77], v[20:21]
	v_pk_fma_f32 v[74:75], v[98:99], v[74:75], v[18:19]
	v_pk_fma_f32 v[80:81], v[82:83], v[80:81], v[12:13]
	v_pk_fma_f32 v[78:79], v[108:109], v[78:79], v[10:11]
	v_max_f32_e32 v71, 0, v71
	v_max_f32_e32 v70, 0, v70
	v_max_f32_e32 v73, 0, v73
	v_max_f32_e32 v72, 0, v72
	v_pk_mul_f32 v[68:69], v[68:69], v[68:69]
	v_pk_mul_f32 v[66:67], v[66:67], v[66:67]
	v_max_f32_e32 v75, 0, v75
	v_max_f32_e32 v74, 0, v74
	v_max_f32_e32 v77, 0, v77
	v_max_f32_e32 v76, 0, v76
	v_max_f32_e32 v79, 0, v79
	v_max_f32_e32 v78, 0, v78
	v_max_f32_e32 v81, 0, v81
	v_max_f32_e32 v80, 0, v80
	v_pk_mul_f32 v[72:73], v[72:73], v[72:73]
	v_pk_mul_f32 v[70:71], v[70:71], v[70:71]
	v_cvt_pk_bf16_f32 v66, v66, v67
	v_cvt_pk_bf16_f32 v67, v68, v69
	v_pk_mul_f32 v[76:77], v[76:77], v[76:77]
	v_cvt_pk_bf16_f32 v68, v70, v71
	v_cvt_pk_bf16_f32 v69, v72, v73
	v_pk_mul_f32 v[74:75], v[74:75], v[74:75]
	v_pk_mul_f32 v[80:81], v[80:81], v[80:81]
	v_pk_mul_f32 v[78:79], v[78:79], v[78:79]
	global_store_dwordx4 v[84:85], v[66:69], off nt
	s_nop 1
	v_cvt_pk_bf16_f32 v66, v74, v75
	v_cvt_pk_bf16_f32 v67, v76, v77
	v_cvt_pk_bf16_f32 v68, v78, v79
	v_cvt_pk_bf16_f32 v69, v80, v81
	global_store_dwordx4 v[86:87], v[66:69], off nt
	global_load_dword v66, v[100:101], off offset:640
	s_nop 0
	v_add_u32_e32 v67, 0x5000, v169
	v_and_b32_e32 v138, 0x7780, v67
	v_lshl_add_u64 v[68:69], v[102:103], 0, v[138:139]
	v_lshl_add_u64 v[70:71], v[104:105], 0, v[138:139]
	v_lshl_add_u64 v[68:69], v[68:69], 0, v[90:91]
	v_lshl_add_u64 v[70:71], v[70:71], 0, v[90:91]
	s_waitcnt vmcnt(0)
	v_pk_mul_f32 v[72:73], v[6:7], v[66:67] op_sel_hi:[1,0]
	v_pk_mul_f32 v[74:75], v[8:9], v[66:67] op_sel_hi:[1,0]
	v_pk_mul_f32 v[76:77], v[2:3], v[66:67] op_sel_hi:[1,0]
	v_pk_mul_f32 v[78:79], v[4:5], v[66:67] op_sel_hi:[1,0]
	v_pk_fma_f32 v[52:53], v[74:75], v[52:53], v[28:29]
	v_pk_fma_f32 v[50:51], v[72:73], v[50:51], v[26:27]
	v_pk_mul_f32 v[80:81], v[30:31], v[66:67] op_sel_hi:[1,0]
	v_pk_mul_f32 v[82:83], v[32:33], v[66:67] op_sel_hi:[1,0]
	v_pk_mul_f32 v[84:85], v[14:15], v[66:67] op_sel_hi:[1,0]
	v_pk_mul_f32 v[66:67], v[16:17], v[66:67] op_sel_hi:[1,0]
	v_pk_fma_f32 v[56:57], v[78:79], v[56:57], v[24:25]
	v_pk_fma_f32 v[54:55], v[76:77], v[54:55], v[22:23]
	v_max_f32_e32 v51, 0, v51
	v_max_f32_e32 v50, 0, v50
	v_max_f32_e32 v53, 0, v53
	v_max_f32_e32 v52, 0, v52
	v_pk_fma_f32 v[60:61], v[82:83], v[60:61], v[20:21]
	v_pk_fma_f32 v[58:59], v[80:81], v[58:59], v[18:19]
	v_pk_fma_f32 v[64:65], v[66:67], v[64:65], v[12:13]
	v_pk_fma_f32 v[62:63], v[84:85], v[62:63], v[10:11]
	v_max_f32_e32 v55, 0, v55
	v_max_f32_e32 v54, 0, v54
	v_max_f32_e32 v57, 0, v57
	v_max_f32_e32 v56, 0, v56
	v_pk_mul_f32 v[52:53], v[52:53], v[52:53]
	v_pk_mul_f32 v[50:51], v[50:51], v[50:51]
	v_max_f32_e32 v59, 0, v59
	v_max_f32_e32 v58, 0, v58
	v_max_f32_e32 v61, 0, v61
	v_max_f32_e32 v60, 0, v60
	v_max_f32_e32 v63, 0, v63
	v_max_f32_e32 v62, 0, v62
	v_max_f32_e32 v65, 0, v65
	v_max_f32_e32 v64, 0, v64
	v_pk_mul_f32 v[56:57], v[56:57], v[56:57]
	v_pk_mul_f32 v[54:55], v[54:55], v[54:55]
	v_cvt_pk_bf16_f32 v50, v50, v51
	v_cvt_pk_bf16_f32 v51, v52, v53
	v_pk_mul_f32 v[60:61], v[60:61], v[60:61]
	v_cvt_pk_bf16_f32 v52, v54, v55
	v_cvt_pk_bf16_f32 v53, v56, v57
	v_pk_mul_f32 v[58:59], v[58:59], v[58:59]
	v_pk_mul_f32 v[64:65], v[64:65], v[64:65]
	v_pk_mul_f32 v[62:63], v[62:63], v[62:63]
	global_store_dwordx4 v[68:69], v[50:53], off nt
	s_nop 1
	v_cvt_pk_bf16_f32 v50, v58, v59
	v_cvt_pk_bf16_f32 v51, v60, v61
	v_cvt_pk_bf16_f32 v52, v62, v63
	v_cvt_pk_bf16_f32 v53, v64, v65
	global_store_dwordx4 v[70:71], v[50:53], off nt
	global_load_dword v50, v[100:101], off offset:704
	s_nop 0
	v_add_u32_e32 v51, 0x5800, v169
	v_and_b32_e32 v138, 0x7f80, v51
	v_lshl_add_u64 v[52:53], v[102:103], 0, v[138:139]
	v_lshl_add_u64 v[54:55], v[104:105], 0, v[138:139]
	v_lshl_add_u64 v[52:53], v[52:53], 0, v[90:91]
	v_lshl_add_u64 v[54:55], v[54:55], 0, v[90:91]
	s_waitcnt vmcnt(0)
	v_pk_mul_f32 v[2:3], v[2:3], v[50:51] op_sel_hi:[1,0]
	v_pk_mul_f32 v[4:5], v[4:5], v[50:51] op_sel_hi:[1,0]
	v_pk_mul_f32 v[6:7], v[6:7], v[50:51] op_sel_hi:[1,0]
	v_pk_mul_f32 v[8:9], v[8:9], v[50:51] op_sel_hi:[1,0]
	v_pk_mul_f32 v[30:31], v[30:31], v[50:51] op_sel_hi:[1,0]
	v_pk_fma_f32 v[4:5], v[4:5], v[40:41], v[24:25]
	v_pk_fma_f32 v[2:3], v[2:3], v[38:39], v[22:23]
	v_pk_mul_f32 v[32:33], v[32:33], v[50:51] op_sel_hi:[1,0]
	v_pk_mul_f32 v[14:15], v[14:15], v[50:51] op_sel_hi:[1,0]
	v_pk_mul_f32 v[16:17], v[16:17], v[50:51] op_sel_hi:[1,0]
	v_pk_fma_f32 v[8:9], v[8:9], v[36:37], v[28:29]
	v_pk_fma_f32 v[6:7], v[6:7], v[34:35], v[26:27]
	v_pk_fma_f32 v[18:19], v[30:31], v[42:43], v[18:19]
	v_max_f32_e32 v3, 0, v3
	v_max_f32_e32 v2, 0, v2
	v_max_f32_e32 v5, 0, v5
	v_max_f32_e32 v4, 0, v4
	v_pk_fma_f32 v[20:21], v[32:33], v[44:45], v[20:21]
	v_pk_fma_f32 v[12:13], v[16:17], v[48:49], v[12:13]
	v_pk_fma_f32 v[10:11], v[14:15], v[46:47], v[10:11]
	v_max_f32_e32 v7, 0, v7
	v_max_f32_e32 v6, 0, v6
	v_max_f32_e32 v9, 0, v9
	v_max_f32_e32 v8, 0, v8
	v_max_f32_e32 v15, 0, v19
	v_max_f32_e32 v14, 0, v18
	v_pk_mul_f32 v[18:19], v[4:5], v[4:5]
	v_pk_mul_f32 v[4:5], v[2:3], v[2:3]
	v_max_f32_e32 v17, 0, v21
	v_max_f32_e32 v16, 0, v20
	v_max_f32_e32 v11, 0, v11
	v_max_f32_e32 v10, 0, v10
	v_max_f32_e32 v13, 0, v13
	v_max_f32_e32 v12, 0, v12
	v_pk_mul_f32 v[8:9], v[8:9], v[8:9]
	v_pk_mul_f32 v[6:7], v[6:7], v[6:7]
	v_pk_mul_f32 v[16:17], v[16:17], v[16:17]
	v_cvt_pk_bf16_f32 v2, v6, v7
	v_cvt_pk_bf16_f32 v3, v8, v9
	v_cvt_pk_bf16_f32 v4, v4, v5
	v_cvt_pk_bf16_f32 v5, v18, v19
	v_pk_mul_f32 v[14:15], v[14:15], v[14:15]
	v_pk_mul_f32 v[12:13], v[12:13], v[12:13]
	v_pk_mul_f32 v[10:11], v[10:11], v[10:11]
	global_store_dwordx4 v[52:53], v[2:5], off nt
	s_nop 1
	v_cvt_pk_bf16_f32 v2, v14, v15
	v_cvt_pk_bf16_f32 v3, v16, v17
	v_cvt_pk_bf16_f32 v4, v10, v11
	v_cvt_pk_bf16_f32 v5, v12, v13
	global_store_dwordx4 v[54:55], v[2:5], off nt
	s_cbranch_vccnz .LBB0_1926
	s_andn2_b64 vcc, exec, s[10:11]
	s_cbranch_vccnz .LBB0_1925
	s_barrier
	s_branch .LBB0_1925

.LBB0_2022:
	ds_read_b128 v[114:117], v209
	ds_read_b128 v[118:121], v209 offset:1024
	ds_read_b128 v[122:125], v209 offset:2048
	ds_read_b128 v[126:129], v209 offset:3072
	ds_read_b128 v[146:149], v210
	ds_read_b128 v[150:153], v210 offset:1024
	ds_read_b128 v[154:157], v210 offset:2048
	ds_read_b128 v[158:161], v210 offset:3072
	s_add_i32 s84, s36, 2
	s_add_u32 s37, s34, 0x4000
	s_addc_u32 s38, s35, 0
	s_cmp_eq_u32 s63, s36
	s_cselect_b32 s39, s5, s38
	s_cselect_b32 s38, s4, s37
	s_cselect_b32 s86, s30, s82
	s_cselect_b32 s87, s31, s83
	s_add_u32 s36, s38, 0x8000
	s_addc_u32 s37, s39, 0
	v_lshl_add_u64 v[218:219], s[34:35], 0, v[170:171]
	s_add_i32 m0, s47, 0xc000
	ds_read_b128 v[178:181], v211
	ds_read_b128 v[182:185], v211 offset:1024
	ds_read_b128 v[186:189], v211 offset:2048
	ds_read_b128 v[190:193], v211 offset:3072
	ds_read_b128 v[194:197], v211 offset:4096
	ds_read_b128 v[198:201], v211 offset:5120
	ds_read_b128 v[202:205], v211 offset:6144
	ds_read_b128 v[214:217], v211 offset:7168
	global_load_lds_dwordx4 v[218:219], off nt
	v_lshl_add_u64 v[218:219], s[34:35], 0, v[172:173]
	s_add_i32 m0, s47, 0xe000
	s_nop 0
	global_load_lds_dwordx4 v[218:219], off nt
	s_waitcnt vmcnt(8)
	s_waitcnt lgkmcnt(0)
	s_setprio 1
	s_waitcnt lgkmcnt(0)
	v_mfma_f32_16x16x32_bf16 v[142:145], v[114:117], v[178:181], v[142:145]
	v_mfma_f32_16x16x32_bf16 v[138:141], v[122:125], v[178:181], v[138:141]
	s_barrier
	v_mfma_f32_16x16x32_bf16 v[110:113], v[114:117], v[186:189], v[110:113]
	v_mfma_f32_16x16x32_bf16 v[106:109], v[122:125], v[186:189], v[106:109]
	v_mfma_f32_16x16x32_bf16 v[94:97], v[114:117], v[194:197], v[94:97]
	v_mfma_f32_16x16x32_bf16 v[90:93], v[122:125], v[194:197], v[90:93]
	v_mfma_f32_16x16x32_bf16 v[78:81], v[114:117], v[202:205], v[78:81]
	v_mfma_f32_16x16x32_bf16 v[74:77], v[122:125], v[202:205], v[74:77]
	v_mfma_f32_16x16x32_bf16 v[142:145], v[118:121], v[182:185], v[142:145]
	v_mfma_f32_16x16x32_bf16 v[138:141], v[126:129], v[182:185], v[138:141]
	v_mfma_f32_16x16x32_bf16 v[110:113], v[118:121], v[190:193], v[110:113]
	v_mfma_f32_16x16x32_bf16 v[106:109], v[126:129], v[190:193], v[106:109]
	v_mfma_f32_16x16x32_bf16 v[94:97], v[118:121], v[198:201], v[94:97]
	v_mfma_f32_16x16x32_bf16 v[90:93], v[126:129], v[198:201], v[90:93]
	v_mfma_f32_16x16x32_bf16 v[78:81], v[118:121], v[214:217], v[78:81]
	v_mfma_f32_16x16x32_bf16 v[74:77], v[126:129], v[214:217], v[74:77]
	s_setprio 0
	s_setprio 1
	v_mfma_f32_16x16x32_bf16 v[134:137], v[146:149], v[178:181], v[134:137]
	v_mfma_f32_16x16x32_bf16 v[130:133], v[154:157], v[178:181], v[130:133]
	v_mfma_f32_16x16x32_bf16 v[102:105], v[146:149], v[186:189], v[102:105]
	v_mfma_f32_16x16x32_bf16 v[98:101], v[154:157], v[186:189], v[98:101]
	v_mfma_f32_16x16x32_bf16 v[86:89], v[146:149], v[194:197], v[86:89]
	v_mfma_f32_16x16x32_bf16 v[82:85], v[154:157], v[194:197], v[82:85]
	v_mfma_f32_16x16x32_bf16 v[70:73], v[146:149], v[202:205], v[70:73]
	v_mfma_f32_16x16x32_bf16 v[66:69], v[154:157], v[202:205], v[66:69]
	v_mfma_f32_16x16x32_bf16 v[134:137], v[150:153], v[182:185], v[134:137]
	v_mfma_f32_16x16x32_bf16 v[130:133], v[158:161], v[182:185], v[130:133]
	v_mfma_f32_16x16x32_bf16 v[102:105], v[150:153], v[190:193], v[102:105]
	v_mfma_f32_16x16x32_bf16 v[98:101], v[158:161], v[190:193], v[98:101]
	v_mfma_f32_16x16x32_bf16 v[86:89], v[150:153], v[198:201], v[86:89]
	v_mfma_f32_16x16x32_bf16 v[82:85], v[158:161], v[198:201], v[82:85]
	v_mfma_f32_16x16x32_bf16 v[70:73], v[150:153], v[214:217], v[70:73]
	v_mfma_f32_16x16x32_bf16 v[66:69], v[158:161], v[214:217], v[66:69]
	s_setprio 0
	s_barrier
	s_add_i32 s85, s66, s46
	v_lshl_add_u64 v[218:219], s[86:87], 0, v[164:165]
	s_mov_b32 m0, s85
	ds_read_b128 v[178:181], v211 offset:16384
	ds_read_b128 v[182:185], v211 offset:17408
	ds_read_b128 v[186:189], v211 offset:18432
	ds_read_b128 v[190:193], v211 offset:19456
	ds_read_b128 v[194:197], v211 offset:20480
	ds_read_b128 v[198:201], v211 offset:21504
	ds_read_b128 v[202:205], v211 offset:22528
	ds_read_b128 v[214:217], v211 offset:23552
	global_load_lds_dwordx4 v[218:219], off
	s_add_i32 m0, s85, 0x2000
	v_lshl_add_u64 v[220:221], s[86:87], 0, v[168:169]
	s_add_u32 s86, s86, s8
	s_addc_u32 s87, s87, s9
	s_add_i32 s85, s67, s46
	global_load_lds_dwordx4 v[220:221], off
	v_lshl_add_u64 v[222:223], s[86:87], 0, v[164:165]
	s_mov_b32 m0, s85
	v_lshl_add_u64 v[224:225], s[86:87], 0, v[168:169]
	global_load_lds_dwordx4 v[222:223], off
	s_add_i32 m0, s85, 0x2000
	v_lshl_add_u64 v[226:227], s[38:39], 0, v[162:163]
	global_load_lds_dwordx4 v[224:225], off
	s_mov_b32 m0, s47
	s_nop 0
	global_load_lds_dwordx4 v[226:227], off nt
	v_lshl_add_u64 v[226:227], s[38:39], 0, v[166:167]
	s_mov_b32 m0, s50
	s_nop 0
	global_load_lds_dwordx4 v[226:227], off nt
	s_waitcnt vmcnt(8)
	s_waitcnt lgkmcnt(0)
	s_setprio 1
	s_waitcnt lgkmcnt(0)
	v_mfma_f32_16x16x32_bf16 v[62:65], v[114:117], v[178:181], v[62:65]
	v_mfma_f32_16x16x32_bf16 v[58:61], v[122:125], v[178:181], v[58:61]
	s_barrier
	v_mfma_f32_16x16x32_bf16 v[46:49], v[114:117], v[186:189], v[46:49]
	v_mfma_f32_16x16x32_bf16 v[42:45], v[122:125], v[186:189], v[42:45]
	v_mfma_f32_16x16x32_bf16 v[30:33], v[114:117], v[194:197], v[30:33]
	v_mfma_f32_16x16x32_bf16 v[26:29], v[122:125], v[194:197], v[26:29]
	v_mfma_f32_16x16x32_bf16 v[14:17], v[114:117], v[202:205], v[14:17]
	v_mfma_f32_16x16x32_bf16 v[10:13], v[122:125], v[202:205], v[10:13]
	v_mfma_f32_16x16x32_bf16 v[62:65], v[118:121], v[182:185], v[62:65]
	v_mfma_f32_16x16x32_bf16 v[58:61], v[126:129], v[182:185], v[58:61]
	v_mfma_f32_16x16x32_bf16 v[46:49], v[118:121], v[190:193], v[46:49]
	v_mfma_f32_16x16x32_bf16 v[42:45], v[126:129], v[190:193], v[42:45]
	v_mfma_f32_16x16x32_bf16 v[30:33], v[118:121], v[198:201], v[30:33]
	v_mfma_f32_16x16x32_bf16 v[26:29], v[126:129], v[198:201], v[26:29]
	v_mfma_f32_16x16x32_bf16 v[14:17], v[118:121], v[214:217], v[14:17]
	v_mfma_f32_16x16x32_bf16 v[10:13], v[126:129], v[214:217], v[10:13]
	s_setprio 0
	s_setprio 1
	v_mfma_f32_16x16x32_bf16 v[54:57], v[146:149], v[178:181], v[54:57]
	v_mfma_f32_16x16x32_bf16 v[50:53], v[154:157], v[178:181], v[50:53]
	v_mfma_f32_16x16x32_bf16 v[38:41], v[146:149], v[186:189], v[38:41]
	v_mfma_f32_16x16x32_bf16 v[34:37], v[154:157], v[186:189], v[34:37]
	v_mfma_f32_16x16x32_bf16 v[22:25], v[146:149], v[194:197], v[22:25]
	v_mfma_f32_16x16x32_bf16 v[18:21], v[154:157], v[194:197], v[18:21]
	v_mfma_f32_16x16x32_bf16 v[6:9], v[146:149], v[202:205], v[6:9]
	v_mfma_f32_16x16x32_bf16 v[2:5], v[154:157], v[202:205], v[2:5]
	v_mfma_f32_16x16x32_bf16 v[54:57], v[150:153], v[182:185], v[54:57]
	v_mfma_f32_16x16x32_bf16 v[50:53], v[158:161], v[182:185], v[50:53]
	v_mfma_f32_16x16x32_bf16 v[38:41], v[150:153], v[190:193], v[38:41]
	v_mfma_f32_16x16x32_bf16 v[34:37], v[158:161], v[190:193], v[34:37]
	v_mfma_f32_16x16x32_bf16 v[22:25], v[150:153], v[198:201], v[22:25]
	v_mfma_f32_16x16x32_bf16 v[18:21], v[158:161], v[198:201], v[18:21]
	v_mfma_f32_16x16x32_bf16 v[6:9], v[150:153], v[214:217], v[6:9]
	v_mfma_f32_16x16x32_bf16 v[2:5], v[158:161], v[214:217], v[2:5]
	s_setprio 0
	s_barrier
	s_add_i32 s85, 0, 0x18000
	s_add_i32 s86, 0, 0x1c000
	v_add_u32_e32 v126, s85, v207
	v_add_u32_e32 v158, s86, v207
	ds_read_b128 v[114:117], v126
	ds_read_b128 v[118:121], v126 offset:1024
	ds_read_b128 v[122:125], v126 offset:2048
	ds_read_b128 v[126:129], v126 offset:3072
	ds_read_b128 v[146:149], v158
	ds_read_b128 v[150:153], v158 offset:1024
	ds_read_b128 v[154:157], v158 offset:2048
	ds_read_b128 v[158:161], v158 offset:3072
	s_add_u32 s38, s38, 0x4000
	s_addc_u32 s39, s39, 0
	s_mov_b32 m0, s51
	v_lshl_add_u64 v[226:227], s[38:39], 0, v[162:163]
	ds_read_b128 v[178:181], v211 offset:32768
	ds_read_b128 v[182:185], v211 offset:33792
	ds_read_b128 v[186:189], v211 offset:34816
	ds_read_b128 v[190:193], v211 offset:35840
	ds_read_b128 v[194:197], v211 offset:36864
	ds_read_b128 v[198:201], v211 offset:37888
	ds_read_b128 v[202:205], v211 offset:38912
	ds_read_b128 v[214:217], v211 offset:39936
	global_load_lds_dwordx4 v[226:227], off nt
	v_lshl_add_u64 v[226:227], s[38:39], 0, v[166:167]
	s_mov_b32 m0, s54
	s_nop 0
	global_load_lds_dwordx4 v[226:227], off nt
	s_waitcnt vmcnt(8)
	s_waitcnt lgkmcnt(0)
	s_setprio 1
	s_waitcnt lgkmcnt(0)
	v_mfma_f32_16x16x32_bf16 v[142:145], v[114:117], v[178:181], v[142:145]
	v_mfma_f32_16x16x32_bf16 v[138:141], v[122:125], v[178:181], v[138:141]
	s_barrier
	v_mfma_f32_16x16x32_bf16 v[110:113], v[114:117], v[186:189], v[110:113]
	v_mfma_f32_16x16x32_bf16 v[106:109], v[122:125], v[186:189], v[106:109]
	v_mfma_f32_16x16x32_bf16 v[94:97], v[114:117], v[194:197], v[94:97]
	v_mfma_f32_16x16x32_bf16 v[90:93], v[122:125], v[194:197], v[90:93]
	v_mfma_f32_16x16x32_bf16 v[78:81], v[114:117], v[202:205], v[78:81]
	v_mfma_f32_16x16x32_bf16 v[74:77], v[122:125], v[202:205], v[74:77]
	v_mfma_f32_16x16x32_bf16 v[142:145], v[118:121], v[182:185], v[142:145]
	v_mfma_f32_16x16x32_bf16 v[138:141], v[126:129], v[182:185], v[138:141]
	v_mfma_f32_16x16x32_bf16 v[110:113], v[118:121], v[190:193], v[110:113]
	v_mfma_f32_16x16x32_bf16 v[106:109], v[126:129], v[190:193], v[106:109]
	v_mfma_f32_16x16x32_bf16 v[94:97], v[118:121], v[198:201], v[94:97]
	v_mfma_f32_16x16x32_bf16 v[90:93], v[126:129], v[198:201], v[90:93]
	v_mfma_f32_16x16x32_bf16 v[78:81], v[118:121], v[214:217], v[78:81]
	v_mfma_f32_16x16x32_bf16 v[74:77], v[126:129], v[214:217], v[74:77]
	s_setprio 0
	s_setprio 1
	v_mfma_f32_16x16x32_bf16 v[134:137], v[146:149], v[178:181], v[134:137]
	v_mfma_f32_16x16x32_bf16 v[130:133], v[154:157], v[178:181], v[130:133]
	v_mfma_f32_16x16x32_bf16 v[102:105], v[146:149], v[186:189], v[102:105]
	v_mfma_f32_16x16x32_bf16 v[98:101], v[154:157], v[186:189], v[98:101]
	v_mfma_f32_16x16x32_bf16 v[86:89], v[146:149], v[194:197], v[86:89]
	v_mfma_f32_16x16x32_bf16 v[82:85], v[154:157], v[194:197], v[82:85]
	v_mfma_f32_16x16x32_bf16 v[70:73], v[146:149], v[202:205], v[70:73]
	v_mfma_f32_16x16x32_bf16 v[66:69], v[154:157], v[202:205], v[66:69]
	v_mfma_f32_16x16x32_bf16 v[134:137], v[150:153], v[182:185], v[134:137]
	v_mfma_f32_16x16x32_bf16 v[130:133], v[158:161], v[182:185], v[130:133]
	v_mfma_f32_16x16x32_bf16 v[102:105], v[150:153], v[190:193], v[102:105]
	v_mfma_f32_16x16x32_bf16 v[98:101], v[158:161], v[190:193], v[98:101]
	v_mfma_f32_16x16x32_bf16 v[86:89], v[150:153], v[198:201], v[86:89]
	v_mfma_f32_16x16x32_bf16 v[82:85], v[158:161], v[198:201], v[82:85]
	v_mfma_f32_16x16x32_bf16 v[70:73], v[150:153], v[214:217], v[70:73]
	v_mfma_f32_16x16x32_bf16 v[66:69], v[158:161], v[214:217], v[66:69]
	s_setprio 0
	s_barrier
	s_add_i32 s38, s85, s46
	v_lshl_add_u64 v[218:219], v[218:219], 0, s[24:25]
	s_mov_b32 m0, s38
	ds_read_b128 v[178:181], v211 offset:49152
	ds_read_b128 v[182:185], v211 offset:50176
	ds_read_b128 v[186:189], v211 offset:51200
	ds_read_b128 v[190:193], v211 offset:52224
	ds_read_b128 v[194:197], v211 offset:53248
	ds_read_b128 v[198:201], v211 offset:54272
	ds_read_b128 v[202:205], v211 offset:55296
	ds_read_b128 v[214:217], v211 offset:56320
	global_load_lds_dwordx4 v[218:219], off
	v_lshl_add_u64 v[218:219], v[220:221], 0, s[24:25]
	s_add_i32 m0, s38, 0x2000
	s_add_i32 s38, s86, s46
	global_load_lds_dwordx4 v[218:219], off
	v_lshl_add_u64 v[218:219], v[222:223], 0, s[24:25]
	s_mov_b32 m0, s38
	s_nop 0
	global_load_lds_dwordx4 v[218:219], off
	v_lshl_add_u64 v[218:219], v[224:225], 0, s[24:25]
	s_add_i32 m0, s38, 0x2000
	s_nop 0
	global_load_lds_dwordx4 v[218:219], off
	v_lshl_add_u64 v[218:219], s[36:37], 0, v[162:163]
	s_mov_b32 m0, s61
	s_nop 0
	global_load_lds_dwordx4 v[218:219], off nt
	v_lshl_add_u64 v[218:219], s[36:37], 0, v[166:167]
	s_mov_b32 m0, s62
	s_nop 0
	global_load_lds_dwordx4 v[218:219], off nt
	s_waitcnt vmcnt(8)
	s_waitcnt lgkmcnt(0)
	s_setprio 1
	s_waitcnt lgkmcnt(0)
	v_mfma_f32_16x16x32_bf16 v[62:65], v[114:117], v[178:181], v[62:65]
	v_mfma_f32_16x16x32_bf16 v[58:61], v[122:125], v[178:181], v[58:61]
	s_barrier
	v_mfma_f32_16x16x32_bf16 v[46:49], v[114:117], v[186:189], v[46:49]
	v_mfma_f32_16x16x32_bf16 v[42:45], v[122:125], v[186:189], v[42:45]
	v_mfma_f32_16x16x32_bf16 v[30:33], v[114:117], v[194:197], v[30:33]
	v_mfma_f32_16x16x32_bf16 v[26:29], v[122:125], v[194:197], v[26:29]
	v_mfma_f32_16x16x32_bf16 v[14:17], v[114:117], v[202:205], v[14:17]
	v_mfma_f32_16x16x32_bf16 v[10:13], v[122:125], v[202:205], v[10:13]
	v_mfma_f32_16x16x32_bf16 v[62:65], v[118:121], v[182:185], v[62:65]
	v_mfma_f32_16x16x32_bf16 v[58:61], v[126:129], v[182:185], v[58:61]
	v_mfma_f32_16x16x32_bf16 v[46:49], v[118:121], v[190:193], v[46:49]
	v_mfma_f32_16x16x32_bf16 v[42:45], v[126:129], v[190:193], v[42:45]
	v_mfma_f32_16x16x32_bf16 v[30:33], v[118:121], v[198:201], v[30:33]
	v_mfma_f32_16x16x32_bf16 v[26:29], v[126:129], v[198:201], v[26:29]
	v_mfma_f32_16x16x32_bf16 v[14:17], v[118:121], v[214:217], v[14:17]
	v_mfma_f32_16x16x32_bf16 v[10:13], v[126:129], v[214:217], v[10:13]
	s_setprio 0
	s_setprio 1
	v_mfma_f32_16x16x32_bf16 v[54:57], v[146:149], v[178:181], v[54:57]
	v_mfma_f32_16x16x32_bf16 v[50:53], v[154:157], v[178:181], v[50:53]
	v_mfma_f32_16x16x32_bf16 v[38:41], v[146:149], v[186:189], v[38:41]
	v_mfma_f32_16x16x32_bf16 v[34:37], v[154:157], v[186:189], v[34:37]
	v_mfma_f32_16x16x32_bf16 v[22:25], v[146:149], v[194:197], v[22:25]
	v_mfma_f32_16x16x32_bf16 v[18:21], v[154:157], v[194:197], v[18:21]
	v_mfma_f32_16x16x32_bf16 v[6:9], v[146:149], v[202:205], v[6:9]
	v_mfma_f32_16x16x32_bf16 v[2:5], v[154:157], v[202:205], v[2:5]
	v_mfma_f32_16x16x32_bf16 v[54:57], v[150:153], v[182:185], v[54:57]
	v_mfma_f32_16x16x32_bf16 v[50:53], v[158:161], v[182:185], v[50:53]
	v_mfma_f32_16x16x32_bf16 v[38:41], v[150:153], v[190:193], v[38:41]
	v_mfma_f32_16x16x32_bf16 v[34:37], v[158:161], v[190:193], v[34:37]
	v_mfma_f32_16x16x32_bf16 v[22:25], v[150:153], v[198:201], v[22:25]
	v_mfma_f32_16x16x32_bf16 v[18:21], v[158:161], v[198:201], v[18:21]
	v_mfma_f32_16x16x32_bf16 v[6:9], v[150:153], v[214:217], v[6:9]
	v_mfma_f32_16x16x32_bf16 v[2:5], v[158:161], v[214:217], v[2:5]
	s_setprio 0
	s_barrier
	s_add_u32 s82, s82, 0x100
	s_addc_u32 s83, s83, 0
	s_add_u32 s34, s34, 0x10000
	s_addc_u32 s35, s35, 0
	s_cmp_ge_i32 s84, s60
	s_mov_b32 s36, s84
	s_cbranch_scc0 .LBB0_2022

.LBB0_2953:
	s_lshl_b32 s26, s30, 8
	s_add_i32 s28, s26, s56
	s_lshl_b32 s26, s31, 8
	s_or_b32 s29, s26, s57
	s_lshr_b32 s26, s30, 4
	s_add_i32 s26, s26, -1
	v_or_b32_e32 v2, s29, v186
	s_cmp_gt_i32 s30, 31
	s_cselect_b32 s26, s26, 0
	v_ashrrev_i32_e32 v3, 31, v2
	v_or_b32_e32 v168, s28, v187
	v_lshlrev_b64 v[10:11], 2, v[2:3]
	v_ashrrev_i32_e32 v169, 31, v168
	s_ashr_i32 s27, s26, 31
	v_lshl_add_u64 v[12:13], s[16:17], 0, v[10:11]
	v_lshl_add_u64 v[100:101], v[168:169], 2, s[14:15]
	s_lshl_b64 s[26:27], s[26:27], 15
	global_load_dwordx4 v[2:5], v[12:13], off offset:16
	global_load_dwordx4 v[6:9], v[12:13], off
	global_load_dword v190, v[100:101], off
	s_add_u32 s26, s47, s26
	global_load_dwordx4 v[14:17], v[12:13], off offset:528
	global_load_dwordx4 v[30:33], v[12:13], off offset:512
	s_addc_u32 s27, s50, s27
	v_lshl_add_u64 v[10:11], s[26:27], 0, v[10:11]
	global_load_dwordx4 v[26:29], v[10:11], off
	global_load_dwordx4 v[22:25], v[10:11], off offset:16
	global_load_dwordx4 v[18:21], v[10:11], off offset:512
	s_nop 0
	global_load_dwordx4 v[10:13], v[10:11], off offset:528
	s_ashr_i32 s28, s28, 8
	v_bitop3_b32 v90, s29, 56, v186 bitop3:0xc8
	s_ashr_i32 s26, s29, 6
	s_ashr_i32 s29, s28, 31
	s_ashr_i32 s27, s26, 31
	s_lshl_b64 s[34:35], s[28:29], 7
	s_add_u32 s28, s34, s26
	s_addc_u32 s29, s35, s27
	s_lshl_b64 s[28:29], s[28:29], 15
	s_add_u32 s30, s12, s28
	s_addc_u32 s31, s13, s29
	s_or_b32 s28, s26, 2
	s_ashr_i32 s29, s28, 31
	s_add_u32 s34, s34, s28
	v_lshlrev_b32_e32 v169, 7, v168
	s_addc_u32 s35, s35, s29
	v_and_b32_e32 v138, 0x6780, v169
	s_lshl_b64 s[34:35], s[34:35], 15
	v_mov_b32_e32 v91, v139
	v_lshlrev_b32_e32 v90, 1, v90
	v_lshl_add_u64 v[192:193], s[30:31], 0, v[138:139]
	s_add_u32 s34, s12, s34
	v_lshl_add_u64 v[192:193], v[192:193], 0, v[90:91]
	s_addc_u32 s35, s13, s35
	s_and_b64 vcc, exec, s[0:1]
	s_mov_b64 s[0:1], -1
	s_waitcnt vmcnt(0)
	v_pk_mul_f32 v[194:195], v[6:7], v[190:191] op_sel_hi:[1,0]
	v_pk_mul_f32 v[196:197], v[8:9], v[190:191] op_sel_hi:[1,0]
	v_pk_mul_f32 v[198:199], v[2:3], v[190:191] op_sel_hi:[1,0]
	v_pk_mul_f32 v[204:205], v[32:33], v[190:191] op_sel_hi:[1,0]
	v_pk_fma_f32 v[170:171], v[196:197], v[170:171], v[28:29]
	v_pk_fma_f32 v[172:173], v[194:195], v[172:173], v[26:27]
	v_pk_mul_f32 v[200:201], v[4:5], v[190:191] op_sel_hi:[1,0]
	v_pk_mul_f32 v[202:203], v[30:31], v[190:191] op_sel_hi:[1,0]
	v_pk_mul_f32 v[206:207], v[14:15], v[190:191] op_sel_hi:[1,0]
	v_pk_mul_f32 v[190:191], v[16:17], v[190:191] op_sel_hi:[1,0]
	v_pk_fma_f32 v[174:175], v[198:199], v[174:175], v[22:23]
	v_pk_fma_f32 v[182:183], v[204:205], v[182:183], v[20:21]
	v_max_f32_e32 v173, 0, v173
	v_max_f32_e32 v172, 0, v172
	v_max_f32_e32 v171, 0, v171
	v_max_f32_e32 v170, 0, v170
	v_pk_fma_f32 v[176:177], v[200:201], v[176:177], v[24:25]
	v_pk_fma_f32 v[180:181], v[202:203], v[180:181], v[18:19]
	v_pk_fma_f32 v[184:185], v[190:191], v[184:185], v[12:13]
	v_max_f32_e32 v175, 0, v175
	v_max_f32_e32 v174, 0, v174
	v_max_f32_e32 v183, 0, v183
	v_max_f32_e32 v182, 0, v182
	v_pk_mul_f32 v[190:191], v[170:171], v[170:171]
	v_pk_mul_f32 v[170:171], v[172:173], v[172:173]
	v_max_f32_e32 v177, 0, v177
	v_max_f32_e32 v176, 0, v176
	v_max_f32_e32 v181, 0, v181
	v_max_f32_e32 v180, 0, v180
	v_pk_mul_f32 v[172:173], v[174:175], v[174:175]
	v_pk_mul_f32 v[174:175], v[182:183], v[182:183]
	v_cvt_pk_bf16_f32 v170, v170, v171
	v_cvt_pk_bf16_f32 v171, v190, v191
	v_pk_fma_f32 v[178:179], v[206:207], v[178:179], v[10:11]
	v_pk_mul_f32 v[176:177], v[176:177], v[176:177]
	v_pk_mul_f32 v[180:181], v[180:181], v[180:181]
	v_cvt_pk_bf16_f32 v172, v172, v173
	v_cvt_pk_bf16_f32 v173, v176, v177
	global_store_dwordx4 v[192:193], v[170:173], off nt
	v_max_f32_e32 v179, 0, v179
	v_max_f32_e32 v178, 0, v178
	v_cvt_pk_bf16_f32 v170, v180, v181
	v_cvt_pk_bf16_f32 v171, v174, v175
	v_lshl_add_u64 v[174:175], s[34:35], 0, v[138:139]
	v_max_f32_e32 v185, 0, v185
	v_max_f32_e32 v184, 0, v184
	v_lshl_add_u64 v[174:175], v[174:175], 0, v[90:91]
	v_pk_mul_f32 v[182:183], v[184:185], v[184:185]
	v_pk_mul_f32 v[178:179], v[178:179], v[178:179]
	s_nop 0
	v_cvt_pk_bf16_f32 v172, v178, v179
	v_cvt_pk_bf16_f32 v173, v182, v183
	global_store_dwordx4 v[174:175], v[170:173], off nt
	v_or_b32_e32 v174, 32, v168
	v_ashrrev_i32_e32 v175, 31, v174
	v_or_b32_e32 v170, 16, v168
	v_ashrrev_i32_e32 v171, 31, v170
	v_lshl_add_u64 v[172:173], v[170:171], 2, s[14:15]
	global_load_dword v172, v[172:173], off
	v_lshlrev_b32_e32 v138, 7, v170
	v_and_b32_e32 v138, 0x6f80, v138
	v_lshl_add_u64 v[176:177], s[30:31], 0, v[138:139]
	v_lshl_add_u64 v[178:179], s[34:35], 0, v[138:139]
	v_lshl_add_u64 v[176:177], v[176:177], 0, v[90:91]
	v_lshl_add_u64 v[178:179], v[178:179], 0, v[90:91]
	v_lshl_add_u64 v[170:171], v[174:175], 2, s[14:15]
	v_lshlrev_b32_e32 v138, 7, v174
	v_and_b32_e32 v138, 0x7780, v138
	s_waitcnt vmcnt(0)
	v_pk_mul_f32 v[180:181], v[6:7], v[172:173] op_sel_hi:[1,0]
	v_pk_mul_f32 v[182:183], v[8:9], v[172:173] op_sel_hi:[1,0]
	v_pk_mul_f32 v[184:185], v[2:3], v[172:173] op_sel_hi:[1,0]
	v_pk_mul_f32 v[190:191], v[4:5], v[172:173] op_sel_hi:[1,0]
	v_pk_fma_f32 v[154:155], v[182:183], v[154:155], v[28:29]
	v_pk_fma_f32 v[152:153], v[180:181], v[152:153], v[26:27]
	v_pk_mul_f32 v[192:193], v[30:31], v[172:173] op_sel_hi:[1,0]
	v_pk_mul_f32 v[194:195], v[32:33], v[172:173] op_sel_hi:[1,0]
	v_pk_mul_f32 v[196:197], v[14:15], v[172:173] op_sel_hi:[1,0]
	v_pk_mul_f32 v[172:173], v[16:17], v[172:173] op_sel_hi:[1,0]
	v_pk_fma_f32 v[158:159], v[190:191], v[158:159], v[24:25]
	v_pk_fma_f32 v[156:157], v[184:185], v[156:157], v[22:23]
	v_max_f32_e32 v153, 0, v153
	v_max_f32_e32 v152, 0, v152
	v_max_f32_e32 v155, 0, v155
	v_max_f32_e32 v154, 0, v154
	v_pk_fma_f32 v[162:163], v[194:195], v[162:163], v[20:21]
	v_pk_fma_f32 v[160:161], v[192:193], v[160:161], v[18:19]
	v_pk_fma_f32 v[166:167], v[172:173], v[166:167], v[12:13]
	v_pk_fma_f32 v[164:165], v[196:197], v[164:165], v[10:11]
	v_max_f32_e32 v157, 0, v157
	v_max_f32_e32 v156, 0, v156
	v_max_f32_e32 v159, 0, v159
	v_max_f32_e32 v158, 0, v158
	v_pk_mul_f32 v[154:155], v[154:155], v[154:155]
	v_pk_mul_f32 v[152:153], v[152:153], v[152:153]
	v_max_f32_e32 v161, 0, v161
	v_max_f32_e32 v160, 0, v160
	v_max_f32_e32 v163, 0, v163
	v_max_f32_e32 v162, 0, v162
	v_max_f32_e32 v165, 0, v165
	v_max_f32_e32 v164, 0, v164
	v_max_f32_e32 v167, 0, v167
	v_max_f32_e32 v166, 0, v166
	v_pk_mul_f32 v[158:159], v[158:159], v[158:159]
	v_pk_mul_f32 v[156:157], v[156:157], v[156:157]
	v_cvt_pk_bf16_f32 v152, v152, v153
	v_cvt_pk_bf16_f32 v153, v154, v155
	v_pk_mul_f32 v[162:163], v[162:163], v[162:163]
	v_cvt_pk_bf16_f32 v154, v156, v157
	v_cvt_pk_bf16_f32 v155, v158, v159
	v_pk_mul_f32 v[160:161], v[160:161], v[160:161]
	v_pk_mul_f32 v[166:167], v[166:167], v[166:167]
	v_pk_mul_f32 v[164:165], v[164:165], v[164:165]
	global_store_dwordx4 v[176:177], v[152:155], off nt
	v_lshl_add_u64 v[158:159], s[30:31], 0, v[138:139]
	v_lshl_add_u64 v[158:159], v[158:159], 0, v[90:91]
	v_cvt_pk_bf16_f32 v152, v160, v161
	v_cvt_pk_bf16_f32 v153, v162, v163
	v_cvt_pk_bf16_f32 v154, v164, v165
	v_cvt_pk_bf16_f32 v155, v166, v167
	global_store_dwordx4 v[178:179], v[152:155], off nt
	global_load_dword v152, v[170:171], off
	v_lshl_add_u64 v[160:161], s[34:35], 0, v[138:139]
	v_or_b32_e32 v154, 48, v168
	v_ashrrev_i32_e32 v155, 31, v154
	v_lshl_add_u64 v[160:161], v[160:161], 0, v[90:91]
	v_lshl_add_u64 v[156:157], v[154:155], 2, s[14:15]
	s_waitcnt vmcnt(0)
	v_pk_mul_f32 v[162:163], v[6:7], v[152:153] op_sel_hi:[1,0]
	v_pk_mul_f32 v[164:165], v[8:9], v[152:153] op_sel_hi:[1,0]
	v_pk_mul_f32 v[166:167], v[2:3], v[152:153] op_sel_hi:[1,0]
	v_pk_mul_f32 v[170:171], v[4:5], v[152:153] op_sel_hi:[1,0]
	v_pk_fma_f32 v[120:121], v[164:165], v[120:121], v[28:29]
	v_pk_fma_f32 v[118:119], v[162:163], v[118:119], v[26:27]
	v_pk_mul_f32 v[172:173], v[30:31], v[152:153] op_sel_hi:[1,0]
	v_pk_mul_f32 v[174:175], v[32:33], v[152:153] op_sel_hi:[1,0]
	v_pk_mul_f32 v[176:177], v[14:15], v[152:153] op_sel_hi:[1,0]
	v_pk_mul_f32 v[152:153], v[16:17], v[152:153] op_sel_hi:[1,0]
	v_pk_fma_f32 v[124:125], v[170:171], v[124:125], v[24:25]
	v_pk_fma_f32 v[122:123], v[166:167], v[122:123], v[22:23]
	v_max_f32_e32 v119, 0, v119
	v_max_f32_e32 v118, 0, v118
	v_max_f32_e32 v121, 0, v121
	v_max_f32_e32 v120, 0, v120
	v_pk_fma_f32 v[128:129], v[174:175], v[128:129], v[20:21]
	v_pk_fma_f32 v[126:127], v[172:173], v[126:127], v[18:19]
	v_pk_fma_f32 v[150:151], v[152:153], v[150:151], v[12:13]
	v_pk_fma_f32 v[148:149], v[176:177], v[148:149], v[10:11]
	v_max_f32_e32 v123, 0, v123
	v_max_f32_e32 v122, 0, v122
	v_max_f32_e32 v125, 0, v125
	v_max_f32_e32 v124, 0, v124
	v_pk_mul_f32 v[120:121], v[120:121], v[120:121]
	v_pk_mul_f32 v[118:119], v[118:119], v[118:119]
	v_max_f32_e32 v127, 0, v127
	v_max_f32_e32 v126, 0, v126
	v_max_f32_e32 v129, 0, v129
	v_max_f32_e32 v128, 0, v128
	v_max_f32_e32 v149, 0, v149
	v_max_f32_e32 v148, 0, v148
	v_max_f32_e32 v151, 0, v151
	v_max_f32_e32 v150, 0, v150
	v_pk_mul_f32 v[124:125], v[124:125], v[124:125]
	v_pk_mul_f32 v[122:123], v[122:123], v[122:123]
	v_cvt_pk_bf16_f32 v118, v118, v119
	v_cvt_pk_bf16_f32 v119, v120, v121
	v_pk_mul_f32 v[128:129], v[128:129], v[128:129]
	v_cvt_pk_bf16_f32 v120, v122, v123
	v_cvt_pk_bf16_f32 v121, v124, v125
	v_pk_mul_f32 v[126:127], v[126:127], v[126:127]
	v_pk_mul_f32 v[150:151], v[150:151], v[150:151]
	v_pk_mul_f32 v[148:149], v[148:149], v[148:149]
	global_store_dwordx4 v[158:159], v[118:121], off nt
	s_nop 1
	v_cvt_pk_bf16_f32 v118, v126, v127
	v_cvt_pk_bf16_f32 v119, v128, v129
	v_cvt_pk_bf16_f32 v120, v148, v149
	v_cvt_pk_bf16_f32 v121, v150, v151
	global_store_dwordx4 v[160:161], v[118:121], off nt
	global_load_dword v118, v[156:157], off
	s_nop 0
	v_lshlrev_b32_e32 v119, 7, v154
	v_and_b32_e32 v138, 0x7f80, v119
	v_lshl_add_u64 v[120:121], s[30:31], 0, v[138:139]
	v_lshl_add_u64 v[122:123], s[34:35], 0, v[138:139]
	v_lshl_add_u64 v[120:121], v[120:121], 0, v[90:91]
	v_lshl_add_u64 v[122:123], v[122:123], 0, v[90:91]
	s_waitcnt vmcnt(0)
	v_pk_mul_f32 v[124:125], v[6:7], v[118:119] op_sel_hi:[1,0]
	v_pk_mul_f32 v[126:127], v[8:9], v[118:119] op_sel_hi:[1,0]
	v_pk_mul_f32 v[128:129], v[2:3], v[118:119] op_sel_hi:[1,0]
	v_pk_mul_f32 v[148:149], v[4:5], v[118:119] op_sel_hi:[1,0]
	v_pk_fma_f32 v[104:105], v[126:127], v[104:105], v[28:29]
	v_pk_fma_f32 v[102:103], v[124:125], v[102:103], v[26:27]
	v_pk_mul_f32 v[150:151], v[30:31], v[118:119] op_sel_hi:[1,0]
	v_pk_mul_f32 v[152:153], v[32:33], v[118:119] op_sel_hi:[1,0]
	v_pk_mul_f32 v[154:155], v[14:15], v[118:119] op_sel_hi:[1,0]
	v_pk_mul_f32 v[118:119], v[16:17], v[118:119] op_sel_hi:[1,0]
	v_pk_fma_f32 v[108:109], v[148:149], v[108:109], v[24:25]
	v_pk_fma_f32 v[106:107], v[128:129], v[106:107], v[22:23]
	v_max_f32_e32 v103, 0, v103
	v_max_f32_e32 v102, 0, v102
	v_max_f32_e32 v105, 0, v105
	v_max_f32_e32 v104, 0, v104
	v_pk_fma_f32 v[112:113], v[152:153], v[112:113], v[20:21]
	v_pk_fma_f32 v[110:111], v[150:151], v[110:111], v[18:19]
	v_pk_fma_f32 v[116:117], v[118:119], v[116:117], v[12:13]
	v_pk_fma_f32 v[114:115], v[154:155], v[114:115], v[10:11]
	v_max_f32_e32 v107, 0, v107
	v_max_f32_e32 v106, 0, v106
	v_max_f32_e32 v109, 0, v109
	v_max_f32_e32 v108, 0, v108
	v_pk_mul_f32 v[104:105], v[104:105], v[104:105]
	v_pk_mul_f32 v[102:103], v[102:103], v[102:103]
	v_max_f32_e32 v111, 0, v111
	v_max_f32_e32 v110, 0, v110
	v_max_f32_e32 v113, 0, v113
	v_max_f32_e32 v112, 0, v112
	v_max_f32_e32 v115, 0, v115
	v_max_f32_e32 v114, 0, v114
	v_max_f32_e32 v117, 0, v117
	v_max_f32_e32 v116, 0, v116
	v_pk_mul_f32 v[108:109], v[108:109], v[108:109]
	v_pk_mul_f32 v[106:107], v[106:107], v[106:107]
	v_cvt_pk_bf16_f32 v102, v102, v103
	v_cvt_pk_bf16_f32 v103, v104, v105
	v_pk_mul_f32 v[112:113], v[112:113], v[112:113]
	v_cvt_pk_bf16_f32 v104, v106, v107
	v_cvt_pk_bf16_f32 v105, v108, v109
	v_pk_mul_f32 v[110:111], v[110:111], v[110:111]
	v_pk_mul_f32 v[116:117], v[116:117], v[116:117]
	v_pk_mul_f32 v[114:115], v[114:115], v[114:115]
	global_store_dwordx4 v[120:121], v[102:105], off nt
	s_nop 1
	v_cvt_pk_bf16_f32 v102, v110, v111
	v_cvt_pk_bf16_f32 v103, v112, v113
	v_cvt_pk_bf16_f32 v104, v114, v115
	v_cvt_pk_bf16_f32 v105, v116, v117
	global_store_dwordx4 v[122:123], v[102:105], off nt
	global_load_dword v106, v[100:101], off offset:512
	s_nop 0
	v_add_u32_e32 v103, 0x80, v168
	v_ashrrev_i32_e32 v102, 8, v103
	v_lshlrev_b32_e32 v107, 7, v103
	v_ashrrev_i32_e32 v103, 31, v102
	v_lshlrev_b64 v[104:105], 7, v[102:103]
	v_lshl_add_u64 v[102:103], v[104:105], 0, s[26:27]
	v_lshl_add_u64 v[104:105], v[104:105], 0, s[28:29]
	v_lshlrev_b64 v[102:103], 15, v[102:103]
	v_lshlrev_b64 v[104:105], 15, v[104:105]
	v_lshl_add_u64 v[102:103], s[12:13], 0, v[102:103]
	v_lshl_add_u64 v[104:105], s[12:13], 0, v[104:105]
	v_and_b32_e32 v138, 0x6780, v107
	v_lshl_add_u64 v[108:109], v[102:103], 0, v[138:139]
	v_lshl_add_u64 v[110:111], v[104:105], 0, v[138:139]
	v_lshl_add_u64 v[108:109], v[108:109], 0, v[90:91]
	v_lshl_add_u64 v[110:111], v[110:111], 0, v[90:91]
	s_waitcnt vmcnt(0)
	v_pk_mul_f32 v[112:113], v[6:7], v[106:107] op_sel_hi:[1,0]
	v_pk_mul_f32 v[114:115], v[8:9], v[106:107] op_sel_hi:[1,0]
	v_pk_mul_f32 v[116:117], v[2:3], v[106:107] op_sel_hi:[1,0]
	v_pk_mul_f32 v[118:119], v[4:5], v[106:107] op_sel_hi:[1,0]
	v_pk_fma_f32 v[84:85], v[114:115], v[84:85], v[28:29]
	v_pk_fma_f32 v[82:83], v[112:113], v[82:83], v[26:27]
	v_pk_mul_f32 v[120:121], v[30:31], v[106:107] op_sel_hi:[1,0]
	v_pk_mul_f32 v[122:123], v[32:33], v[106:107] op_sel_hi:[1,0]
	v_pk_mul_f32 v[124:125], v[14:15], v[106:107] op_sel_hi:[1,0]
	v_pk_mul_f32 v[106:107], v[16:17], v[106:107] op_sel_hi:[1,0]
	v_pk_fma_f32 v[88:89], v[118:119], v[88:89], v[24:25]
	v_pk_fma_f32 v[86:87], v[116:117], v[86:87], v[22:23]
	v_max_f32_e32 v83, 0, v83
	v_max_f32_e32 v82, 0, v82
	v_max_f32_e32 v85, 0, v85
	v_max_f32_e32 v84, 0, v84
	v_pk_fma_f32 v[94:95], v[122:123], v[94:95], v[20:21]
	v_pk_fma_f32 v[92:93], v[120:121], v[92:93], v[18:19]
	v_pk_fma_f32 v[98:99], v[106:107], v[98:99], v[12:13]
	v_pk_fma_f32 v[96:97], v[124:125], v[96:97], v[10:11]
	v_max_f32_e32 v87, 0, v87
	v_max_f32_e32 v86, 0, v86
	v_max_f32_e32 v89, 0, v89
	v_max_f32_e32 v88, 0, v88
	v_pk_mul_f32 v[84:85], v[84:85], v[84:85]
	v_pk_mul_f32 v[82:83], v[82:83], v[82:83]
	v_max_f32_e32 v93, 0, v93
	v_max_f32_e32 v92, 0, v92
	v_max_f32_e32 v95, 0, v95
	v_max_f32_e32 v94, 0, v94
	v_max_f32_e32 v97, 0, v97
	v_max_f32_e32 v96, 0, v96
	v_max_f32_e32 v99, 0, v99
	v_max_f32_e32 v98, 0, v98
	v_pk_mul_f32 v[88:89], v[88:89], v[88:89]
	v_pk_mul_f32 v[86:87], v[86:87], v[86:87]
	v_cvt_pk_bf16_f32 v82, v82, v83
	v_cvt_pk_bf16_f32 v83, v84, v85
	v_pk_mul_f32 v[94:95], v[94:95], v[94:95]
	v_cvt_pk_bf16_f32 v84, v86, v87
	v_cvt_pk_bf16_f32 v85, v88, v89
	v_pk_mul_f32 v[92:93], v[92:93], v[92:93]
	v_pk_mul_f32 v[98:99], v[98:99], v[98:99]
	v_pk_mul_f32 v[96:97], v[96:97], v[96:97]
	global_store_dwordx4 v[108:109], v[82:85], off nt
	s_nop 1
	v_cvt_pk_bf16_f32 v82, v92, v93
	v_cvt_pk_bf16_f32 v83, v94, v95
	v_cvt_pk_bf16_f32 v84, v96, v97
	v_cvt_pk_bf16_f32 v85, v98, v99
	global_store_dwordx4 v[110:111], v[82:85], off nt
	global_load_dword v82, v[100:101], off offset:576
	s_nop 0
	v_add_u32_e32 v83, 0x4800, v169
	v_and_b32_e32 v138, 0x6f80, v83
	v_lshl_add_u64 v[84:85], v[102:103], 0, v[138:139]
	v_lshl_add_u64 v[86:87], v[104:105], 0, v[138:139]
	v_lshl_add_u64 v[84:85], v[84:85], 0, v[90:91]
	v_lshl_add_u64 v[86:87], v[86:87], 0, v[90:91]
	s_waitcnt vmcnt(0)
	v_pk_mul_f32 v[88:89], v[6:7], v[82:83] op_sel_hi:[1,0]
	v_pk_mul_f32 v[92:93], v[8:9], v[82:83] op_sel_hi:[1,0]
	v_pk_mul_f32 v[94:95], v[2:3], v[82:83] op_sel_hi:[1,0]
	v_pk_mul_f32 v[96:97], v[4:5], v[82:83] op_sel_hi:[1,0]
	v_pk_fma_f32 v[68:69], v[92:93], v[68:69], v[28:29]
	v_pk_fma_f32 v[66:67], v[88:89], v[66:67], v[26:27]
	v_pk_mul_f32 v[98:99], v[30:31], v[82:83] op_sel_hi:[1,0]
	v_pk_mul_f32 v[106:107], v[32:33], v[82:83] op_sel_hi:[1,0]
	v_pk_mul_f32 v[108:109], v[14:15], v[82:83] op_sel_hi:[1,0]
	v_pk_mul_f32 v[82:83], v[16:17], v[82:83] op_sel_hi:[1,0]
	v_pk_fma_f32 v[72:73], v[96:97], v[72:73], v[24:25]
	v_pk_fma_f32 v[70:71], v[94:95], v[70:71], v[22:23]
	v_max_f32_e32 v67, 0, v67
	v_max_f32_e32 v66, 0, v66
	v_max_f32_e32 v69, 0, v69
	v_max_f32_e32 v68, 0, v68
	v_pk_fma_f32 v[76:77], v[106:107], v[76:77], v[20:21]
	v_pk_fma_f32 v[74:75], v[98:99], v[74:75], v[18:19]
	v_pk_fma_f32 v[80:81], v[82:83], v[80:81], v[12:13]
	v_pk_fma_f32 v[78:79], v[108:109], v[78:79], v[10:11]
	v_max_f32_e32 v71, 0, v71
	v_max_f32_e32 v70, 0, v70
	v_max_f32_e32 v73, 0, v73
	v_max_f32_e32 v72, 0, v72
	v_pk_mul_f32 v[68:69], v[68:69], v[68:69]
	v_pk_mul_f32 v[66:67], v[66:67], v[66:67]
	v_max_f32_e32 v75, 0, v75
	v_max_f32_e32 v74, 0, v74
	v_max_f32_e32 v77, 0, v77
	v_max_f32_e32 v76, 0, v76
	v_max_f32_e32 v79, 0, v79
	v_max_f32_e32 v78, 0, v78
	v_max_f32_e32 v81, 0, v81
	v_max_f32_e32 v80, 0, v80
	v_pk_mul_f32 v[72:73], v[72:73], v[72:73]
	v_pk_mul_f32 v[70:71], v[70:71], v[70:71]
	v_cvt_pk_bf16_f32 v66, v66, v67
	v_cvt_pk_bf16_f32 v67, v68, v69
	v_pk_mul_f32 v[76:77], v[76:77], v[76:77]
	v_cvt_pk_bf16_f32 v68, v70, v71
	v_cvt_pk_bf16_f32 v69, v72, v73
	v_pk_mul_f32 v[74:75], v[74:75], v[74:75]
	v_pk_mul_f32 v[80:81], v[80:81], v[80:81]
	v_pk_mul_f32 v[78:79], v[78:79], v[78:79]
	global_store_dwordx4 v[84:85], v[66:69], off nt
	s_nop 1
	v_cvt_pk_bf16_f32 v66, v74, v75
	v_cvt_pk_bf16_f32 v67, v76, v77
	v_cvt_pk_bf16_f32 v68, v78, v79
	v_cvt_pk_bf16_f32 v69, v80, v81
	global_store_dwordx4 v[86:87], v[66:69], off nt
	global_load_dword v66, v[100:101], off offset:640
	s_nop 0
	v_add_u32_e32 v67, 0x5000, v169
	v_and_b32_e32 v138, 0x7780, v67
	v_lshl_add_u64 v[68:69], v[102:103], 0, v[138:139]
	v_lshl_add_u64 v[70:71], v[104:105], 0, v[138:139]
	v_lshl_add_u64 v[68:69], v[68:69], 0, v[90:91]
	v_lshl_add_u64 v[70:71], v[70:71], 0, v[90:91]
	s_waitcnt vmcnt(0)
	v_pk_mul_f32 v[72:73], v[6:7], v[66:67] op_sel_hi:[1,0]
	v_pk_mul_f32 v[74:75], v[8:9], v[66:67] op_sel_hi:[1,0]
	v_pk_mul_f32 v[76:77], v[2:3], v[66:67] op_sel_hi:[1,0]
	v_pk_mul_f32 v[78:79], v[4:5], v[66:67] op_sel_hi:[1,0]
	v_pk_fma_f32 v[52:53], v[74:75], v[52:53], v[28:29]
	v_pk_fma_f32 v[50:51], v[72:73], v[50:51], v[26:27]
	v_pk_mul_f32 v[80:81], v[30:31], v[66:67] op_sel_hi:[1,0]
	v_pk_mul_f32 v[82:83], v[32:33], v[66:67] op_sel_hi:[1,0]
	v_pk_mul_f32 v[84:85], v[14:15], v[66:67] op_sel_hi:[1,0]
	v_pk_mul_f32 v[66:67], v[16:17], v[66:67] op_sel_hi:[1,0]
	v_pk_fma_f32 v[56:57], v[78:79], v[56:57], v[24:25]
	v_pk_fma_f32 v[54:55], v[76:77], v[54:55], v[22:23]
	v_max_f32_e32 v51, 0, v51
	v_max_f32_e32 v50, 0, v50
	v_max_f32_e32 v53, 0, v53
	v_max_f32_e32 v52, 0, v52
	v_pk_fma_f32 v[60:61], v[82:83], v[60:61], v[20:21]
	v_pk_fma_f32 v[58:59], v[80:81], v[58:59], v[18:19]
	v_pk_fma_f32 v[64:65], v[66:67], v[64:65], v[12:13]
	v_pk_fma_f32 v[62:63], v[84:85], v[62:63], v[10:11]
	v_max_f32_e32 v55, 0, v55
	v_max_f32_e32 v54, 0, v54
	v_max_f32_e32 v57, 0, v57
	v_max_f32_e32 v56, 0, v56
	v_pk_mul_f32 v[52:53], v[52:53], v[52:53]
	v_pk_mul_f32 v[50:51], v[50:51], v[50:51]
	v_max_f32_e32 v59, 0, v59
	v_max_f32_e32 v58, 0, v58
	v_max_f32_e32 v61, 0, v61
	v_max_f32_e32 v60, 0, v60
	v_max_f32_e32 v63, 0, v63
	v_max_f32_e32 v62, 0, v62
	v_max_f32_e32 v65, 0, v65
	v_max_f32_e32 v64, 0, v64
	v_pk_mul_f32 v[56:57], v[56:57], v[56:57]
	v_pk_mul_f32 v[54:55], v[54:55], v[54:55]
	v_cvt_pk_bf16_f32 v50, v50, v51
	v_cvt_pk_bf16_f32 v51, v52, v53
	v_pk_mul_f32 v[60:61], v[60:61], v[60:61]
	v_cvt_pk_bf16_f32 v52, v54, v55
	v_cvt_pk_bf16_f32 v53, v56, v57
	v_pk_mul_f32 v[58:59], v[58:59], v[58:59]
	v_pk_mul_f32 v[64:65], v[64:65], v[64:65]
	v_pk_mul_f32 v[62:63], v[62:63], v[62:63]
	global_store_dwordx4 v[68:69], v[50:53], off nt
	s_nop 1
	v_cvt_pk_bf16_f32 v50, v58, v59
	v_cvt_pk_bf16_f32 v51, v60, v61
	v_cvt_pk_bf16_f32 v52, v62, v63
	v_cvt_pk_bf16_f32 v53, v64, v65
	global_store_dwordx4 v[70:71], v[50:53], off nt
	global_load_dword v50, v[100:101], off offset:704
	s_nop 0
	v_add_u32_e32 v51, 0x5800, v169
	v_and_b32_e32 v138, 0x7f80, v51
	v_lshl_add_u64 v[52:53], v[102:103], 0, v[138:139]
	v_lshl_add_u64 v[54:55], v[104:105], 0, v[138:139]
	v_lshl_add_u64 v[52:53], v[52:53], 0, v[90:91]
	v_lshl_add_u64 v[54:55], v[54:55], 0, v[90:91]
	s_waitcnt vmcnt(0)
	v_pk_mul_f32 v[2:3], v[2:3], v[50:51] op_sel_hi:[1,0]
	v_pk_mul_f32 v[4:5], v[4:5], v[50:51] op_sel_hi:[1,0]
	v_pk_mul_f32 v[6:7], v[6:7], v[50:51] op_sel_hi:[1,0]
	v_pk_mul_f32 v[8:9], v[8:9], v[50:51] op_sel_hi:[1,0]
	v_pk_mul_f32 v[30:31], v[30:31], v[50:51] op_sel_hi:[1,0]
	v_pk_fma_f32 v[4:5], v[4:5], v[40:41], v[24:25]
	v_pk_fma_f32 v[2:3], v[2:3], v[38:39], v[22:23]
	v_pk_mul_f32 v[32:33], v[32:33], v[50:51] op_sel_hi:[1,0]
	v_pk_mul_f32 v[14:15], v[14:15], v[50:51] op_sel_hi:[1,0]
	v_pk_mul_f32 v[16:17], v[16:17], v[50:51] op_sel_hi:[1,0]
	v_pk_fma_f32 v[8:9], v[8:9], v[36:37], v[28:29]
	v_pk_fma_f32 v[6:7], v[6:7], v[34:35], v[26:27]
	v_pk_fma_f32 v[18:19], v[30:31], v[42:43], v[18:19]
	v_max_f32_e32 v3, 0, v3
	v_max_f32_e32 v2, 0, v2
	v_max_f32_e32 v5, 0, v5
	v_max_f32_e32 v4, 0, v4
	v_pk_fma_f32 v[20:21], v[32:33], v[44:45], v[20:21]
	v_pk_fma_f32 v[12:13], v[16:17], v[48:49], v[12:13]
	v_pk_fma_f32 v[10:11], v[14:15], v[46:47], v[10:11]
	v_max_f32_e32 v7, 0, v7
	v_max_f32_e32 v6, 0, v6
	v_max_f32_e32 v9, 0, v9
	v_max_f32_e32 v8, 0, v8
	v_max_f32_e32 v15, 0, v19
	v_max_f32_e32 v14, 0, v18
	v_pk_mul_f32 v[18:19], v[4:5], v[4:5]
	v_pk_mul_f32 v[4:5], v[2:3], v[2:3]
	v_max_f32_e32 v17, 0, v21
	v_max_f32_e32 v16, 0, v20
	v_max_f32_e32 v11, 0, v11
	v_max_f32_e32 v10, 0, v10
	v_max_f32_e32 v13, 0, v13
	v_max_f32_e32 v12, 0, v12
	v_pk_mul_f32 v[8:9], v[8:9], v[8:9]
	v_pk_mul_f32 v[6:7], v[6:7], v[6:7]
	v_pk_mul_f32 v[16:17], v[16:17], v[16:17]
	v_cvt_pk_bf16_f32 v2, v6, v7
	v_cvt_pk_bf16_f32 v3, v8, v9
	v_cvt_pk_bf16_f32 v4, v4, v5
	v_cvt_pk_bf16_f32 v5, v18, v19
	v_pk_mul_f32 v[14:15], v[14:15], v[14:15]
	v_pk_mul_f32 v[12:13], v[12:13], v[12:13]
	v_pk_mul_f32 v[10:11], v[10:11], v[10:11]
	global_store_dwordx4 v[52:53], v[2:5], off nt
	s_nop 1
	v_cvt_pk_bf16_f32 v2, v14, v15
	v_cvt_pk_bf16_f32 v3, v16, v17
	v_cvt_pk_bf16_f32 v4, v10, v11
	v_cvt_pk_bf16_f32 v5, v12, v13
	global_store_dwordx4 v[54:55], v[2:5], off nt
	s_cbranch_vccnz .LBB0_2936
	s_andn2_b64 vcc, exec, s[10:11]
	s_cbranch_vccnz .LBB0_2935
	s_barrier
	s_branch .LBB0_2935

.LBB0_3032:
	ds_read_b128 v[114:117], v209
	ds_read_b128 v[118:121], v209 offset:1024
	ds_read_b128 v[122:125], v209 offset:2048
	ds_read_b128 v[126:129], v209 offset:3072
	ds_read_b128 v[146:149], v210
	ds_read_b128 v[150:153], v210 offset:1024
	ds_read_b128 v[154:157], v210 offset:2048
	ds_read_b128 v[158:161], v210 offset:3072
	s_add_i32 s80, s36, 2
	s_add_u32 s37, s34, 0x4000
	s_addc_u32 s38, s35, 0
	s_cmp_eq_u32 s61, s36
	s_cselect_b32 s39, s5, s38
	s_cselect_b32 s38, s4, s37
	s_cselect_b32 s82, s30, s70
	s_cselect_b32 s83, s31, s71
	s_add_u32 s36, s38, 0x8000
	s_addc_u32 s37, s39, 0
	v_lshl_add_u64 v[218:219], s[34:35], 0, v[170:171]
	s_add_i32 m0, s45, 0xc000
	ds_read_b128 v[178:181], v211
	ds_read_b128 v[182:185], v211 offset:1024
	ds_read_b128 v[186:189], v211 offset:2048
	ds_read_b128 v[190:193], v211 offset:3072
	ds_read_b128 v[194:197], v211 offset:4096
	ds_read_b128 v[198:201], v211 offset:5120
	ds_read_b128 v[202:205], v211 offset:6144
	ds_read_b128 v[214:217], v211 offset:7168
	global_load_lds_dwordx4 v[218:219], off nt
	v_lshl_add_u64 v[218:219], s[34:35], 0, v[172:173]
	s_add_i32 m0, s45, 0xe000
	s_nop 0
	global_load_lds_dwordx4 v[218:219], off nt
	s_waitcnt vmcnt(8)
	s_waitcnt lgkmcnt(0)
	s_setprio 1
	s_waitcnt lgkmcnt(0)
	v_mfma_f32_16x16x32_bf16 v[142:145], v[114:117], v[178:181], v[142:145]
	v_mfma_f32_16x16x32_bf16 v[138:141], v[122:125], v[178:181], v[138:141]
	s_barrier
	v_mfma_f32_16x16x32_bf16 v[110:113], v[114:117], v[186:189], v[110:113]
	v_mfma_f32_16x16x32_bf16 v[106:109], v[122:125], v[186:189], v[106:109]
	v_mfma_f32_16x16x32_bf16 v[94:97], v[114:117], v[194:197], v[94:97]
	v_mfma_f32_16x16x32_bf16 v[90:93], v[122:125], v[194:197], v[90:93]
	v_mfma_f32_16x16x32_bf16 v[78:81], v[114:117], v[202:205], v[78:81]
	v_mfma_f32_16x16x32_bf16 v[74:77], v[122:125], v[202:205], v[74:77]
	v_mfma_f32_16x16x32_bf16 v[142:145], v[118:121], v[182:185], v[142:145]
	v_mfma_f32_16x16x32_bf16 v[138:141], v[126:129], v[182:185], v[138:141]
	v_mfma_f32_16x16x32_bf16 v[110:113], v[118:121], v[190:193], v[110:113]
	v_mfma_f32_16x16x32_bf16 v[106:109], v[126:129], v[190:193], v[106:109]
	v_mfma_f32_16x16x32_bf16 v[94:97], v[118:121], v[198:201], v[94:97]
	v_mfma_f32_16x16x32_bf16 v[90:93], v[126:129], v[198:201], v[90:93]
	v_mfma_f32_16x16x32_bf16 v[78:81], v[118:121], v[214:217], v[78:81]
	v_mfma_f32_16x16x32_bf16 v[74:77], v[126:129], v[214:217], v[74:77]
	s_setprio 0
	s_setprio 1
	v_mfma_f32_16x16x32_bf16 v[134:137], v[146:149], v[178:181], v[134:137]
	v_mfma_f32_16x16x32_bf16 v[130:133], v[154:157], v[178:181], v[130:133]
	v_mfma_f32_16x16x32_bf16 v[102:105], v[146:149], v[186:189], v[102:105]
	v_mfma_f32_16x16x32_bf16 v[98:101], v[154:157], v[186:189], v[98:101]
	v_mfma_f32_16x16x32_bf16 v[86:89], v[146:149], v[194:197], v[86:89]
	v_mfma_f32_16x16x32_bf16 v[82:85], v[154:157], v[194:197], v[82:85]
	v_mfma_f32_16x16x32_bf16 v[70:73], v[146:149], v[202:205], v[70:73]
	v_mfma_f32_16x16x32_bf16 v[66:69], v[154:157], v[202:205], v[66:69]
	v_mfma_f32_16x16x32_bf16 v[134:137], v[150:153], v[182:185], v[134:137]
	v_mfma_f32_16x16x32_bf16 v[130:133], v[158:161], v[182:185], v[130:133]
	v_mfma_f32_16x16x32_bf16 v[102:105], v[150:153], v[190:193], v[102:105]
	v_mfma_f32_16x16x32_bf16 v[98:101], v[158:161], v[190:193], v[98:101]
	v_mfma_f32_16x16x32_bf16 v[86:89], v[150:153], v[198:201], v[86:89]
	v_mfma_f32_16x16x32_bf16 v[82:85], v[158:161], v[198:201], v[82:85]
	v_mfma_f32_16x16x32_bf16 v[70:73], v[150:153], v[214:217], v[70:73]
	v_mfma_f32_16x16x32_bf16 v[66:69], v[158:161], v[214:217], v[66:69]
	s_setprio 0
	s_barrier
	s_add_i32 s81, s64, s44
	v_lshl_add_u64 v[218:219], s[82:83], 0, v[164:165]
	s_mov_b32 m0, s81
	ds_read_b128 v[178:181], v211 offset:16384
	ds_read_b128 v[182:185], v211 offset:17408
	ds_read_b128 v[186:189], v211 offset:18432
	ds_read_b128 v[190:193], v211 offset:19456
	ds_read_b128 v[194:197], v211 offset:20480
	ds_read_b128 v[198:201], v211 offset:21504
	ds_read_b128 v[202:205], v211 offset:22528
	ds_read_b128 v[214:217], v211 offset:23552
	global_load_lds_dwordx4 v[218:219], off
	s_add_i32 m0, s81, 0x2000
	v_lshl_add_u64 v[220:221], s[82:83], 0, v[168:169]
	s_add_u32 s82, s82, s8
	s_addc_u32 s83, s83, s9
	s_add_i32 s81, s65, s44
	global_load_lds_dwordx4 v[220:221], off
	v_lshl_add_u64 v[222:223], s[82:83], 0, v[164:165]
	s_mov_b32 m0, s81
	v_lshl_add_u64 v[224:225], s[82:83], 0, v[168:169]
	global_load_lds_dwordx4 v[222:223], off
	s_add_i32 m0, s81, 0x2000
	v_lshl_add_u64 v[226:227], s[38:39], 0, v[162:163]
	global_load_lds_dwordx4 v[224:225], off
	s_mov_b32 m0, s45
	s_nop 0
	global_load_lds_dwordx4 v[226:227], off nt
	v_lshl_add_u64 v[226:227], s[38:39], 0, v[166:167]
	s_mov_b32 m0, s46
	s_nop 0
	global_load_lds_dwordx4 v[226:227], off nt
	s_waitcnt vmcnt(8)
	s_waitcnt lgkmcnt(0)
	s_setprio 1
	s_waitcnt lgkmcnt(0)
	v_mfma_f32_16x16x32_bf16 v[62:65], v[114:117], v[178:181], v[62:65]
	v_mfma_f32_16x16x32_bf16 v[58:61], v[122:125], v[178:181], v[58:61]
	s_barrier
	v_mfma_f32_16x16x32_bf16 v[46:49], v[114:117], v[186:189], v[46:49]
	v_mfma_f32_16x16x32_bf16 v[42:45], v[122:125], v[186:189], v[42:45]
	v_mfma_f32_16x16x32_bf16 v[30:33], v[114:117], v[194:197], v[30:33]
	v_mfma_f32_16x16x32_bf16 v[26:29], v[122:125], v[194:197], v[26:29]
	v_mfma_f32_16x16x32_bf16 v[14:17], v[114:117], v[202:205], v[14:17]
	v_mfma_f32_16x16x32_bf16 v[10:13], v[122:125], v[202:205], v[10:13]
	v_mfma_f32_16x16x32_bf16 v[62:65], v[118:121], v[182:185], v[62:65]
	v_mfma_f32_16x16x32_bf16 v[58:61], v[126:129], v[182:185], v[58:61]
	v_mfma_f32_16x16x32_bf16 v[46:49], v[118:121], v[190:193], v[46:49]
	v_mfma_f32_16x16x32_bf16 v[42:45], v[126:129], v[190:193], v[42:45]
	v_mfma_f32_16x16x32_bf16 v[30:33], v[118:121], v[198:201], v[30:33]
	v_mfma_f32_16x16x32_bf16 v[26:29], v[126:129], v[198:201], v[26:29]
	v_mfma_f32_16x16x32_bf16 v[14:17], v[118:121], v[214:217], v[14:17]
	v_mfma_f32_16x16x32_bf16 v[10:13], v[126:129], v[214:217], v[10:13]
	s_setprio 0
	s_setprio 1
	v_mfma_f32_16x16x32_bf16 v[54:57], v[146:149], v[178:181], v[54:57]
	v_mfma_f32_16x16x32_bf16 v[50:53], v[154:157], v[178:181], v[50:53]
	v_mfma_f32_16x16x32_bf16 v[38:41], v[146:149], v[186:189], v[38:41]
	v_mfma_f32_16x16x32_bf16 v[34:37], v[154:157], v[186:189], v[34:37]
	v_mfma_f32_16x16x32_bf16 v[22:25], v[146:149], v[194:197], v[22:25]
	v_mfma_f32_16x16x32_bf16 v[18:21], v[154:157], v[194:197], v[18:21]
	v_mfma_f32_16x16x32_bf16 v[6:9], v[146:149], v[202:205], v[6:9]
	v_mfma_f32_16x16x32_bf16 v[2:5], v[154:157], v[202:205], v[2:5]
	v_mfma_f32_16x16x32_bf16 v[54:57], v[150:153], v[182:185], v[54:57]
	v_mfma_f32_16x16x32_bf16 v[50:53], v[158:161], v[182:185], v[50:53]
	v_mfma_f32_16x16x32_bf16 v[38:41], v[150:153], v[190:193], v[38:41]
	v_mfma_f32_16x16x32_bf16 v[34:37], v[158:161], v[190:193], v[34:37]
	v_mfma_f32_16x16x32_bf16 v[22:25], v[150:153], v[198:201], v[22:25]
	v_mfma_f32_16x16x32_bf16 v[18:21], v[158:161], v[198:201], v[18:21]
	v_mfma_f32_16x16x32_bf16 v[6:9], v[150:153], v[214:217], v[6:9]
	v_mfma_f32_16x16x32_bf16 v[2:5], v[158:161], v[214:217], v[2:5]
	s_setprio 0
	s_barrier
	s_add_i32 s81, 0, 0x18000
	s_add_i32 s82, 0, 0x1c000
	v_add_u32_e32 v126, s81, v207
	v_add_u32_e32 v158, s82, v207
	ds_read_b128 v[114:117], v126
	ds_read_b128 v[118:121], v126 offset:1024
	ds_read_b128 v[122:125], v126 offset:2048
	ds_read_b128 v[126:129], v126 offset:3072
	ds_read_b128 v[146:149], v158
	ds_read_b128 v[150:153], v158 offset:1024
	ds_read_b128 v[154:157], v158 offset:2048
	ds_read_b128 v[158:161], v158 offset:3072
	s_add_u32 s38, s38, 0x4000
	s_addc_u32 s39, s39, 0
	s_mov_b32 m0, s47
	v_lshl_add_u64 v[226:227], s[38:39], 0, v[162:163]
	ds_read_b128 v[178:181], v211 offset:32768
	ds_read_b128 v[182:185], v211 offset:33792
	ds_read_b128 v[186:189], v211 offset:34816
	ds_read_b128 v[190:193], v211 offset:35840
	ds_read_b128 v[194:197], v211 offset:36864
	ds_read_b128 v[198:201], v211 offset:37888
	ds_read_b128 v[202:205], v211 offset:38912
	ds_read_b128 v[214:217], v211 offset:39936
	global_load_lds_dwordx4 v[226:227], off nt
	v_lshl_add_u64 v[226:227], s[38:39], 0, v[166:167]
	s_mov_b32 m0, s50
	s_nop 0
	global_load_lds_dwordx4 v[226:227], off nt
	s_waitcnt vmcnt(8)
	s_waitcnt lgkmcnt(0)
	s_setprio 1
	s_waitcnt lgkmcnt(0)
	v_mfma_f32_16x16x32_bf16 v[142:145], v[114:117], v[178:181], v[142:145]
	v_mfma_f32_16x16x32_bf16 v[138:141], v[122:125], v[178:181], v[138:141]
	s_barrier
	v_mfma_f32_16x16x32_bf16 v[110:113], v[114:117], v[186:189], v[110:113]
	v_mfma_f32_16x16x32_bf16 v[106:109], v[122:125], v[186:189], v[106:109]
	v_mfma_f32_16x16x32_bf16 v[94:97], v[114:117], v[194:197], v[94:97]
	v_mfma_f32_16x16x32_bf16 v[90:93], v[122:125], v[194:197], v[90:93]
	v_mfma_f32_16x16x32_bf16 v[78:81], v[114:117], v[202:205], v[78:81]
	v_mfma_f32_16x16x32_bf16 v[74:77], v[122:125], v[202:205], v[74:77]
	v_mfma_f32_16x16x32_bf16 v[142:145], v[118:121], v[182:185], v[142:145]
	v_mfma_f32_16x16x32_bf16 v[138:141], v[126:129], v[182:185], v[138:141]
	v_mfma_f32_16x16x32_bf16 v[110:113], v[118:121], v[190:193], v[110:113]
	v_mfma_f32_16x16x32_bf16 v[106:109], v[126:129], v[190:193], v[106:109]
	v_mfma_f32_16x16x32_bf16 v[94:97], v[118:121], v[198:201], v[94:97]
	v_mfma_f32_16x16x32_bf16 v[90:93], v[126:129], v[198:201], v[90:93]
	v_mfma_f32_16x16x32_bf16 v[78:81], v[118:121], v[214:217], v[78:81]
	v_mfma_f32_16x16x32_bf16 v[74:77], v[126:129], v[214:217], v[74:77]
	s_setprio 0
	s_setprio 1
	v_mfma_f32_16x16x32_bf16 v[134:137], v[146:149], v[178:181], v[134:137]
	v_mfma_f32_16x16x32_bf16 v[130:133], v[154:157], v[178:181], v[130:133]
	v_mfma_f32_16x16x32_bf16 v[102:105], v[146:149], v[186:189], v[102:105]
	v_mfma_f32_16x16x32_bf16 v[98:101], v[154:157], v[186:189], v[98:101]
	v_mfma_f32_16x16x32_bf16 v[86:89], v[146:149], v[194:197], v[86:89]
	v_mfma_f32_16x16x32_bf16 v[82:85], v[154:157], v[194:197], v[82:85]
	v_mfma_f32_16x16x32_bf16 v[70:73], v[146:149], v[202:205], v[70:73]
	v_mfma_f32_16x16x32_bf16 v[66:69], v[154:157], v[202:205], v[66:69]
	v_mfma_f32_16x16x32_bf16 v[134:137], v[150:153], v[182:185], v[134:137]
	v_mfma_f32_16x16x32_bf16 v[130:133], v[158:161], v[182:185], v[130:133]
	v_mfma_f32_16x16x32_bf16 v[102:105], v[150:153], v[190:193], v[102:105]
	v_mfma_f32_16x16x32_bf16 v[98:101], v[158:161], v[190:193], v[98:101]
	v_mfma_f32_16x16x32_bf16 v[86:89], v[150:153], v[198:201], v[86:89]
	v_mfma_f32_16x16x32_bf16 v[82:85], v[158:161], v[198:201], v[82:85]
	v_mfma_f32_16x16x32_bf16 v[70:73], v[150:153], v[214:217], v[70:73]
	v_mfma_f32_16x16x32_bf16 v[66:69], v[158:161], v[214:217], v[66:69]
	s_setprio 0
	s_barrier
	s_add_i32 s38, s81, s44
	v_lshl_add_u64 v[218:219], v[218:219], 0, s[24:25]
	s_mov_b32 m0, s38
	ds_read_b128 v[178:181], v211 offset:49152
	ds_read_b128 v[182:185], v211 offset:50176
	ds_read_b128 v[186:189], v211 offset:51200
	ds_read_b128 v[190:193], v211 offset:52224
	ds_read_b128 v[194:197], v211 offset:53248
	ds_read_b128 v[198:201], v211 offset:54272
	ds_read_b128 v[202:205], v211 offset:55296
	ds_read_b128 v[214:217], v211 offset:56320
	global_load_lds_dwordx4 v[218:219], off
	v_lshl_add_u64 v[218:219], v[220:221], 0, s[24:25]
	s_add_i32 m0, s38, 0x2000
	s_add_i32 s38, s82, s44
	global_load_lds_dwordx4 v[218:219], off
	v_lshl_add_u64 v[218:219], v[222:223], 0, s[24:25]
	s_mov_b32 m0, s38
	s_nop 0
	global_load_lds_dwordx4 v[218:219], off
	v_lshl_add_u64 v[218:219], v[224:225], 0, s[24:25]
	s_add_i32 m0, s38, 0x2000
	s_nop 0
	global_load_lds_dwordx4 v[218:219], off
	v_lshl_add_u64 v[218:219], s[36:37], 0, v[162:163]
	s_mov_b32 m0, s59
	s_nop 0
	global_load_lds_dwordx4 v[218:219], off nt
	v_lshl_add_u64 v[218:219], s[36:37], 0, v[166:167]
	s_mov_b32 m0, s60
	s_nop 0
	global_load_lds_dwordx4 v[218:219], off nt
	s_waitcnt vmcnt(8)
	s_waitcnt lgkmcnt(0)
	s_setprio 1
	s_waitcnt lgkmcnt(0)
	v_mfma_f32_16x16x32_bf16 v[62:65], v[114:117], v[178:181], v[62:65]
	v_mfma_f32_16x16x32_bf16 v[58:61], v[122:125], v[178:181], v[58:61]
	s_barrier
	v_mfma_f32_16x16x32_bf16 v[46:49], v[114:117], v[186:189], v[46:49]
	v_mfma_f32_16x16x32_bf16 v[42:45], v[122:125], v[186:189], v[42:45]
	v_mfma_f32_16x16x32_bf16 v[30:33], v[114:117], v[194:197], v[30:33]
	v_mfma_f32_16x16x32_bf16 v[26:29], v[122:125], v[194:197], v[26:29]
	v_mfma_f32_16x16x32_bf16 v[14:17], v[114:117], v[202:205], v[14:17]
	v_mfma_f32_16x16x32_bf16 v[10:13], v[122:125], v[202:205], v[10:13]
	v_mfma_f32_16x16x32_bf16 v[62:65], v[118:121], v[182:185], v[62:65]
	v_mfma_f32_16x16x32_bf16 v[58:61], v[126:129], v[182:185], v[58:61]
	v_mfma_f32_16x16x32_bf16 v[46:49], v[118:121], v[190:193], v[46:49]
	v_mfma_f32_16x16x32_bf16 v[42:45], v[126:129], v[190:193], v[42:45]
	v_mfma_f32_16x16x32_bf16 v[30:33], v[118:121], v[198:201], v[30:33]
	v_mfma_f32_16x16x32_bf16 v[26:29], v[126:129], v[198:201], v[26:29]
	v_mfma_f32_16x16x32_bf16 v[14:17], v[118:121], v[214:217], v[14:17]
	v_mfma_f32_16x16x32_bf16 v[10:13], v[126:129], v[214:217], v[10:13]
	s_setprio 0
	s_setprio 1
	v_mfma_f32_16x16x32_bf16 v[54:57], v[146:149], v[178:181], v[54:57]
	v_mfma_f32_16x16x32_bf16 v[50:53], v[154:157], v[178:181], v[50:53]
	v_mfma_f32_16x16x32_bf16 v[38:41], v[146:149], v[186:189], v[38:41]
	v_mfma_f32_16x16x32_bf16 v[34:37], v[154:157], v[186:189], v[34:37]
	v_mfma_f32_16x16x32_bf16 v[22:25], v[146:149], v[194:197], v[22:25]
	v_mfma_f32_16x16x32_bf16 v[18:21], v[154:157], v[194:197], v[18:21]
	v_mfma_f32_16x16x32_bf16 v[6:9], v[146:149], v[202:205], v[6:9]
	v_mfma_f32_16x16x32_bf16 v[2:5], v[154:157], v[202:205], v[2:5]
	v_mfma_f32_16x16x32_bf16 v[54:57], v[150:153], v[182:185], v[54:57]
	v_mfma_f32_16x16x32_bf16 v[50:53], v[158:161], v[182:185], v[50:53]
	v_mfma_f32_16x16x32_bf16 v[38:41], v[150:153], v[190:193], v[38:41]
	v_mfma_f32_16x16x32_bf16 v[34:37], v[158:161], v[190:193], v[34:37]
	v_mfma_f32_16x16x32_bf16 v[22:25], v[150:153], v[198:201], v[22:25]
	v_mfma_f32_16x16x32_bf16 v[18:21], v[158:161], v[198:201], v[18:21]
	v_mfma_f32_16x16x32_bf16 v[6:9], v[150:153], v[214:217], v[6:9]
	v_mfma_f32_16x16x32_bf16 v[2:5], v[158:161], v[214:217], v[2:5]
	s_setprio 0
	s_barrier
	s_add_u32 s70, s70, 0x100
	s_addc_u32 s71, s71, 0
	s_add_u32 s34, s34, 0x10000
	s_addc_u32 s35, s35, 0
	s_cmp_ge_i32 s80, s58
	s_mov_b32 s36, s80
	s_cbranch_scc0 .LBB0_3032

.LBB0_3802:
	s_lshl_b32 s26, s30, 8
	s_add_i32 s28, s26, s52
	s_lshl_b32 s26, s31, 8
	s_or_b32 s29, s26, s53
	s_lshr_b32 s26, s30, 4
	s_add_i32 s26, s26, -1
	v_or_b32_e32 v2, s29, v186
	s_cmp_gt_i32 s30, 31
	s_cselect_b32 s26, s26, 0
	v_ashrrev_i32_e32 v3, 31, v2
	v_or_b32_e32 v168, s28, v187
	v_lshlrev_b64 v[10:11], 2, v[2:3]
	v_ashrrev_i32_e32 v169, 31, v168
	s_ashr_i32 s27, s26, 31
	v_lshl_add_u64 v[12:13], s[16:17], 0, v[10:11]
	v_lshl_add_u64 v[100:101], v[168:169], 2, s[14:15]
	s_lshl_b64 s[26:27], s[26:27], 15
	global_load_dwordx4 v[2:5], v[12:13], off offset:16
	global_load_dwordx4 v[6:9], v[12:13], off
	global_load_dword v190, v[100:101], off
	s_add_u32 s26, s47, s26
	global_load_dwordx4 v[14:17], v[12:13], off offset:528
	global_load_dwordx4 v[30:33], v[12:13], off offset:512
	s_addc_u32 s27, s48, s27
	v_lshl_add_u64 v[10:11], s[26:27], 0, v[10:11]
	global_load_dwordx4 v[26:29], v[10:11], off
	global_load_dwordx4 v[22:25], v[10:11], off offset:16
	global_load_dwordx4 v[18:21], v[10:11], off offset:512
	s_nop 0
	global_load_dwordx4 v[10:13], v[10:11], off offset:528
	s_ashr_i32 s28, s28, 8
	v_bitop3_b32 v90, s29, 56, v186 bitop3:0xc8
	s_ashr_i32 s26, s29, 6
	s_ashr_i32 s29, s28, 31
	s_ashr_i32 s27, s26, 31
	s_lshl_b64 s[34:35], s[28:29], 7
	s_add_u32 s28, s34, s26
	s_addc_u32 s29, s35, s27
	s_lshl_b64 s[28:29], s[28:29], 15
	s_add_u32 s30, s12, s28
	s_addc_u32 s31, s13, s29
	s_or_b32 s28, s26, 2
	s_ashr_i32 s29, s28, 31
	s_add_u32 s34, s34, s28
	v_lshlrev_b32_e32 v169, 7, v168
	s_addc_u32 s35, s35, s29
	v_and_b32_e32 v138, 0x6780, v169
	s_lshl_b64 s[34:35], s[34:35], 15
	v_mov_b32_e32 v91, v139
	v_lshlrev_b32_e32 v90, 1, v90
	v_lshl_add_u64 v[192:193], s[30:31], 0, v[138:139]
	s_add_u32 s34, s12, s34
	v_lshl_add_u64 v[192:193], v[192:193], 0, v[90:91]
	s_addc_u32 s35, s13, s35
	s_and_b64 vcc, exec, s[0:1]
	s_mov_b64 s[0:1], -1
	s_waitcnt vmcnt(0)
	v_pk_mul_f32 v[194:195], v[6:7], v[190:191] op_sel_hi:[1,0]
	v_pk_mul_f32 v[196:197], v[8:9], v[190:191] op_sel_hi:[1,0]
	v_pk_mul_f32 v[198:199], v[2:3], v[190:191] op_sel_hi:[1,0]
	v_pk_mul_f32 v[204:205], v[32:33], v[190:191] op_sel_hi:[1,0]
	v_pk_fma_f32 v[170:171], v[196:197], v[170:171], v[28:29]
	v_pk_fma_f32 v[172:173], v[194:195], v[172:173], v[26:27]
	v_pk_mul_f32 v[200:201], v[4:5], v[190:191] op_sel_hi:[1,0]
	v_pk_mul_f32 v[202:203], v[30:31], v[190:191] op_sel_hi:[1,0]
	v_pk_mul_f32 v[206:207], v[14:15], v[190:191] op_sel_hi:[1,0]
	v_pk_mul_f32 v[190:191], v[16:17], v[190:191] op_sel_hi:[1,0]
	v_pk_fma_f32 v[174:175], v[198:199], v[174:175], v[22:23]
	v_pk_fma_f32 v[182:183], v[204:205], v[182:183], v[20:21]
	v_max_f32_e32 v173, 0, v173
	v_max_f32_e32 v172, 0, v172
	v_max_f32_e32 v171, 0, v171
	v_max_f32_e32 v170, 0, v170
	v_pk_fma_f32 v[176:177], v[200:201], v[176:177], v[24:25]
	v_pk_fma_f32 v[180:181], v[202:203], v[180:181], v[18:19]
	v_pk_fma_f32 v[184:185], v[190:191], v[184:185], v[12:13]
	v_max_f32_e32 v175, 0, v175
	v_max_f32_e32 v174, 0, v174
	v_max_f32_e32 v183, 0, v183
	v_max_f32_e32 v182, 0, v182
	v_pk_mul_f32 v[190:191], v[170:171], v[170:171]
	v_pk_mul_f32 v[170:171], v[172:173], v[172:173]
	v_max_f32_e32 v177, 0, v177
	v_max_f32_e32 v176, 0, v176
	v_max_f32_e32 v181, 0, v181
	v_max_f32_e32 v180, 0, v180
	v_pk_mul_f32 v[172:173], v[174:175], v[174:175]
	v_pk_mul_f32 v[174:175], v[182:183], v[182:183]
	v_cvt_pk_bf16_f32 v170, v170, v171
	v_cvt_pk_bf16_f32 v171, v190, v191
	v_pk_fma_f32 v[178:179], v[206:207], v[178:179], v[10:11]
	v_pk_mul_f32 v[176:177], v[176:177], v[176:177]
	v_pk_mul_f32 v[180:181], v[180:181], v[180:181]
	v_cvt_pk_bf16_f32 v172, v172, v173
	v_cvt_pk_bf16_f32 v173, v176, v177
	global_store_dwordx4 v[192:193], v[170:173], off nt
	v_max_f32_e32 v179, 0, v179
	v_max_f32_e32 v178, 0, v178
	v_cvt_pk_bf16_f32 v170, v180, v181
	v_cvt_pk_bf16_f32 v171, v174, v175
	v_lshl_add_u64 v[174:175], s[34:35], 0, v[138:139]
	v_max_f32_e32 v185, 0, v185
	v_max_f32_e32 v184, 0, v184
	v_lshl_add_u64 v[174:175], v[174:175], 0, v[90:91]
	v_pk_mul_f32 v[182:183], v[184:185], v[184:185]
	v_pk_mul_f32 v[178:179], v[178:179], v[178:179]
	s_nop 0
	v_cvt_pk_bf16_f32 v172, v178, v179
	v_cvt_pk_bf16_f32 v173, v182, v183
	global_store_dwordx4 v[174:175], v[170:173], off nt
	v_or_b32_e32 v174, 32, v168
	v_ashrrev_i32_e32 v175, 31, v174
	v_or_b32_e32 v170, 16, v168
	v_ashrrev_i32_e32 v171, 31, v170
	v_lshl_add_u64 v[172:173], v[170:171], 2, s[14:15]
	global_load_dword v172, v[172:173], off
	v_lshlrev_b32_e32 v138, 7, v170
	v_and_b32_e32 v138, 0x6f80, v138
	v_lshl_add_u64 v[176:177], s[30:31], 0, v[138:139]
	v_lshl_add_u64 v[178:179], s[34:35], 0, v[138:139]
	v_lshl_add_u64 v[176:177], v[176:177], 0, v[90:91]
	v_lshl_add_u64 v[178:179], v[178:179], 0, v[90:91]
	v_lshl_add_u64 v[170:171], v[174:175], 2, s[14:15]
	v_lshlrev_b32_e32 v138, 7, v174
	v_and_b32_e32 v138, 0x7780, v138
	s_waitcnt vmcnt(0)
	v_pk_mul_f32 v[180:181], v[6:7], v[172:173] op_sel_hi:[1,0]
	v_pk_mul_f32 v[182:183], v[8:9], v[172:173] op_sel_hi:[1,0]
	v_pk_mul_f32 v[184:185], v[2:3], v[172:173] op_sel_hi:[1,0]
	v_pk_mul_f32 v[190:191], v[4:5], v[172:173] op_sel_hi:[1,0]
	v_pk_fma_f32 v[154:155], v[182:183], v[154:155], v[28:29]
	v_pk_fma_f32 v[152:153], v[180:181], v[152:153], v[26:27]
	v_pk_mul_f32 v[192:193], v[30:31], v[172:173] op_sel_hi:[1,0]
	v_pk_mul_f32 v[194:195], v[32:33], v[172:173] op_sel_hi:[1,0]
	v_pk_mul_f32 v[196:197], v[14:15], v[172:173] op_sel_hi:[1,0]
	v_pk_mul_f32 v[172:173], v[16:17], v[172:173] op_sel_hi:[1,0]
	v_pk_fma_f32 v[158:159], v[190:191], v[158:159], v[24:25]
	v_pk_fma_f32 v[156:157], v[184:185], v[156:157], v[22:23]
	v_max_f32_e32 v153, 0, v153
	v_max_f32_e32 v152, 0, v152
	v_max_f32_e32 v155, 0, v155
	v_max_f32_e32 v154, 0, v154
	v_pk_fma_f32 v[162:163], v[194:195], v[162:163], v[20:21]
	v_pk_fma_f32 v[160:161], v[192:193], v[160:161], v[18:19]
	v_pk_fma_f32 v[166:167], v[172:173], v[166:167], v[12:13]
	v_pk_fma_f32 v[164:165], v[196:197], v[164:165], v[10:11]
	v_max_f32_e32 v157, 0, v157
	v_max_f32_e32 v156, 0, v156
	v_max_f32_e32 v159, 0, v159
	v_max_f32_e32 v158, 0, v158
	v_pk_mul_f32 v[154:155], v[154:155], v[154:155]
	v_pk_mul_f32 v[152:153], v[152:153], v[152:153]
	v_max_f32_e32 v161, 0, v161
	v_max_f32_e32 v160, 0, v160
	v_max_f32_e32 v163, 0, v163
	v_max_f32_e32 v162, 0, v162
	v_max_f32_e32 v165, 0, v165
	v_max_f32_e32 v164, 0, v164
	v_max_f32_e32 v167, 0, v167
	v_max_f32_e32 v166, 0, v166
	v_pk_mul_f32 v[158:159], v[158:159], v[158:159]
	v_pk_mul_f32 v[156:157], v[156:157], v[156:157]
	v_cvt_pk_bf16_f32 v152, v152, v153
	v_cvt_pk_bf16_f32 v153, v154, v155
	v_pk_mul_f32 v[162:163], v[162:163], v[162:163]
	v_cvt_pk_bf16_f32 v154, v156, v157
	v_cvt_pk_bf16_f32 v155, v158, v159
	v_pk_mul_f32 v[160:161], v[160:161], v[160:161]
	v_pk_mul_f32 v[166:167], v[166:167], v[166:167]
	v_pk_mul_f32 v[164:165], v[164:165], v[164:165]
	global_store_dwordx4 v[176:177], v[152:155], off nt
	v_lshl_add_u64 v[158:159], s[30:31], 0, v[138:139]
	v_lshl_add_u64 v[158:159], v[158:159], 0, v[90:91]
	v_cvt_pk_bf16_f32 v152, v160, v161
	v_cvt_pk_bf16_f32 v153, v162, v163
	v_cvt_pk_bf16_f32 v154, v164, v165
	v_cvt_pk_bf16_f32 v155, v166, v167
	global_store_dwordx4 v[178:179], v[152:155], off nt
	global_load_dword v152, v[170:171], off
	v_lshl_add_u64 v[160:161], s[34:35], 0, v[138:139]
	v_or_b32_e32 v154, 48, v168
	v_ashrrev_i32_e32 v155, 31, v154
	v_lshl_add_u64 v[160:161], v[160:161], 0, v[90:91]
	v_lshl_add_u64 v[156:157], v[154:155], 2, s[14:15]
	s_waitcnt vmcnt(0)
	v_pk_mul_f32 v[162:163], v[6:7], v[152:153] op_sel_hi:[1,0]
	v_pk_mul_f32 v[164:165], v[8:9], v[152:153] op_sel_hi:[1,0]
	v_pk_mul_f32 v[166:167], v[2:3], v[152:153] op_sel_hi:[1,0]
	v_pk_mul_f32 v[170:171], v[4:5], v[152:153] op_sel_hi:[1,0]
	v_pk_fma_f32 v[120:121], v[164:165], v[120:121], v[28:29]
	v_pk_fma_f32 v[118:119], v[162:163], v[118:119], v[26:27]
	v_pk_mul_f32 v[172:173], v[30:31], v[152:153] op_sel_hi:[1,0]
	v_pk_mul_f32 v[174:175], v[32:33], v[152:153] op_sel_hi:[1,0]
	v_pk_mul_f32 v[176:177], v[14:15], v[152:153] op_sel_hi:[1,0]
	v_pk_mul_f32 v[152:153], v[16:17], v[152:153] op_sel_hi:[1,0]
	v_pk_fma_f32 v[124:125], v[170:171], v[124:125], v[24:25]
	v_pk_fma_f32 v[122:123], v[166:167], v[122:123], v[22:23]
	v_max_f32_e32 v119, 0, v119
	v_max_f32_e32 v118, 0, v118
	v_max_f32_e32 v121, 0, v121
	v_max_f32_e32 v120, 0, v120
	v_pk_fma_f32 v[128:129], v[174:175], v[128:129], v[20:21]
	v_pk_fma_f32 v[126:127], v[172:173], v[126:127], v[18:19]
	v_pk_fma_f32 v[150:151], v[152:153], v[150:151], v[12:13]
	v_pk_fma_f32 v[148:149], v[176:177], v[148:149], v[10:11]
	v_max_f32_e32 v123, 0, v123
	v_max_f32_e32 v122, 0, v122
	v_max_f32_e32 v125, 0, v125
	v_max_f32_e32 v124, 0, v124
	v_pk_mul_f32 v[120:121], v[120:121], v[120:121]
	v_pk_mul_f32 v[118:119], v[118:119], v[118:119]
	v_max_f32_e32 v127, 0, v127
	v_max_f32_e32 v126, 0, v126
	v_max_f32_e32 v129, 0, v129
	v_max_f32_e32 v128, 0, v128
	v_max_f32_e32 v149, 0, v149
	v_max_f32_e32 v148, 0, v148
	v_max_f32_e32 v151, 0, v151
	v_max_f32_e32 v150, 0, v150
	v_pk_mul_f32 v[124:125], v[124:125], v[124:125]
	v_pk_mul_f32 v[122:123], v[122:123], v[122:123]
	v_cvt_pk_bf16_f32 v118, v118, v119
	v_cvt_pk_bf16_f32 v119, v120, v121
	v_pk_mul_f32 v[128:129], v[128:129], v[128:129]
	v_cvt_pk_bf16_f32 v120, v122, v123
	v_cvt_pk_bf16_f32 v121, v124, v125
	v_pk_mul_f32 v[126:127], v[126:127], v[126:127]
	v_pk_mul_f32 v[150:151], v[150:151], v[150:151]
	v_pk_mul_f32 v[148:149], v[148:149], v[148:149]
	global_store_dwordx4 v[158:159], v[118:121], off nt
	s_nop 1
	v_cvt_pk_bf16_f32 v118, v126, v127
	v_cvt_pk_bf16_f32 v119, v128, v129
	v_cvt_pk_bf16_f32 v120, v148, v149
	v_cvt_pk_bf16_f32 v121, v150, v151
	global_store_dwordx4 v[160:161], v[118:121], off nt
	global_load_dword v118, v[156:157], off
	s_nop 0
	v_lshlrev_b32_e32 v119, 7, v154
	v_and_b32_e32 v138, 0x7f80, v119
	v_lshl_add_u64 v[120:121], s[30:31], 0, v[138:139]
	v_lshl_add_u64 v[122:123], s[34:35], 0, v[138:139]
	v_lshl_add_u64 v[120:121], v[120:121], 0, v[90:91]
	v_lshl_add_u64 v[122:123], v[122:123], 0, v[90:91]
	s_waitcnt vmcnt(0)
	v_pk_mul_f32 v[124:125], v[6:7], v[118:119] op_sel_hi:[1,0]
	v_pk_mul_f32 v[126:127], v[8:9], v[118:119] op_sel_hi:[1,0]
	v_pk_mul_f32 v[128:129], v[2:3], v[118:119] op_sel_hi:[1,0]
	v_pk_mul_f32 v[148:149], v[4:5], v[118:119] op_sel_hi:[1,0]
	v_pk_fma_f32 v[104:105], v[126:127], v[104:105], v[28:29]
	v_pk_fma_f32 v[102:103], v[124:125], v[102:103], v[26:27]
	v_pk_mul_f32 v[150:151], v[30:31], v[118:119] op_sel_hi:[1,0]
	v_pk_mul_f32 v[152:153], v[32:33], v[118:119] op_sel_hi:[1,0]
	v_pk_mul_f32 v[154:155], v[14:15], v[118:119] op_sel_hi:[1,0]
	v_pk_mul_f32 v[118:119], v[16:17], v[118:119] op_sel_hi:[1,0]
	v_pk_fma_f32 v[108:109], v[148:149], v[108:109], v[24:25]
	v_pk_fma_f32 v[106:107], v[128:129], v[106:107], v[22:23]
	v_max_f32_e32 v103, 0, v103
	v_max_f32_e32 v102, 0, v102
	v_max_f32_e32 v105, 0, v105
	v_max_f32_e32 v104, 0, v104
	v_pk_fma_f32 v[112:113], v[152:153], v[112:113], v[20:21]
	v_pk_fma_f32 v[110:111], v[150:151], v[110:111], v[18:19]
	v_pk_fma_f32 v[116:117], v[118:119], v[116:117], v[12:13]
	v_pk_fma_f32 v[114:115], v[154:155], v[114:115], v[10:11]
	v_max_f32_e32 v107, 0, v107
	v_max_f32_e32 v106, 0, v106
	v_max_f32_e32 v109, 0, v109
	v_max_f32_e32 v108, 0, v108
	v_pk_mul_f32 v[104:105], v[104:105], v[104:105]
	v_pk_mul_f32 v[102:103], v[102:103], v[102:103]
	v_max_f32_e32 v111, 0, v111
	v_max_f32_e32 v110, 0, v110
	v_max_f32_e32 v113, 0, v113
	v_max_f32_e32 v112, 0, v112
	v_max_f32_e32 v115, 0, v115
	v_max_f32_e32 v114, 0, v114
	v_max_f32_e32 v117, 0, v117
	v_max_f32_e32 v116, 0, v116
	v_pk_mul_f32 v[108:109], v[108:109], v[108:109]
	v_pk_mul_f32 v[106:107], v[106:107], v[106:107]
	v_cvt_pk_bf16_f32 v102, v102, v103
	v_cvt_pk_bf16_f32 v103, v104, v105
	v_pk_mul_f32 v[112:113], v[112:113], v[112:113]
	v_cvt_pk_bf16_f32 v104, v106, v107
	v_cvt_pk_bf16_f32 v105, v108, v109
	v_pk_mul_f32 v[110:111], v[110:111], v[110:111]
	v_pk_mul_f32 v[116:117], v[116:117], v[116:117]
	v_pk_mul_f32 v[114:115], v[114:115], v[114:115]
	global_store_dwordx4 v[120:121], v[102:105], off nt
	s_nop 1
	v_cvt_pk_bf16_f32 v102, v110, v111
	v_cvt_pk_bf16_f32 v103, v112, v113
	v_cvt_pk_bf16_f32 v104, v114, v115
	v_cvt_pk_bf16_f32 v105, v116, v117
	global_store_dwordx4 v[122:123], v[102:105], off nt
	global_load_dword v106, v[100:101], off offset:512
	s_nop 0
	v_add_u32_e32 v103, 0x80, v168
	v_ashrrev_i32_e32 v102, 8, v103
	v_lshlrev_b32_e32 v107, 7, v103
	v_ashrrev_i32_e32 v103, 31, v102
	v_lshlrev_b64 v[104:105], 7, v[102:103]
	v_lshl_add_u64 v[102:103], v[104:105], 0, s[26:27]
	v_lshl_add_u64 v[104:105], v[104:105], 0, s[28:29]
	v_lshlrev_b64 v[102:103], 15, v[102:103]
	v_lshlrev_b64 v[104:105], 15, v[104:105]
	v_lshl_add_u64 v[102:103], s[12:13], 0, v[102:103]
	v_lshl_add_u64 v[104:105], s[12:13], 0, v[104:105]
	v_and_b32_e32 v138, 0x6780, v107
	v_lshl_add_u64 v[108:109], v[102:103], 0, v[138:139]
	v_lshl_add_u64 v[110:111], v[104:105], 0, v[138:139]
	v_lshl_add_u64 v[108:109], v[108:109], 0, v[90:91]
	v_lshl_add_u64 v[110:111], v[110:111], 0, v[90:91]
	s_waitcnt vmcnt(0)
	v_pk_mul_f32 v[112:113], v[6:7], v[106:107] op_sel_hi:[1,0]
	v_pk_mul_f32 v[114:115], v[8:9], v[106:107] op_sel_hi:[1,0]
	v_pk_mul_f32 v[116:117], v[2:3], v[106:107] op_sel_hi:[1,0]
	v_pk_mul_f32 v[118:119], v[4:5], v[106:107] op_sel_hi:[1,0]
	v_pk_fma_f32 v[84:85], v[114:115], v[84:85], v[28:29]
	v_pk_fma_f32 v[82:83], v[112:113], v[82:83], v[26:27]
	v_pk_mul_f32 v[120:121], v[30:31], v[106:107] op_sel_hi:[1,0]
	v_pk_mul_f32 v[122:123], v[32:33], v[106:107] op_sel_hi:[1,0]
	v_pk_mul_f32 v[124:125], v[14:15], v[106:107] op_sel_hi:[1,0]
	v_pk_mul_f32 v[106:107], v[16:17], v[106:107] op_sel_hi:[1,0]
	v_pk_fma_f32 v[88:89], v[118:119], v[88:89], v[24:25]
	v_pk_fma_f32 v[86:87], v[116:117], v[86:87], v[22:23]
	v_max_f32_e32 v83, 0, v83
	v_max_f32_e32 v82, 0, v82
	v_max_f32_e32 v85, 0, v85
	v_max_f32_e32 v84, 0, v84
	v_pk_fma_f32 v[94:95], v[122:123], v[94:95], v[20:21]
	v_pk_fma_f32 v[92:93], v[120:121], v[92:93], v[18:19]
	v_pk_fma_f32 v[98:99], v[106:107], v[98:99], v[12:13]
	v_pk_fma_f32 v[96:97], v[124:125], v[96:97], v[10:11]
	v_max_f32_e32 v87, 0, v87
	v_max_f32_e32 v86, 0, v86
	v_max_f32_e32 v89, 0, v89
	v_max_f32_e32 v88, 0, v88
	v_pk_mul_f32 v[84:85], v[84:85], v[84:85]
	v_pk_mul_f32 v[82:83], v[82:83], v[82:83]
	v_max_f32_e32 v93, 0, v93
	v_max_f32_e32 v92, 0, v92
	v_max_f32_e32 v95, 0, v95
	v_max_f32_e32 v94, 0, v94
	v_max_f32_e32 v97, 0, v97
	v_max_f32_e32 v96, 0, v96
	v_max_f32_e32 v99, 0, v99
	v_max_f32_e32 v98, 0, v98
	v_pk_mul_f32 v[88:89], v[88:89], v[88:89]
	v_pk_mul_f32 v[86:87], v[86:87], v[86:87]
	v_cvt_pk_bf16_f32 v82, v82, v83
	v_cvt_pk_bf16_f32 v83, v84, v85
	v_pk_mul_f32 v[94:95], v[94:95], v[94:95]
	v_cvt_pk_bf16_f32 v84, v86, v87
	v_cvt_pk_bf16_f32 v85, v88, v89
	v_pk_mul_f32 v[92:93], v[92:93], v[92:93]
	v_pk_mul_f32 v[98:99], v[98:99], v[98:99]
	v_pk_mul_f32 v[96:97], v[96:97], v[96:97]
	global_store_dwordx4 v[108:109], v[82:85], off nt
	s_nop 1
	v_cvt_pk_bf16_f32 v82, v92, v93
	v_cvt_pk_bf16_f32 v83, v94, v95
	v_cvt_pk_bf16_f32 v84, v96, v97
	v_cvt_pk_bf16_f32 v85, v98, v99
	global_store_dwordx4 v[110:111], v[82:85], off nt
	global_load_dword v82, v[100:101], off offset:576
	s_nop 0
	v_add_u32_e32 v83, 0x4800, v169
	v_and_b32_e32 v138, 0x6f80, v83
	v_lshl_add_u64 v[84:85], v[102:103], 0, v[138:139]
	v_lshl_add_u64 v[86:87], v[104:105], 0, v[138:139]
	v_lshl_add_u64 v[84:85], v[84:85], 0, v[90:91]
	v_lshl_add_u64 v[86:87], v[86:87], 0, v[90:91]
	s_waitcnt vmcnt(0)
	v_pk_mul_f32 v[88:89], v[6:7], v[82:83] op_sel_hi:[1,0]
	v_pk_mul_f32 v[92:93], v[8:9], v[82:83] op_sel_hi:[1,0]
	v_pk_mul_f32 v[94:95], v[2:3], v[82:83] op_sel_hi:[1,0]
	v_pk_mul_f32 v[96:97], v[4:5], v[82:83] op_sel_hi:[1,0]
	v_pk_fma_f32 v[68:69], v[92:93], v[68:69], v[28:29]
	v_pk_fma_f32 v[66:67], v[88:89], v[66:67], v[26:27]
	v_pk_mul_f32 v[98:99], v[30:31], v[82:83] op_sel_hi:[1,0]
	v_pk_mul_f32 v[106:107], v[32:33], v[82:83] op_sel_hi:[1,0]
	v_pk_mul_f32 v[108:109], v[14:15], v[82:83] op_sel_hi:[1,0]
	v_pk_mul_f32 v[82:83], v[16:17], v[82:83] op_sel_hi:[1,0]
	v_pk_fma_f32 v[72:73], v[96:97], v[72:73], v[24:25]
	v_pk_fma_f32 v[70:71], v[94:95], v[70:71], v[22:23]
	v_max_f32_e32 v67, 0, v67
	v_max_f32_e32 v66, 0, v66
	v_max_f32_e32 v69, 0, v69
	v_max_f32_e32 v68, 0, v68
	v_pk_fma_f32 v[76:77], v[106:107], v[76:77], v[20:21]
	v_pk_fma_f32 v[74:75], v[98:99], v[74:75], v[18:19]
	v_pk_fma_f32 v[80:81], v[82:83], v[80:81], v[12:13]
	v_pk_fma_f32 v[78:79], v[108:109], v[78:79], v[10:11]
	v_max_f32_e32 v71, 0, v71
	v_max_f32_e32 v70, 0, v70
	v_max_f32_e32 v73, 0, v73
	v_max_f32_e32 v72, 0, v72
	v_pk_mul_f32 v[68:69], v[68:69], v[68:69]
	v_pk_mul_f32 v[66:67], v[66:67], v[66:67]
	v_max_f32_e32 v75, 0, v75
	v_max_f32_e32 v74, 0, v74
	v_max_f32_e32 v77, 0, v77
	v_max_f32_e32 v76, 0, v76
	v_max_f32_e32 v79, 0, v79
	v_max_f32_e32 v78, 0, v78
	v_max_f32_e32 v81, 0, v81
	v_max_f32_e32 v80, 0, v80
	v_pk_mul_f32 v[72:73], v[72:73], v[72:73]
	v_pk_mul_f32 v[70:71], v[70:71], v[70:71]
	v_cvt_pk_bf16_f32 v66, v66, v67
	v_cvt_pk_bf16_f32 v67, v68, v69
	v_pk_mul_f32 v[76:77], v[76:77], v[76:77]
	v_cvt_pk_bf16_f32 v68, v70, v71
	v_cvt_pk_bf16_f32 v69, v72, v73
	v_pk_mul_f32 v[74:75], v[74:75], v[74:75]
	v_pk_mul_f32 v[80:81], v[80:81], v[80:81]
	v_pk_mul_f32 v[78:79], v[78:79], v[78:79]
	global_store_dwordx4 v[84:85], v[66:69], off nt
	s_nop 1
	v_cvt_pk_bf16_f32 v66, v74, v75
	v_cvt_pk_bf16_f32 v67, v76, v77
	v_cvt_pk_bf16_f32 v68, v78, v79
	v_cvt_pk_bf16_f32 v69, v80, v81
	global_store_dwordx4 v[86:87], v[66:69], off nt
	global_load_dword v66, v[100:101], off offset:640
	s_nop 0
	v_add_u32_e32 v67, 0x5000, v169
	v_and_b32_e32 v138, 0x7780, v67
	v_lshl_add_u64 v[68:69], v[102:103], 0, v[138:139]
	v_lshl_add_u64 v[70:71], v[104:105], 0, v[138:139]
	v_lshl_add_u64 v[68:69], v[68:69], 0, v[90:91]
	v_lshl_add_u64 v[70:71], v[70:71], 0, v[90:91]
	s_waitcnt vmcnt(0)
	v_pk_mul_f32 v[72:73], v[6:7], v[66:67] op_sel_hi:[1,0]
	v_pk_mul_f32 v[74:75], v[8:9], v[66:67] op_sel_hi:[1,0]
	v_pk_mul_f32 v[76:77], v[2:3], v[66:67] op_sel_hi:[1,0]
	v_pk_mul_f32 v[78:79], v[4:5], v[66:67] op_sel_hi:[1,0]
	v_pk_fma_f32 v[52:53], v[74:75], v[52:53], v[28:29]
	v_pk_fma_f32 v[50:51], v[72:73], v[50:51], v[26:27]
	v_pk_mul_f32 v[80:81], v[30:31], v[66:67] op_sel_hi:[1,0]
	v_pk_mul_f32 v[82:83], v[32:33], v[66:67] op_sel_hi:[1,0]
	v_pk_mul_f32 v[84:85], v[14:15], v[66:67] op_sel_hi:[1,0]
	v_pk_mul_f32 v[66:67], v[16:17], v[66:67] op_sel_hi:[1,0]
	v_pk_fma_f32 v[56:57], v[78:79], v[56:57], v[24:25]
	v_pk_fma_f32 v[54:55], v[76:77], v[54:55], v[22:23]
	v_max_f32_e32 v51, 0, v51
	v_max_f32_e32 v50, 0, v50
	v_max_f32_e32 v53, 0, v53
	v_max_f32_e32 v52, 0, v52
	v_pk_fma_f32 v[60:61], v[82:83], v[60:61], v[20:21]
	v_pk_fma_f32 v[58:59], v[80:81], v[58:59], v[18:19]
	v_pk_fma_f32 v[64:65], v[66:67], v[64:65], v[12:13]
	v_pk_fma_f32 v[62:63], v[84:85], v[62:63], v[10:11]
	v_max_f32_e32 v55, 0, v55
	v_max_f32_e32 v54, 0, v54
	v_max_f32_e32 v57, 0, v57
	v_max_f32_e32 v56, 0, v56
	v_pk_mul_f32 v[52:53], v[52:53], v[52:53]
	v_pk_mul_f32 v[50:51], v[50:51], v[50:51]
	v_max_f32_e32 v59, 0, v59
	v_max_f32_e32 v58, 0, v58
	v_max_f32_e32 v61, 0, v61
	v_max_f32_e32 v60, 0, v60
	v_max_f32_e32 v63, 0, v63
	v_max_f32_e32 v62, 0, v62
	v_max_f32_e32 v65, 0, v65
	v_max_f32_e32 v64, 0, v64
	v_pk_mul_f32 v[56:57], v[56:57], v[56:57]
	v_pk_mul_f32 v[54:55], v[54:55], v[54:55]
	v_cvt_pk_bf16_f32 v50, v50, v51
	v_cvt_pk_bf16_f32 v51, v52, v53
	v_pk_mul_f32 v[60:61], v[60:61], v[60:61]
	v_cvt_pk_bf16_f32 v52, v54, v55
	v_cvt_pk_bf16_f32 v53, v56, v57
	v_pk_mul_f32 v[58:59], v[58:59], v[58:59]
	v_pk_mul_f32 v[64:65], v[64:65], v[64:65]
	v_pk_mul_f32 v[62:63], v[62:63], v[62:63]
	global_store_dwordx4 v[68:69], v[50:53], off nt
	s_nop 1
	v_cvt_pk_bf16_f32 v50, v58, v59
	v_cvt_pk_bf16_f32 v51, v60, v61
	v_cvt_pk_bf16_f32 v52, v62, v63
	v_cvt_pk_bf16_f32 v53, v64, v65
	global_store_dwordx4 v[70:71], v[50:53], off nt
	global_load_dword v50, v[100:101], off offset:704
	s_nop 0
	v_add_u32_e32 v51, 0x5800, v169
	v_and_b32_e32 v138, 0x7f80, v51
	v_lshl_add_u64 v[52:53], v[102:103], 0, v[138:139]
	v_lshl_add_u64 v[54:55], v[104:105], 0, v[138:139]
	v_lshl_add_u64 v[52:53], v[52:53], 0, v[90:91]
	v_lshl_add_u64 v[54:55], v[54:55], 0, v[90:91]
	s_waitcnt vmcnt(0)
	v_pk_mul_f32 v[2:3], v[2:3], v[50:51] op_sel_hi:[1,0]
	v_pk_mul_f32 v[4:5], v[4:5], v[50:51] op_sel_hi:[1,0]
	v_pk_mul_f32 v[6:7], v[6:7], v[50:51] op_sel_hi:[1,0]
	v_pk_mul_f32 v[8:9], v[8:9], v[50:51] op_sel_hi:[1,0]
	v_pk_mul_f32 v[30:31], v[30:31], v[50:51] op_sel_hi:[1,0]
	v_pk_fma_f32 v[4:5], v[4:5], v[40:41], v[24:25]
	v_pk_fma_f32 v[2:3], v[2:3], v[38:39], v[22:23]
	v_pk_mul_f32 v[32:33], v[32:33], v[50:51] op_sel_hi:[1,0]
	v_pk_mul_f32 v[14:15], v[14:15], v[50:51] op_sel_hi:[1,0]
	v_pk_mul_f32 v[16:17], v[16:17], v[50:51] op_sel_hi:[1,0]
	v_pk_fma_f32 v[8:9], v[8:9], v[36:37], v[28:29]
	v_pk_fma_f32 v[6:7], v[6:7], v[34:35], v[26:27]
	v_pk_fma_f32 v[18:19], v[30:31], v[42:43], v[18:19]
	v_max_f32_e32 v3, 0, v3
	v_max_f32_e32 v2, 0, v2
	v_max_f32_e32 v5, 0, v5
	v_max_f32_e32 v4, 0, v4
	v_pk_fma_f32 v[20:21], v[32:33], v[44:45], v[20:21]
	v_pk_fma_f32 v[12:13], v[16:17], v[48:49], v[12:13]
	v_pk_fma_f32 v[10:11], v[14:15], v[46:47], v[10:11]
	v_max_f32_e32 v7, 0, v7
	v_max_f32_e32 v6, 0, v6
	v_max_f32_e32 v9, 0, v9
	v_max_f32_e32 v8, 0, v8
	v_max_f32_e32 v15, 0, v19
	v_max_f32_e32 v14, 0, v18
	v_pk_mul_f32 v[18:19], v[4:5], v[4:5]
	v_pk_mul_f32 v[4:5], v[2:3], v[2:3]
	v_max_f32_e32 v17, 0, v21
	v_max_f32_e32 v16, 0, v20
	v_max_f32_e32 v11, 0, v11
	v_max_f32_e32 v10, 0, v10
	v_max_f32_e32 v13, 0, v13
	v_max_f32_e32 v12, 0, v12
	v_pk_mul_f32 v[8:9], v[8:9], v[8:9]
	v_pk_mul_f32 v[6:7], v[6:7], v[6:7]
	v_pk_mul_f32 v[16:17], v[16:17], v[16:17]
	v_cvt_pk_bf16_f32 v2, v6, v7
	v_cvt_pk_bf16_f32 v3, v8, v9
	v_cvt_pk_bf16_f32 v4, v4, v5
	v_cvt_pk_bf16_f32 v5, v18, v19
	v_pk_mul_f32 v[14:15], v[14:15], v[14:15]
	v_pk_mul_f32 v[12:13], v[12:13], v[12:13]
	v_pk_mul_f32 v[10:11], v[10:11], v[10:11]
	global_store_dwordx4 v[52:53], v[2:5], off nt
	s_nop 1
	v_cvt_pk_bf16_f32 v2, v14, v15
	v_cvt_pk_bf16_f32 v3, v16, v17
	v_cvt_pk_bf16_f32 v4, v10, v11
	v_cvt_pk_bf16_f32 v5, v12, v13
	global_store_dwordx4 v[54:55], v[2:5], off nt
	s_cbranch_vccnz .LBB0_3785
	s_andn2_b64 vcc, exec, s[10:11]
	s_cbranch_vccnz .LBB0_3784
	s_barrier
	s_branch .LBB0_3784

.LBB0_3879:
	ds_read_b128 v[130:133], v169
	ds_read_b128 v[134:137], v169 offset:1024
	ds_read_b128 v[138:141], v169 offset:2048
	ds_read_b128 v[142:145], v169 offset:3072
	ds_read_b128 v[162:165], v170
	ds_read_b128 v[172:175], v170 offset:1024
	ds_read_b128 v[176:179], v170 offset:2048
	ds_read_b128 v[180:183], v170 offset:3072
	s_add_i32 s59, s26, 2
	s_add_u32 s27, s24, 0x4000
	s_addc_u32 s28, s25, 0
	s_cmp_eq_u32 s48, s26
	s_cselect_b32 s29, s3, s28
	s_cselect_b32 s28, s2, s27
	s_cselect_b32 s60, s22, s57
	s_cselect_b32 s61, s23, s58
	s_add_u32 s26, s28, 0x8000
	s_addc_u32 s27, s29, 0
	v_lshl_add_u64 v[216:217], s[24:25], 0, v[154:155]
	s_add_i32 m0, s38, 0xc000
	ds_read_b128 v[184:187], v171
	ds_read_b128 v[188:191], v171 offset:1024
	ds_read_b128 v[192:195], v171 offset:2048
	ds_read_b128 v[196:199], v171 offset:3072
	ds_read_b128 v[200:203], v171 offset:4096
	ds_read_b128 v[204:207], v171 offset:5120
	ds_read_b128 v[208:211], v171 offset:6144
	ds_read_b128 v[212:215], v171 offset:7168
	global_load_lds_dwordx4 v[216:217], off nt
	v_lshl_add_u64 v[216:217], s[24:25], 0, v[156:157]
	s_add_i32 m0, s38, 0xe000
	s_nop 0
	global_load_lds_dwordx4 v[216:217], off nt
	s_waitcnt vmcnt(8)
	s_waitcnt lgkmcnt(0)
	s_setprio 1
	s_waitcnt lgkmcnt(0)
	v_mfma_f32_16x16x32_bf16 v[126:129], v[130:133], v[184:187], v[126:129]
	v_mfma_f32_16x16x32_bf16 v[122:125], v[138:141], v[184:187], v[122:125]
	s_barrier
	v_mfma_f32_16x16x32_bf16 v[110:113], v[130:133], v[192:195], v[110:113]
	v_mfma_f32_16x16x32_bf16 v[106:109], v[138:141], v[192:195], v[106:109]
	v_mfma_f32_16x16x32_bf16 v[94:97], v[130:133], v[200:203], v[94:97]
	v_mfma_f32_16x16x32_bf16 v[90:93], v[138:141], v[200:203], v[90:93]
	v_mfma_f32_16x16x32_bf16 v[78:81], v[130:133], v[208:211], v[78:81]
	v_mfma_f32_16x16x32_bf16 v[74:77], v[138:141], v[208:211], v[74:77]
	v_mfma_f32_16x16x32_bf16 v[126:129], v[134:137], v[188:191], v[126:129]
	v_mfma_f32_16x16x32_bf16 v[122:125], v[142:145], v[188:191], v[122:125]
	v_mfma_f32_16x16x32_bf16 v[110:113], v[134:137], v[196:199], v[110:113]
	v_mfma_f32_16x16x32_bf16 v[106:109], v[142:145], v[196:199], v[106:109]
	v_mfma_f32_16x16x32_bf16 v[94:97], v[134:137], v[204:207], v[94:97]
	v_mfma_f32_16x16x32_bf16 v[90:93], v[142:145], v[204:207], v[90:93]
	v_mfma_f32_16x16x32_bf16 v[78:81], v[134:137], v[212:215], v[78:81]
	v_mfma_f32_16x16x32_bf16 v[74:77], v[142:145], v[212:215], v[74:77]
	s_setprio 0
	s_setprio 1
	v_mfma_f32_16x16x32_bf16 v[118:121], v[162:165], v[184:187], v[118:121]
	v_mfma_f32_16x16x32_bf16 v[114:117], v[176:179], v[184:187], v[114:117]
	v_mfma_f32_16x16x32_bf16 v[102:105], v[162:165], v[192:195], v[102:105]
	v_mfma_f32_16x16x32_bf16 v[98:101], v[176:179], v[192:195], v[98:101]
	v_mfma_f32_16x16x32_bf16 v[86:89], v[162:165], v[200:203], v[86:89]
	v_mfma_f32_16x16x32_bf16 v[82:85], v[176:179], v[200:203], v[82:85]
	v_mfma_f32_16x16x32_bf16 v[70:73], v[162:165], v[208:211], v[70:73]
	v_mfma_f32_16x16x32_bf16 v[66:69], v[176:179], v[208:211], v[66:69]
	v_mfma_f32_16x16x32_bf16 v[118:121], v[172:175], v[188:191], v[118:121]
	v_mfma_f32_16x16x32_bf16 v[114:117], v[180:183], v[188:191], v[114:117]
	v_mfma_f32_16x16x32_bf16 v[102:105], v[172:175], v[196:199], v[102:105]
	v_mfma_f32_16x16x32_bf16 v[98:101], v[180:183], v[196:199], v[98:101]
	v_mfma_f32_16x16x32_bf16 v[86:89], v[172:175], v[204:207], v[86:89]
	v_mfma_f32_16x16x32_bf16 v[82:85], v[180:183], v[204:207], v[82:85]
	v_mfma_f32_16x16x32_bf16 v[70:73], v[172:175], v[212:215], v[70:73]
	v_mfma_f32_16x16x32_bf16 v[66:69], v[180:183], v[212:215], v[66:69]
	s_setprio 0
	s_barrier
	s_add_i32 s62, s50, s37
	v_lshl_add_u64 v[216:217], s[60:61], 0, v[148:149]
	s_mov_b32 m0, s62
	ds_read_b128 v[184:187], v171 offset:16384
	ds_read_b128 v[188:191], v171 offset:17408
	ds_read_b128 v[192:195], v171 offset:18432
	ds_read_b128 v[196:199], v171 offset:19456
	ds_read_b128 v[200:203], v171 offset:20480
	ds_read_b128 v[204:207], v171 offset:21504
	ds_read_b128 v[208:211], v171 offset:22528
	ds_read_b128 v[212:215], v171 offset:23552
	global_load_lds_dwordx4 v[216:217], off
	s_add_i32 m0, s62, 0x2000
	v_lshl_add_u64 v[218:219], s[60:61], 0, v[152:153]
	s_add_u32 s60, s60, s6
	s_addc_u32 s61, s61, s7
	s_add_i32 s62, s51, s37
	global_load_lds_dwordx4 v[218:219], off
	v_lshl_add_u64 v[220:221], s[60:61], 0, v[148:149]
	s_mov_b32 m0, s62
	v_lshl_add_u64 v[222:223], s[60:61], 0, v[152:153]
	global_load_lds_dwordx4 v[220:221], off
	s_add_i32 m0, s62, 0x2000
	v_lshl_add_u64 v[224:225], s[28:29], 0, v[146:147]
	global_load_lds_dwordx4 v[222:223], off
	s_mov_b32 m0, s38
	s_nop 0
	global_load_lds_dwordx4 v[224:225], off nt
	v_lshl_add_u64 v[224:225], s[28:29], 0, v[150:151]
	s_mov_b32 m0, s39
	s_nop 0
	global_load_lds_dwordx4 v[224:225], off nt
	s_waitcnt vmcnt(8)
	s_waitcnt lgkmcnt(0)
	s_setprio 1
	s_waitcnt lgkmcnt(0)
	v_mfma_f32_16x16x32_bf16 v[62:65], v[130:133], v[184:187], v[62:65]
	v_mfma_f32_16x16x32_bf16 v[58:61], v[138:141], v[184:187], v[58:61]
	s_barrier
	v_mfma_f32_16x16x32_bf16 v[46:49], v[130:133], v[192:195], v[46:49]
	v_mfma_f32_16x16x32_bf16 v[42:45], v[138:141], v[192:195], v[42:45]
	v_mfma_f32_16x16x32_bf16 v[30:33], v[130:133], v[200:203], v[30:33]
	v_mfma_f32_16x16x32_bf16 v[26:29], v[138:141], v[200:203], v[26:29]
	v_mfma_f32_16x16x32_bf16 v[14:17], v[130:133], v[208:211], v[14:17]
	v_mfma_f32_16x16x32_bf16 v[10:13], v[138:141], v[208:211], v[10:13]
	v_mfma_f32_16x16x32_bf16 v[62:65], v[134:137], v[188:191], v[62:65]
	v_mfma_f32_16x16x32_bf16 v[58:61], v[142:145], v[188:191], v[58:61]
	v_mfma_f32_16x16x32_bf16 v[46:49], v[134:137], v[196:199], v[46:49]
	v_mfma_f32_16x16x32_bf16 v[42:45], v[142:145], v[196:199], v[42:45]
	v_mfma_f32_16x16x32_bf16 v[30:33], v[134:137], v[204:207], v[30:33]
	v_mfma_f32_16x16x32_bf16 v[26:29], v[142:145], v[204:207], v[26:29]
	v_mfma_f32_16x16x32_bf16 v[14:17], v[134:137], v[212:215], v[14:17]
	v_mfma_f32_16x16x32_bf16 v[10:13], v[142:145], v[212:215], v[10:13]
	s_setprio 0
	s_setprio 1
	v_mfma_f32_16x16x32_bf16 v[54:57], v[162:165], v[184:187], v[54:57]
	v_mfma_f32_16x16x32_bf16 v[50:53], v[176:179], v[184:187], v[50:53]
	v_mfma_f32_16x16x32_bf16 v[38:41], v[162:165], v[192:195], v[38:41]
	v_mfma_f32_16x16x32_bf16 v[34:37], v[176:179], v[192:195], v[34:37]
	v_mfma_f32_16x16x32_bf16 v[22:25], v[162:165], v[200:203], v[22:25]
	v_mfma_f32_16x16x32_bf16 v[18:21], v[176:179], v[200:203], v[18:21]
	v_mfma_f32_16x16x32_bf16 v[6:9], v[162:165], v[208:211], v[6:9]
	v_mfma_f32_16x16x32_bf16 v[2:5], v[176:179], v[208:211], v[2:5]
	v_mfma_f32_16x16x32_bf16 v[54:57], v[172:175], v[188:191], v[54:57]
	v_mfma_f32_16x16x32_bf16 v[50:53], v[180:183], v[188:191], v[50:53]
	v_mfma_f32_16x16x32_bf16 v[38:41], v[172:175], v[196:199], v[38:41]
	v_mfma_f32_16x16x32_bf16 v[34:37], v[180:183], v[196:199], v[34:37]
	v_mfma_f32_16x16x32_bf16 v[22:25], v[172:175], v[204:207], v[22:25]
	v_mfma_f32_16x16x32_bf16 v[18:21], v[180:183], v[204:207], v[18:21]
	v_mfma_f32_16x16x32_bf16 v[6:9], v[172:175], v[212:215], v[6:9]
	v_mfma_f32_16x16x32_bf16 v[2:5], v[180:183], v[212:215], v[2:5]
	s_setprio 0
	s_barrier
	s_add_i32 s60, 0, 0x18000
	s_add_i32 s61, 0, 0x1c000
	v_add_u32_e32 v142, s60, v167
	v_add_u32_e32 v180, s61, v167
	ds_read_b128 v[130:133], v142
	ds_read_b128 v[134:137], v142 offset:1024
	ds_read_b128 v[138:141], v142 offset:2048
	ds_read_b128 v[142:145], v142 offset:3072
	ds_read_b128 v[162:165], v180
	ds_read_b128 v[172:175], v180 offset:1024
	ds_read_b128 v[176:179], v180 offset:2048
	ds_read_b128 v[180:183], v180 offset:3072
	s_add_u32 s28, s28, 0x4000
	s_addc_u32 s29, s29, 0
	s_mov_b32 m0, s40
	v_lshl_add_u64 v[224:225], s[28:29], 0, v[146:147]
	ds_read_b128 v[184:187], v171 offset:32768
	ds_read_b128 v[188:191], v171 offset:33792
	ds_read_b128 v[192:195], v171 offset:34816
	ds_read_b128 v[196:199], v171 offset:35840
	ds_read_b128 v[200:203], v171 offset:36864
	ds_read_b128 v[204:207], v171 offset:37888
	ds_read_b128 v[208:211], v171 offset:38912
	ds_read_b128 v[212:215], v171 offset:39936
	global_load_lds_dwordx4 v[224:225], off nt
	v_lshl_add_u64 v[224:225], s[28:29], 0, v[150:151]
	s_mov_b32 m0, s41
	s_nop 0
	global_load_lds_dwordx4 v[224:225], off nt
	s_waitcnt vmcnt(8)
	s_waitcnt lgkmcnt(0)
	s_setprio 1
	s_waitcnt lgkmcnt(0)
	v_mfma_f32_16x16x32_bf16 v[126:129], v[130:133], v[184:187], v[126:129]
	v_mfma_f32_16x16x32_bf16 v[122:125], v[138:141], v[184:187], v[122:125]
	s_barrier
	v_mfma_f32_16x16x32_bf16 v[110:113], v[130:133], v[192:195], v[110:113]
	v_mfma_f32_16x16x32_bf16 v[106:109], v[138:141], v[192:195], v[106:109]
	v_mfma_f32_16x16x32_bf16 v[94:97], v[130:133], v[200:203], v[94:97]
	v_mfma_f32_16x16x32_bf16 v[90:93], v[138:141], v[200:203], v[90:93]
	v_mfma_f32_16x16x32_bf16 v[78:81], v[130:133], v[208:211], v[78:81]
	v_mfma_f32_16x16x32_bf16 v[74:77], v[138:141], v[208:211], v[74:77]
	v_mfma_f32_16x16x32_bf16 v[126:129], v[134:137], v[188:191], v[126:129]
	v_mfma_f32_16x16x32_bf16 v[122:125], v[142:145], v[188:191], v[122:125]
	v_mfma_f32_16x16x32_bf16 v[110:113], v[134:137], v[196:199], v[110:113]
	v_mfma_f32_16x16x32_bf16 v[106:109], v[142:145], v[196:199], v[106:109]
	v_mfma_f32_16x16x32_bf16 v[94:97], v[134:137], v[204:207], v[94:97]
	v_mfma_f32_16x16x32_bf16 v[90:93], v[142:145], v[204:207], v[90:93]
	v_mfma_f32_16x16x32_bf16 v[78:81], v[134:137], v[212:215], v[78:81]
	v_mfma_f32_16x16x32_bf16 v[74:77], v[142:145], v[212:215], v[74:77]
	s_setprio 0
	s_setprio 1
	v_mfma_f32_16x16x32_bf16 v[118:121], v[162:165], v[184:187], v[118:121]
	v_mfma_f32_16x16x32_bf16 v[114:117], v[176:179], v[184:187], v[114:117]
	v_mfma_f32_16x16x32_bf16 v[102:105], v[162:165], v[192:195], v[102:105]
	v_mfma_f32_16x16x32_bf16 v[98:101], v[176:179], v[192:195], v[98:101]
	v_mfma_f32_16x16x32_bf16 v[86:89], v[162:165], v[200:203], v[86:89]
	v_mfma_f32_16x16x32_bf16 v[82:85], v[176:179], v[200:203], v[82:85]
	v_mfma_f32_16x16x32_bf16 v[70:73], v[162:165], v[208:211], v[70:73]
	v_mfma_f32_16x16x32_bf16 v[66:69], v[176:179], v[208:211], v[66:69]
	v_mfma_f32_16x16x32_bf16 v[118:121], v[172:175], v[188:191], v[118:121]
	v_mfma_f32_16x16x32_bf16 v[114:117], v[180:183], v[188:191], v[114:117]
	v_mfma_f32_16x16x32_bf16 v[102:105], v[172:175], v[196:199], v[102:105]
	v_mfma_f32_16x16x32_bf16 v[98:101], v[180:183], v[196:199], v[98:101]
	v_mfma_f32_16x16x32_bf16 v[86:89], v[172:175], v[204:207], v[86:89]
	v_mfma_f32_16x16x32_bf16 v[82:85], v[180:183], v[204:207], v[82:85]
	v_mfma_f32_16x16x32_bf16 v[70:73], v[172:175], v[212:215], v[70:73]
	v_mfma_f32_16x16x32_bf16 v[66:69], v[180:183], v[212:215], v[66:69]
	s_setprio 0
	s_barrier
	s_add_i32 s28, s60, s37
	v_lshl_add_u64 v[216:217], v[216:217], 0, s[14:15]
	s_mov_b32 m0, s28
	ds_read_b128 v[184:187], v171 offset:49152
	ds_read_b128 v[188:191], v171 offset:50176
	ds_read_b128 v[192:195], v171 offset:51200
	ds_read_b128 v[196:199], v171 offset:52224
	ds_read_b128 v[200:203], v171 offset:53248
	ds_read_b128 v[204:207], v171 offset:54272
	ds_read_b128 v[208:211], v171 offset:55296
	ds_read_b128 v[212:215], v171 offset:56320
	global_load_lds_dwordx4 v[216:217], off
	v_lshl_add_u64 v[216:217], v[218:219], 0, s[14:15]
	s_add_i32 m0, s28, 0x2000
	s_add_i32 s28, s61, s37
	global_load_lds_dwordx4 v[216:217], off
	v_lshl_add_u64 v[216:217], v[220:221], 0, s[14:15]
	s_mov_b32 m0, s28
	s_nop 0
	global_load_lds_dwordx4 v[216:217], off
	v_lshl_add_u64 v[216:217], v[222:223], 0, s[14:15]
	s_add_i32 m0, s28, 0x2000
	s_nop 0
	global_load_lds_dwordx4 v[216:217], off
	v_lshl_add_u64 v[216:217], s[26:27], 0, v[146:147]
	s_mov_b32 m0, s46
	s_nop 0
	global_load_lds_dwordx4 v[216:217], off nt
	v_lshl_add_u64 v[216:217], s[26:27], 0, v[150:151]
	s_mov_b32 m0, s47
	s_nop 0
	global_load_lds_dwordx4 v[216:217], off nt
	s_waitcnt vmcnt(8)
	s_waitcnt lgkmcnt(0)
	s_setprio 1
	s_waitcnt lgkmcnt(0)
	v_mfma_f32_16x16x32_bf16 v[62:65], v[130:133], v[184:187], v[62:65]
	v_mfma_f32_16x16x32_bf16 v[58:61], v[138:141], v[184:187], v[58:61]
	s_barrier
	v_mfma_f32_16x16x32_bf16 v[46:49], v[130:133], v[192:195], v[46:49]
	v_mfma_f32_16x16x32_bf16 v[42:45], v[138:141], v[192:195], v[42:45]
	v_mfma_f32_16x16x32_bf16 v[30:33], v[130:133], v[200:203], v[30:33]
	v_mfma_f32_16x16x32_bf16 v[26:29], v[138:141], v[200:203], v[26:29]
	v_mfma_f32_16x16x32_bf16 v[14:17], v[130:133], v[208:211], v[14:17]
	v_mfma_f32_16x16x32_bf16 v[10:13], v[138:141], v[208:211], v[10:13]
	v_mfma_f32_16x16x32_bf16 v[62:65], v[134:137], v[188:191], v[62:65]
	v_mfma_f32_16x16x32_bf16 v[58:61], v[142:145], v[188:191], v[58:61]
	v_mfma_f32_16x16x32_bf16 v[46:49], v[134:137], v[196:199], v[46:49]
	v_mfma_f32_16x16x32_bf16 v[42:45], v[142:145], v[196:199], v[42:45]
	v_mfma_f32_16x16x32_bf16 v[30:33], v[134:137], v[204:207], v[30:33]
	v_mfma_f32_16x16x32_bf16 v[26:29], v[142:145], v[204:207], v[26:29]
	v_mfma_f32_16x16x32_bf16 v[14:17], v[134:137], v[212:215], v[14:17]
	v_mfma_f32_16x16x32_bf16 v[10:13], v[142:145], v[212:215], v[10:13]
	s_setprio 0
	s_setprio 1
	v_mfma_f32_16x16x32_bf16 v[54:57], v[162:165], v[184:187], v[54:57]
	v_mfma_f32_16x16x32_bf16 v[50:53], v[176:179], v[184:187], v[50:53]
	v_mfma_f32_16x16x32_bf16 v[38:41], v[162:165], v[192:195], v[38:41]
	v_mfma_f32_16x16x32_bf16 v[34:37], v[176:179], v[192:195], v[34:37]
	v_mfma_f32_16x16x32_bf16 v[22:25], v[162:165], v[200:203], v[22:25]
	v_mfma_f32_16x16x32_bf16 v[18:21], v[176:179], v[200:203], v[18:21]
	v_mfma_f32_16x16x32_bf16 v[6:9], v[162:165], v[208:211], v[6:9]
	v_mfma_f32_16x16x32_bf16 v[2:5], v[176:179], v[208:211], v[2:5]
	v_mfma_f32_16x16x32_bf16 v[54:57], v[172:175], v[188:191], v[54:57]
	v_mfma_f32_16x16x32_bf16 v[50:53], v[180:183], v[188:191], v[50:53]
	v_mfma_f32_16x16x32_bf16 v[38:41], v[172:175], v[196:199], v[38:41]
	v_mfma_f32_16x16x32_bf16 v[34:37], v[180:183], v[196:199], v[34:37]
	v_mfma_f32_16x16x32_bf16 v[22:25], v[172:175], v[204:207], v[22:25]
	v_mfma_f32_16x16x32_bf16 v[18:21], v[180:183], v[204:207], v[18:21]
	v_mfma_f32_16x16x32_bf16 v[6:9], v[172:175], v[212:215], v[6:9]
	v_mfma_f32_16x16x32_bf16 v[2:5], v[180:183], v[212:215], v[2:5]
	s_setprio 0
	s_barrier
	s_add_u32 s57, s57, 0x100
	s_addc_u32 s58, s58, 0
	s_add_u32 s24, s24, 0x10000
	s_addc_u32 s25, s25, 0
	s_cmp_ge_i32 s59, s45
	s_mov_b32 s26, s59
	s_cbranch_scc0 .LBB0_3879
